# MLA prompt loop: softmax VALU of the PV phase spread evenly over the MFMA gaps (5 per gap, rowmax 4 per gap)
# speedup vs baseline: 1.0001x; 1.0001x over previous
.Lmy_A_entry:
	s_mov_b32 s30, 0x20000
	s_mov_b32 s31, 0
	s_mov_b32 s12, 0x1000
	s_mov_b32 s13, 0
	s_lshr_b32 s71, s24, 1
	s_lshr_b32 s79, s25, 2
	s_add_i32 s79, s79, -1
	s_barrier
	s_mov_b32 s0, 0x60000
	s_mov_b32 s1, 0
	v_lshl_add_u64 v[24:25], v[16:17], 0, s[0:1]
	s_add_u32 m0, s40, 0x9000
	s_mov_b32 s0, 0x3000
	global_load_lds_dwordx4 v[24:25], off
	v_lshl_add_u64 v[30:31], v[222:223], 0, s[0:1]
	s_add_u32 m0, s43, 0x9000
	s_nop 0
	global_load_lds_dwordx4 v[30:31], off
	s_mov_b32 s0, 0x80000
	s_mov_b32 s1, 0
	v_lshl_add_u64 v[24:25], v[16:17], 0, s[0:1]
	s_mov_b32 s0, 0x60000
	v_lshl_add_u64 v[28:29], v[224:225], 0, s[0:1]
	s_mov_b32 s0, 0x4000
	v_lshl_add_u64 v[30:31], v[222:223], 0, s[0:1]
	s_waitcnt lgkmcnt(0)
	v_mfma_f32_32x32x16_bf16 v[82:97], v[218:221], v[4:7], v[66:81]
	v_mfma_f32_32x32x16_bf16 v[98:113], v[214:217], v[4:7], v[66:81]
	v_mfma_f32_32x32x16_bf16 v[82:97], v[210:213], v[8:11], v[82:97]
	v_mfma_f32_32x32x16_bf16 v[98:113], v[206:209], v[8:11], v[98:113]
	v_mfma_f32_32x32x16_bf16 v[82:97], v[202:205], v[12:15], v[82:97]
	v_mfma_f32_32x32x16_bf16 v[98:113], v[198:201], v[12:15], v[98:113]
	v_mfma_f32_32x32x16_bf16 v[82:97], v[194:197], v[130:133], v[82:97]
	v_mfma_f32_32x32x16_bf16 v[98:113], v[190:193], v[130:133], v[98:113]
	v_mfma_f32_32x32x16_bf16 v[82:97], v[186:189], v[134:137], v[82:97]
	v_mfma_f32_32x32x16_bf16 v[98:113], v[182:185], v[134:137], v[98:113]
	v_mfma_f32_32x32x16_bf16 v[82:97], v[178:181], v[138:141], v[82:97]
	v_mfma_f32_32x32x16_bf16 v[98:113], v[174:177], v[138:141], v[98:113]
	v_add_u32_e32 v2, 0x3000, v238
	ds_read_b128 v[218:221], v2
	ds_read_b128 v[214:217], v2 offset:512
	ds_read_b128 v[210:213], v2 offset:2048
	ds_read_b128 v[206:209], v2 offset:2560
	ds_read_b128 v[202:205], v2 offset:4096
	ds_read_b128 v[198:201], v2 offset:4608
	ds_read_b128 v[194:197], v2 offset:6144
	ds_read_b128 v[190:193], v2 offset:6656
	ds_read_b128 v[186:189], v2 offset:8192
	ds_read_b128 v[182:185], v2 offset:8704
	ds_read_b128 v[178:181], v2 offset:10240
	ds_read_b128 v[174:177], v2 offset:10752
	s_nop 7
	v_max3_f32 v19, v82, v83, v84
	v_max3_f32 v26, v85, v86, v87
	v_max3_f32 v19, v19, v88, v89
	v_max3_f32 v26, v26, v90, v91
	v_max3_f32 v19, v19, v92, v93
	v_max3_f32 v26, v26, v94, v95
	v_max3_f32 v19, v19, v96, v97
	v_max3_f32 v26, v26, v98, v99
	v_max3_f32 v19, v19, v100, v101
	v_max3_f32 v26, v26, v102, v103
	v_max3_f32 v19, v19, v104, v105
	v_max3_f32 v26, v26, v106, v107
	v_max3_f32 v19, v19, v108, v109
	v_max3_f32 v26, v26, v110, v111
	v_max3_f32 v19, v19, v112, v113
	v_max_f32_e32 v19, v19, v26
	v_mov_b32_e32 v26, v19
	s_nop 1
	v_permlane32_swap_b32_e32 v19, v26
	v_max_f32_e32 v19, v19, v26
	v_max_f32_e32 v19, v19, v19
	v_mov_b32_e32 v239, v19
	v_xor_b32_e32 v66, 0x80000000, v19
	v_mov_b32_e32 v67, v66
	v_mov_b32_e32 v68, v66
	v_mov_b32_e32 v69, v66
	v_mov_b32_e32 v70, v66
	v_mov_b32_e32 v71, v66
	v_mov_b32_e32 v72, v66
	v_mov_b32_e32 v73, v66
	v_mov_b32_e32 v74, v66
	v_mov_b32_e32 v75, v66
	v_mov_b32_e32 v76, v66
	v_mov_b32_e32 v77, v66
	v_mov_b32_e32 v78, v66
	v_mov_b32_e32 v79, v66
	v_mov_b32_e32 v80, v66
	v_mov_b32_e32 v81, v66
	v_sub_f32_e32 v82, v82, v19
	v_sub_f32_e32 v83, v83, v19
	v_sub_f32_e32 v84, v84, v19
	v_sub_f32_e32 v85, v85, v19
	v_sub_f32_e32 v86, v86, v19
	v_sub_f32_e32 v87, v87, v19
	v_sub_f32_e32 v88, v88, v19
	v_sub_f32_e32 v89, v89, v19
	v_sub_f32_e32 v90, v90, v19
	v_sub_f32_e32 v91, v91, v19
	v_sub_f32_e32 v92, v92, v19
	v_sub_f32_e32 v93, v93, v19
	v_sub_f32_e32 v94, v94, v19
	v_sub_f32_e32 v95, v95, v19
	v_sub_f32_e32 v96, v96, v19
	v_sub_f32_e32 v97, v97, v19
	v_sub_f32_e32 v98, v98, v19
	v_sub_f32_e32 v99, v99, v19
	v_sub_f32_e32 v100, v100, v19
	v_sub_f32_e32 v101, v101, v19
	v_sub_f32_e32 v102, v102, v19
	v_sub_f32_e32 v103, v103, v19
	v_sub_f32_e32 v104, v104, v19
	v_sub_f32_e32 v105, v105, v19
	v_sub_f32_e32 v106, v106, v19
	v_sub_f32_e32 v107, v107, v19
	v_sub_f32_e32 v108, v108, v19
	v_sub_f32_e32 v109, v109, v19
	v_sub_f32_e32 v110, v110, v19
	v_sub_f32_e32 v111, v111, v19
	v_sub_f32_e32 v112, v112, v19
	v_sub_f32_e32 v113, v113, v19
	s_cmp_lt_i32 s79, 1
	s_cbranch_scc1 .Lmy_A_tail
	s_waitcnt lgkmcnt(0)
	v_mov_b32_e32 v2, v237
	v_mfma_f32_32x32x16_bf16 v[142:157], v[218:221], v[4:7], v[66:81]
	v_exp_f32_e32 v82, v82
	v_exp_f32_e32 v83, v83
	v_exp_f32_e32 v84, v84
	v_add_f32_e32 v27, v82, v83
	v_exp_f32_e32 v85, v85
	ds_read_b64_tr_b16 v[114:115], v2 offset:49152
	ds_read_b64_tr_b16 v[116:117], v2 offset:49664
	ds_read_b64_tr_b16 v[118:119], v2 offset:50176
	ds_read_b64_tr_b16 v[120:121], v2 offset:50688
	v_mfma_f32_32x32x16_bf16 v[158:173], v[214:217], v[4:7], v[66:81]
	v_exp_f32_e32 v86, v86
	v_add_f32_e32 v27, v27, v84
	v_exp_f32_e32 v87, v87
	v_add_f32_e32 v27, v27, v85
	v_exp_f32_e32 v88, v88
	ds_read_b64_tr_b16 v[122:123], v2 offset:51200
	ds_read_b64_tr_b16 v[124:125], v2 offset:51712
	ds_read_b64_tr_b16 v[126:127], v2 offset:52224
	ds_read_b64_tr_b16 v[128:129], v2 offset:52736
	v_mfma_f32_32x32x16_bf16 v[142:157], v[210:213], v[8:11], v[142:157]
	v_add_f32_e32 v27, v27, v86
	v_exp_f32_e32 v89, v89
	v_add_f32_e32 v27, v27, v87
	v_add_f32_e32 v27, v27, v88
	v_add_f32_e32 v27, v27, v89
	ds_read_b64_tr_b16 v[240:241], v2 offset:53248
	ds_read_b64_tr_b16 v[242:243], v2 offset:53760
	ds_read_b64_tr_b16 v[244:245], v2 offset:54272
	ds_read_b64_tr_b16 v[246:247], v2 offset:54784
	v_mfma_f32_32x32x16_bf16 v[158:173], v[206:209], v[8:11], v[158:173]
	v_cvt_pk_bf16_f32 v82, v82, v83
	v_cvt_pk_bf16_f32 v83, v84, v85
	v_cvt_pk_bf16_f32 v84, v86, v87
	v_cvt_pk_bf16_f32 v85, v88, v89
	ds_read_b64_tr_b16 v[248:249], v2 offset:55296
	ds_read_b64_tr_b16 v[250:251], v2 offset:55808
	ds_read_b64_tr_b16 v[20:21], v2 offset:56320
	ds_read_b64_tr_b16 v[22:23], v2 offset:56832
	v_mfma_f32_32x32x16_bf16 v[142:157], v[202:205], v[12:15], v[142:157]
	v_exp_f32_e32 v90, v90
	v_exp_f32_e32 v91, v91
	v_exp_f32_e32 v92, v92
	v_add_f32_e32 v27, v27, v90
	v_exp_f32_e32 v93, v93
	v_mfma_f32_32x32x16_bf16 v[158:173], v[198:201], v[12:15], v[158:173]
	v_add_f32_e32 v27, v27, v91
	v_exp_f32_e32 v94, v94
	v_add_f32_e32 v27, v27, v92
	v_exp_f32_e32 v95, v95
	v_add_f32_e32 v27, v27, v93
	s_waitcnt vmcnt(3)
	s_barrier
	v_mfma_f32_32x32x16_bf16 v[142:157], v[194:197], v[130:133], v[142:157]
	s_add_u32 m0, s57, 0x6000
	v_exp_f32_e32 v96, v96
	v_add_f32_e32 v27, v27, v94
	global_load_lds_dwordx4 v[28:29], off
	v_lshl_add_u64 v[28:29], v[28:29], 0, s[30:31]
	v_exp_f32_e32 v97, v97
	v_add_f32_e32 v27, v27, v95
	v_add_f32_e32 v27, v27, v96
	v_mfma_f32_32x32x16_bf16 v[158:173], v[190:193], v[130:133], v[158:173]
	s_add_u32 m0, s40, 0x0
	v_add_f32_e32 v27, v27, v97
	v_cvt_pk_bf16_f32 v90, v90, v91
	global_load_lds_dwordx4 v[24:25], off
	v_lshl_add_u64 v[24:25], v[24:25], 0, s[30:31]
	v_cvt_pk_bf16_f32 v91, v92, v93
	v_cvt_pk_bf16_f32 v92, v94, v95
	v_cvt_pk_bf16_f32 v93, v96, v97
	v_mfma_f32_32x32x16_bf16 v[142:157], v[186:189], v[134:137], v[142:157]
	s_add_u32 m0, s43, 0x0
	v_exp_f32_e32 v98, v98
	v_exp_f32_e32 v99, v99
	global_load_lds_dwordx4 v[30:31], off
	v_lshl_add_u64 v[30:31], v[30:31], 0, s[12:13]
	v_exp_f32_e32 v100, v100
	v_add_f32_e32 v27, v27, v98
	v_exp_f32_e32 v101, v101
	v_mfma_f32_32x32x16_bf16 v[158:173], v[182:185], v[134:137], v[158:173]
	s_add_u32 m0, s40, 0x3000
	v_add_f32_e32 v27, v27, v99
	v_exp_f32_e32 v102, v102
	global_load_lds_dwordx4 v[24:25], off
	v_lshl_add_u64 v[24:25], v[24:25], 0, s[30:31]
	v_add_f32_e32 v27, v27, v100
	v_exp_f32_e32 v103, v103
	v_add_f32_e32 v27, v27, v101
	v_mfma_f32_32x32x16_bf16 v[142:157], v[178:181], v[138:141], v[142:157]
	s_add_u32 m0, s43, 0x3000
	v_exp_f32_e32 v104, v104
	v_add_f32_e32 v27, v27, v102
	global_load_lds_dwordx4 v[30:31], off
	v_lshl_add_u64 v[30:31], v[30:31], 0, s[12:13]
	v_exp_f32_e32 v105, v105
	v_add_f32_e32 v27, v27, v103
	v_add_f32_e32 v27, v27, v104
	v_mfma_f32_32x32x16_bf16 v[158:173], v[174:177], v[138:141], v[158:173]
	v_add_f32_e32 v27, v27, v105
	v_cvt_pk_bf16_f32 v98, v98, v99
	v_cvt_pk_bf16_f32 v99, v100, v101
	v_cvt_pk_bf16_f32 v100, v102, v103
	v_cvt_pk_bf16_f32 v101, v104, v105
	s_waitcnt lgkmcnt(0)
	v_add_u32_e32 v2, 0x6000, v238
	v_mfma_f32_32x32x16_bf16 v[34:49], v[82:85], v[114:117], v[34:49]
	v_exp_f32_e32 v106, v106
	v_exp_f32_e32 v107, v107
	v_exp_f32_e32 v108, v108
	v_add_f32_e32 v27, v27, v106
	v_exp_f32_e32 v109, v109
	ds_read_b128 v[218:221], v2
	ds_read_b128 v[214:217], v2 offset:512
	ds_read_b128 v[210:213], v2 offset:2048
	v_mfma_f32_32x32x16_bf16 v[50:65], v[82:85], v[240:243], v[50:65]
	v_add_f32_e32 v27, v27, v107
	v_exp_f32_e32 v110, v110
	v_add_f32_e32 v27, v27, v108
	v_exp_f32_e32 v111, v111
	v_add_f32_e32 v27, v27, v109
	ds_read_b128 v[206:209], v2 offset:2560
	ds_read_b128 v[202:205], v2 offset:4096
	ds_read_b128 v[198:201], v2 offset:4608
	v_mfma_f32_32x32x16_bf16 v[34:49], v[90:93], v[118:121], v[34:49]
	v_exp_f32_e32 v112, v112
	v_add_f32_e32 v27, v27, v110
	v_exp_f32_e32 v113, v113
	v_add_f32_e32 v27, v27, v111
	v_add_f32_e32 v27, v27, v112
	ds_read_b128 v[194:197], v2 offset:6144
	ds_read_b128 v[190:193], v2 offset:6656
	ds_read_b128 v[186:189], v2 offset:8192
	v_mfma_f32_32x32x16_bf16 v[50:65], v[90:93], v[244:247], v[50:65]
	v_add_f32_e32 v27, v27, v113
	v_cvt_pk_bf16_f32 v106, v106, v107
	v_cvt_pk_bf16_f32 v107, v108, v109
	v_cvt_pk_bf16_f32 v108, v110, v111
	v_cvt_pk_bf16_f32 v109, v112, v113
	v_add_f32_e32 v236, v236, v27
	ds_read_b128 v[182:185], v2 offset:8704
	ds_read_b128 v[178:181], v2 offset:10240
	ds_read_b128 v[174:177], v2 offset:10752
	v_mfma_f32_32x32x16_bf16 v[34:49], v[98:101], v[122:125], v[34:49]
	v_max3_f32 v19, v142, v143, v144
	v_max3_f32 v26, v145, v146, v147
	v_max3_f32 v19, v19, v148, v149
	v_max3_f32 v26, v26, v150, v151
	v_mfma_f32_32x32x16_bf16 v[50:65], v[98:101], v[248:251], v[50:65]
	v_max3_f32 v19, v19, v152, v153
	v_max3_f32 v26, v26, v154, v155
	v_max3_f32 v19, v19, v156, v157
	v_max3_f32 v26, v26, v158, v159
	v_mfma_f32_32x32x16_bf16 v[34:49], v[106:109], v[126:129], v[34:49]
	v_max3_f32 v19, v19, v160, v161
	v_max3_f32 v26, v26, v162, v163
	v_max3_f32 v19, v19, v164, v165
	v_max3_f32 v26, v26, v166, v167
	v_mfma_f32_32x32x16_bf16 v[50:65], v[106:109], v[20:23], v[50:65]
	v_max3_f32 v19, v19, v168, v169
	v_max3_f32 v26, v26, v170, v171
	v_max3_f32 v19, v19, v172, v173
	v_max_f32_e32 v19, v19, v26
	v_cmp_lt_f32_e32 vcc, s41, v19
	s_cbranch_vccz .Lmy_nors_1
	s_nop 15
	s_nop 15
	v_mov_b32_e32 v26, v19
	s_nop 1
	v_permlane32_swap_b32_e32 v19, v26
	v_max_f32_e32 v19, v19, v26
	v_max_f32_e32 v19, v19, v19
	v_max_f32_e32 v90, 0, v19
	v_exp_f32_e64 v91, -v90
	v_add_f32_e32 v239, v239, v90
	v_xor_b32_e32 v66, 0x80000000, v239
	v_mov_b32_e32 v67, v66
	v_mov_b32_e32 v68, v66
	v_mov_b32_e32 v69, v66
	v_mov_b32_e32 v70, v66
	v_mov_b32_e32 v71, v66
	v_mov_b32_e32 v72, v66
	v_mov_b32_e32 v73, v66
	v_mov_b32_e32 v74, v66
	v_mov_b32_e32 v75, v66
	v_mov_b32_e32 v76, v66
	v_mov_b32_e32 v77, v66
	v_mov_b32_e32 v78, v66
	v_mov_b32_e32 v79, v66
	v_mov_b32_e32 v80, v66
	v_mov_b32_e32 v81, v66
	v_sub_f32_e32 v142, v142, v90
	v_sub_f32_e32 v143, v143, v90
	v_sub_f32_e32 v144, v144, v90
	v_sub_f32_e32 v145, v145, v90
	v_sub_f32_e32 v146, v146, v90
	v_sub_f32_e32 v147, v147, v90
	v_sub_f32_e32 v148, v148, v90
	v_sub_f32_e32 v149, v149, v90
	v_sub_f32_e32 v150, v150, v90
	v_sub_f32_e32 v151, v151, v90
	v_sub_f32_e32 v152, v152, v90
	v_sub_f32_e32 v153, v153, v90
	v_sub_f32_e32 v154, v154, v90
	v_sub_f32_e32 v155, v155, v90
	v_sub_f32_e32 v156, v156, v90
	v_sub_f32_e32 v157, v157, v90
	v_sub_f32_e32 v158, v158, v90
	v_sub_f32_e32 v159, v159, v90
	v_sub_f32_e32 v160, v160, v90
	v_sub_f32_e32 v161, v161, v90
	v_sub_f32_e32 v162, v162, v90
	v_sub_f32_e32 v163, v163, v90
	v_sub_f32_e32 v164, v164, v90
	v_sub_f32_e32 v165, v165, v90
	v_sub_f32_e32 v166, v166, v90
	v_sub_f32_e32 v167, v167, v90
	v_sub_f32_e32 v168, v168, v90
	v_sub_f32_e32 v169, v169, v90
	v_sub_f32_e32 v170, v170, v90
	v_sub_f32_e32 v171, v171, v90
	v_sub_f32_e32 v172, v172, v90
	v_sub_f32_e32 v173, v173, v90
	v_mul_f32_e32 v236, v236, v91
	s_mov_b64 s[96:97], exec
	s_and_b64 exec, exec, s[8:9]
	ds_write_b32 v235, v91
	s_mov_b64 exec, s[96:97]
	v_lshl_add_u32 v2, v228, 4, s47
	ds_read_b128 v[94:97], v2 offset:0
	s_waitcnt lgkmcnt(0)
	v_mul_f32_e32 v34, v34, v94
	v_mul_f32_e32 v50, v50, v94
	v_mul_f32_e32 v35, v35, v95
	v_mul_f32_e32 v51, v51, v95
	v_mul_f32_e32 v36, v36, v96
	v_mul_f32_e32 v52, v52, v96
	v_mul_f32_e32 v37, v37, v97
	v_mul_f32_e32 v53, v53, v97
	ds_read_b128 v[94:97], v2 offset:32
	s_waitcnt lgkmcnt(0)
	v_mul_f32_e32 v38, v38, v94
	v_mul_f32_e32 v54, v54, v94
	v_mul_f32_e32 v39, v39, v95
	v_mul_f32_e32 v55, v55, v95
	v_mul_f32_e32 v40, v40, v96
	v_mul_f32_e32 v56, v56, v96
	v_mul_f32_e32 v41, v41, v97
	v_mul_f32_e32 v57, v57, v97
	ds_read_b128 v[94:97], v2 offset:64
	s_waitcnt lgkmcnt(0)
	v_mul_f32_e32 v42, v42, v94
	v_mul_f32_e32 v58, v58, v94
	v_mul_f32_e32 v43, v43, v95
	v_mul_f32_e32 v59, v59, v95
	v_mul_f32_e32 v44, v44, v96
	v_mul_f32_e32 v60, v60, v96
	v_mul_f32_e32 v45, v45, v97
	v_mul_f32_e32 v61, v61, v97
	ds_read_b128 v[94:97], v2 offset:96
	s_waitcnt lgkmcnt(0)
	v_mul_f32_e32 v46, v46, v94
	v_mul_f32_e32 v62, v62, v94
	v_mul_f32_e32 v47, v47, v95
	v_mul_f32_e32 v63, v63, v95
	v_mul_f32_e32 v48, v48, v96
	v_mul_f32_e32 v64, v64, v96
	v_mul_f32_e32 v49, v49, v97
	v_mul_f32_e32 v65, v65, v97
.Lmy_nors_1:
	s_waitcnt lgkmcnt(0)
	v_add_u32_e32 v2, 0x2000, v237
	v_mfma_f32_32x32x16_bf16 v[82:97], v[218:221], v[4:7], v[66:81]
	v_exp_f32_e32 v142, v142
	v_exp_f32_e32 v143, v143
	v_exp_f32_e32 v144, v144
	v_add_f32_e32 v27, v142, v143
	v_exp_f32_e32 v145, v145
	ds_read_b64_tr_b16 v[114:115], v2 offset:49152
	ds_read_b64_tr_b16 v[116:117], v2 offset:49664
	ds_read_b64_tr_b16 v[118:119], v2 offset:50176
	ds_read_b64_tr_b16 v[120:121], v2 offset:50688
	v_mfma_f32_32x32x16_bf16 v[98:113], v[214:217], v[4:7], v[66:81]
	v_exp_f32_e32 v146, v146
	v_add_f32_e32 v27, v27, v144
	v_exp_f32_e32 v147, v147
	v_add_f32_e32 v27, v27, v145
	v_exp_f32_e32 v148, v148
	ds_read_b64_tr_b16 v[122:123], v2 offset:51200
	ds_read_b64_tr_b16 v[124:125], v2 offset:51712
	ds_read_b64_tr_b16 v[126:127], v2 offset:52224
	ds_read_b64_tr_b16 v[128:129], v2 offset:52736
	v_mfma_f32_32x32x16_bf16 v[82:97], v[210:213], v[8:11], v[82:97]
	v_add_f32_e32 v27, v27, v146
	v_exp_f32_e32 v149, v149
	v_add_f32_e32 v27, v27, v147
	v_add_f32_e32 v27, v27, v148
	v_add_f32_e32 v27, v27, v149
	ds_read_b64_tr_b16 v[240:241], v2 offset:53248
	ds_read_b64_tr_b16 v[242:243], v2 offset:53760
	ds_read_b64_tr_b16 v[244:245], v2 offset:54272
	ds_read_b64_tr_b16 v[246:247], v2 offset:54784
	v_mfma_f32_32x32x16_bf16 v[98:113], v[206:209], v[8:11], v[98:113]
	v_cvt_pk_bf16_f32 v142, v142, v143
	v_cvt_pk_bf16_f32 v143, v144, v145
	v_cvt_pk_bf16_f32 v144, v146, v147
	v_cvt_pk_bf16_f32 v145, v148, v149
	ds_read_b64_tr_b16 v[248:249], v2 offset:55296
	ds_read_b64_tr_b16 v[250:251], v2 offset:55808
	ds_read_b64_tr_b16 v[20:21], v2 offset:56320
	ds_read_b64_tr_b16 v[22:23], v2 offset:56832
	v_mfma_f32_32x32x16_bf16 v[82:97], v[202:205], v[12:15], v[82:97]
	v_exp_f32_e32 v150, v150
	v_exp_f32_e32 v151, v151
	v_exp_f32_e32 v152, v152
	v_add_f32_e32 v27, v27, v150
	v_exp_f32_e32 v153, v153
	v_mfma_f32_32x32x16_bf16 v[98:113], v[198:201], v[12:15], v[98:113]
	v_add_f32_e32 v27, v27, v151
	v_exp_f32_e32 v154, v154
	v_add_f32_e32 v27, v27, v152
	v_exp_f32_e32 v155, v155
	v_add_f32_e32 v27, v27, v153
	s_waitcnt vmcnt(5)
	s_barrier
	v_mfma_f32_32x32x16_bf16 v[82:97], v[194:197], v[130:133], v[82:97]
	s_add_u32 m0, s57, 0x0
	v_exp_f32_e32 v156, v156
	v_add_f32_e32 v27, v27, v154
	global_load_lds_dwordx4 v[28:29], off
	v_lshl_add_u64 v[28:29], v[28:29], 0, s[30:31]
	v_exp_f32_e32 v157, v157
	v_add_f32_e32 v27, v27, v155
	v_add_f32_e32 v27, v27, v156
	v_mfma_f32_32x32x16_bf16 v[98:113], v[190:193], v[130:133], v[98:113]
	s_add_u32 m0, s40, 0x6000
	v_add_f32_e32 v27, v27, v157
	v_cvt_pk_bf16_f32 v150, v150, v151
	global_load_lds_dwordx4 v[24:25], off
	v_lshl_add_u64 v[24:25], v[24:25], 0, s[30:31]
	v_cvt_pk_bf16_f32 v151, v152, v153
	v_cvt_pk_bf16_f32 v152, v154, v155
	v_cvt_pk_bf16_f32 v153, v156, v157
	v_mfma_f32_32x32x16_bf16 v[82:97], v[186:189], v[134:137], v[82:97]
	s_add_u32 m0, s43, 0x6000
	v_exp_f32_e32 v158, v158
	v_exp_f32_e32 v159, v159
	global_load_lds_dwordx4 v[30:31], off
	v_lshl_add_u64 v[30:31], v[30:31], 0, s[12:13]
	v_exp_f32_e32 v160, v160
	v_add_f32_e32 v27, v27, v158
	v_exp_f32_e32 v161, v161
	v_mfma_f32_32x32x16_bf16 v[98:113], v[182:185], v[134:137], v[98:113]
	v_add_f32_e32 v27, v27, v159
	v_exp_f32_e32 v162, v162
	v_add_f32_e32 v27, v27, v160
	v_exp_f32_e32 v163, v163
	v_add_f32_e32 v27, v27, v161
	v_mfma_f32_32x32x16_bf16 v[82:97], v[178:181], v[138:141], v[82:97]
	v_exp_f32_e32 v164, v164
	v_add_f32_e32 v27, v27, v162
	v_exp_f32_e32 v165, v165
	v_add_f32_e32 v27, v27, v163
	v_add_f32_e32 v27, v27, v164
	v_mfma_f32_32x32x16_bf16 v[98:113], v[174:177], v[138:141], v[98:113]
	v_add_f32_e32 v27, v27, v165
	v_cvt_pk_bf16_f32 v158, v158, v159
	v_cvt_pk_bf16_f32 v159, v160, v161
	v_cvt_pk_bf16_f32 v160, v162, v163
	v_cvt_pk_bf16_f32 v161, v164, v165
	s_waitcnt lgkmcnt(0)
	v_add_u32_e32 v2, 0x9000, v238
	v_mfma_f32_32x32x16_bf16 v[34:49], v[142:145], v[114:117], v[34:49]
	v_exp_f32_e32 v166, v166
	v_exp_f32_e32 v167, v167
	v_exp_f32_e32 v168, v168
	v_add_f32_e32 v27, v27, v166
	v_exp_f32_e32 v169, v169
	ds_read_b128 v[218:221], v2
	ds_read_b128 v[214:217], v2 offset:512
	ds_read_b128 v[210:213], v2 offset:2048
	v_mfma_f32_32x32x16_bf16 v[50:65], v[142:145], v[240:243], v[50:65]
	v_add_f32_e32 v27, v27, v167
	v_exp_f32_e32 v170, v170
	v_add_f32_e32 v27, v27, v168
	v_exp_f32_e32 v171, v171
	v_add_f32_e32 v27, v27, v169
	ds_read_b128 v[206:209], v2 offset:2560
	ds_read_b128 v[202:205], v2 offset:4096
	ds_read_b128 v[198:201], v2 offset:4608
	v_mfma_f32_32x32x16_bf16 v[34:49], v[150:153], v[118:121], v[34:49]
	v_exp_f32_e32 v172, v172
	v_add_f32_e32 v27, v27, v170
	v_exp_f32_e32 v173, v173
	v_add_f32_e32 v27, v27, v171
	v_add_f32_e32 v27, v27, v172
	ds_read_b128 v[194:197], v2 offset:6144
	ds_read_b128 v[190:193], v2 offset:6656
	ds_read_b128 v[186:189], v2 offset:8192
	v_mfma_f32_32x32x16_bf16 v[50:65], v[150:153], v[244:247], v[50:65]
	v_add_f32_e32 v27, v27, v173
	v_cvt_pk_bf16_f32 v166, v166, v167
	v_cvt_pk_bf16_f32 v167, v168, v169
	v_cvt_pk_bf16_f32 v168, v170, v171
	v_cvt_pk_bf16_f32 v169, v172, v173
	v_add_f32_e32 v236, v236, v27
	ds_read_b128 v[182:185], v2 offset:8704
	ds_read_b128 v[178:181], v2 offset:10240
	ds_read_b128 v[174:177], v2 offset:10752
	v_mfma_f32_32x32x16_bf16 v[34:49], v[158:161], v[122:125], v[34:49]
	v_max3_f32 v19, v82, v83, v84
	v_max3_f32 v26, v85, v86, v87
	v_max3_f32 v19, v19, v88, v89
	v_max3_f32 v26, v26, v90, v91
	v_mfma_f32_32x32x16_bf16 v[50:65], v[158:161], v[248:251], v[50:65]
	v_max3_f32 v19, v19, v92, v93
	v_max3_f32 v26, v26, v94, v95
	v_max3_f32 v19, v19, v96, v97
	v_max3_f32 v26, v26, v98, v99
	v_mfma_f32_32x32x16_bf16 v[34:49], v[166:169], v[126:129], v[34:49]
	v_max3_f32 v19, v19, v100, v101
	v_max3_f32 v26, v26, v102, v103
	v_max3_f32 v19, v19, v104, v105
	v_max3_f32 v26, v26, v106, v107
	v_mfma_f32_32x32x16_bf16 v[50:65], v[166:169], v[20:23], v[50:65]
	v_max3_f32 v19, v19, v108, v109
	v_max3_f32 v26, v26, v110, v111
	v_max3_f32 v19, v19, v112, v113
	v_max_f32_e32 v19, v19, v26
	v_cmp_lt_f32_e32 vcc, s41, v19
	s_cbranch_vccz .Lmy_nors_2
	s_nop 15
	s_nop 15
	v_mov_b32_e32 v26, v19
	s_nop 1
	v_permlane32_swap_b32_e32 v19, v26
	v_max_f32_e32 v19, v19, v26
	v_max_f32_e32 v19, v19, v19
	v_max_f32_e32 v150, 0, v19
	v_exp_f32_e64 v151, -v150
	v_add_f32_e32 v239, v239, v150
	v_xor_b32_e32 v66, 0x80000000, v239
	v_mov_b32_e32 v67, v66
	v_mov_b32_e32 v68, v66
	v_mov_b32_e32 v69, v66
	v_mov_b32_e32 v70, v66
	v_mov_b32_e32 v71, v66
	v_mov_b32_e32 v72, v66
	v_mov_b32_e32 v73, v66
	v_mov_b32_e32 v74, v66
	v_mov_b32_e32 v75, v66
	v_mov_b32_e32 v76, v66
	v_mov_b32_e32 v77, v66
	v_mov_b32_e32 v78, v66
	v_mov_b32_e32 v79, v66
	v_mov_b32_e32 v80, v66
	v_mov_b32_e32 v81, v66
	v_sub_f32_e32 v82, v82, v150
	v_sub_f32_e32 v83, v83, v150
	v_sub_f32_e32 v84, v84, v150
	v_sub_f32_e32 v85, v85, v150
	v_sub_f32_e32 v86, v86, v150
	v_sub_f32_e32 v87, v87, v150
	v_sub_f32_e32 v88, v88, v150
	v_sub_f32_e32 v89, v89, v150
	v_sub_f32_e32 v90, v90, v150
	v_sub_f32_e32 v91, v91, v150
	v_sub_f32_e32 v92, v92, v150
	v_sub_f32_e32 v93, v93, v150
	v_sub_f32_e32 v94, v94, v150
	v_sub_f32_e32 v95, v95, v150
	v_sub_f32_e32 v96, v96, v150
	v_sub_f32_e32 v97, v97, v150
	v_sub_f32_e32 v98, v98, v150
	v_sub_f32_e32 v99, v99, v150
	v_sub_f32_e32 v100, v100, v150
	v_sub_f32_e32 v101, v101, v150
	v_sub_f32_e32 v102, v102, v150
	v_sub_f32_e32 v103, v103, v150
	v_sub_f32_e32 v104, v104, v150
	v_sub_f32_e32 v105, v105, v150
	v_sub_f32_e32 v106, v106, v150
	v_sub_f32_e32 v107, v107, v150
	v_sub_f32_e32 v108, v108, v150
	v_sub_f32_e32 v109, v109, v150
	v_sub_f32_e32 v110, v110, v150
	v_sub_f32_e32 v111, v111, v150
	v_sub_f32_e32 v112, v112, v150
	v_sub_f32_e32 v113, v113, v150
	v_mul_f32_e32 v236, v236, v151
	s_mov_b64 s[96:97], exec
	s_and_b64 exec, exec, s[8:9]
	ds_write_b32 v235, v151
	s_mov_b64 exec, s[96:97]
	v_lshl_add_u32 v2, v228, 4, s47
	ds_read_b128 v[154:157], v2 offset:0
	s_waitcnt lgkmcnt(0)
	v_mul_f32_e32 v34, v34, v154
	v_mul_f32_e32 v50, v50, v154
	v_mul_f32_e32 v35, v35, v155
	v_mul_f32_e32 v51, v51, v155
	v_mul_f32_e32 v36, v36, v156
	v_mul_f32_e32 v52, v52, v156
	v_mul_f32_e32 v37, v37, v157
	v_mul_f32_e32 v53, v53, v157
	ds_read_b128 v[154:157], v2 offset:32
	s_waitcnt lgkmcnt(0)
	v_mul_f32_e32 v38, v38, v154
	v_mul_f32_e32 v54, v54, v154
	v_mul_f32_e32 v39, v39, v155
	v_mul_f32_e32 v55, v55, v155
	v_mul_f32_e32 v40, v40, v156
	v_mul_f32_e32 v56, v56, v156
	v_mul_f32_e32 v41, v41, v157
	v_mul_f32_e32 v57, v57, v157
	ds_read_b128 v[154:157], v2 offset:64
	s_waitcnt lgkmcnt(0)
	v_mul_f32_e32 v42, v42, v154
	v_mul_f32_e32 v58, v58, v154
	v_mul_f32_e32 v43, v43, v155
	v_mul_f32_e32 v59, v59, v155
	v_mul_f32_e32 v44, v44, v156
	v_mul_f32_e32 v60, v60, v156
	v_mul_f32_e32 v45, v45, v157
	v_mul_f32_e32 v61, v61, v157
	ds_read_b128 v[154:157], v2 offset:96
	s_waitcnt lgkmcnt(0)
	v_mul_f32_e32 v46, v46, v154
	v_mul_f32_e32 v62, v62, v154
	v_mul_f32_e32 v47, v47, v155
	v_mul_f32_e32 v63, v63, v155
	v_mul_f32_e32 v48, v48, v156
	v_mul_f32_e32 v64, v64, v156
	v_mul_f32_e32 v49, v49, v157
	v_mul_f32_e32 v65, v65, v157
.Lmy_nors_2:
	s_waitcnt lgkmcnt(0)
	v_add_u32_e32 v2, 0x4000, v237
	v_mfma_f32_32x32x16_bf16 v[142:157], v[218:221], v[4:7], v[66:81]
	v_exp_f32_e32 v82, v82
	v_exp_f32_e32 v83, v83
	v_exp_f32_e32 v84, v84
	v_add_f32_e32 v27, v82, v83
	v_exp_f32_e32 v85, v85
	ds_read_b64_tr_b16 v[114:115], v2 offset:49152
	ds_read_b64_tr_b16 v[116:117], v2 offset:49664
	ds_read_b64_tr_b16 v[118:119], v2 offset:50176
	ds_read_b64_tr_b16 v[120:121], v2 offset:50688
	v_mfma_f32_32x32x16_bf16 v[158:173], v[214:217], v[4:7], v[66:81]
	v_exp_f32_e32 v86, v86
	v_add_f32_e32 v27, v27, v84
	v_exp_f32_e32 v87, v87
	v_add_f32_e32 v27, v27, v85
	v_exp_f32_e32 v88, v88
	ds_read_b64_tr_b16 v[122:123], v2 offset:51200
	ds_read_b64_tr_b16 v[124:125], v2 offset:51712
	ds_read_b64_tr_b16 v[126:127], v2 offset:52224
	ds_read_b64_tr_b16 v[128:129], v2 offset:52736
	v_mfma_f32_32x32x16_bf16 v[142:157], v[210:213], v[8:11], v[142:157]
	v_add_f32_e32 v27, v27, v86
	v_exp_f32_e32 v89, v89
	v_add_f32_e32 v27, v27, v87
	v_add_f32_e32 v27, v27, v88
	v_add_f32_e32 v27, v27, v89
	ds_read_b64_tr_b16 v[240:241], v2 offset:53248
	ds_read_b64_tr_b16 v[242:243], v2 offset:53760
	ds_read_b64_tr_b16 v[244:245], v2 offset:54272
	ds_read_b64_tr_b16 v[246:247], v2 offset:54784
	v_mfma_f32_32x32x16_bf16 v[158:173], v[206:209], v[8:11], v[158:173]
	v_cvt_pk_bf16_f32 v82, v82, v83
	v_cvt_pk_bf16_f32 v83, v84, v85
	v_cvt_pk_bf16_f32 v84, v86, v87
	v_cvt_pk_bf16_f32 v85, v88, v89
	ds_read_b64_tr_b16 v[248:249], v2 offset:55296
	ds_read_b64_tr_b16 v[250:251], v2 offset:55808
	ds_read_b64_tr_b16 v[20:21], v2 offset:56320
	ds_read_b64_tr_b16 v[22:23], v2 offset:56832
	v_mfma_f32_32x32x16_bf16 v[142:157], v[202:205], v[12:15], v[142:157]
	v_exp_f32_e32 v90, v90
	v_exp_f32_e32 v91, v91
	v_exp_f32_e32 v92, v92
	v_add_f32_e32 v27, v27, v90
	v_exp_f32_e32 v93, v93
	v_mfma_f32_32x32x16_bf16 v[158:173], v[198:201], v[12:15], v[158:173]
	v_add_f32_e32 v27, v27, v91
	v_exp_f32_e32 v94, v94
	v_add_f32_e32 v27, v27, v92
	v_exp_f32_e32 v95, v95
	v_add_f32_e32 v27, v27, v93
	s_waitcnt vmcnt(5)
	s_barrier
	v_mfma_f32_32x32x16_bf16 v[142:157], v[194:197], v[130:133], v[142:157]
	s_add_u32 m0, s57, 0x2000
	v_exp_f32_e32 v96, v96
	v_add_f32_e32 v27, v27, v94
	global_load_lds_dwordx4 v[28:29], off
	v_lshl_add_u64 v[28:29], v[28:29], 0, s[30:31]
	v_exp_f32_e32 v97, v97
	v_add_f32_e32 v27, v27, v95
	v_add_f32_e32 v27, v27, v96
	v_mfma_f32_32x32x16_bf16 v[158:173], v[190:193], v[130:133], v[158:173]
	s_add_u32 m0, s40, 0x9000
	v_add_f32_e32 v27, v27, v97
	v_cvt_pk_bf16_f32 v90, v90, v91
	global_load_lds_dwordx4 v[24:25], off
	v_lshl_add_u64 v[24:25], v[24:25], 0, s[30:31]
	v_cvt_pk_bf16_f32 v91, v92, v93
	v_cvt_pk_bf16_f32 v92, v94, v95
	v_cvt_pk_bf16_f32 v93, v96, v97
	v_mfma_f32_32x32x16_bf16 v[142:157], v[186:189], v[134:137], v[142:157]
	s_add_u32 m0, s43, 0x9000
	v_exp_f32_e32 v98, v98
	v_exp_f32_e32 v99, v99
	global_load_lds_dwordx4 v[30:31], off
	v_lshl_add_u64 v[30:31], v[30:31], 0, s[12:13]
	v_exp_f32_e32 v100, v100
	v_add_f32_e32 v27, v27, v98
	v_exp_f32_e32 v101, v101
	v_mfma_f32_32x32x16_bf16 v[158:173], v[182:185], v[134:137], v[158:173]
	v_add_f32_e32 v27, v27, v99
	v_exp_f32_e32 v102, v102
	v_add_f32_e32 v27, v27, v100
	v_exp_f32_e32 v103, v103
	v_add_f32_e32 v27, v27, v101
	v_mfma_f32_32x32x16_bf16 v[142:157], v[178:181], v[138:141], v[142:157]
	v_exp_f32_e32 v104, v104
	v_add_f32_e32 v27, v27, v102
	v_exp_f32_e32 v105, v105
	v_add_f32_e32 v27, v27, v103
	v_add_f32_e32 v27, v27, v104
	v_mfma_f32_32x32x16_bf16 v[158:173], v[174:177], v[138:141], v[158:173]
	v_add_f32_e32 v27, v27, v105
	v_cvt_pk_bf16_f32 v98, v98, v99
	v_cvt_pk_bf16_f32 v99, v100, v101
	v_cvt_pk_bf16_f32 v100, v102, v103
	v_cvt_pk_bf16_f32 v101, v104, v105
	s_waitcnt lgkmcnt(0)
	v_mov_b32_e32 v2, v238
	v_mfma_f32_32x32x16_bf16 v[34:49], v[82:85], v[114:117], v[34:49]
	v_exp_f32_e32 v106, v106
	v_exp_f32_e32 v107, v107
	v_exp_f32_e32 v108, v108
	v_add_f32_e32 v27, v27, v106
	v_exp_f32_e32 v109, v109
	ds_read_b128 v[218:221], v2
	ds_read_b128 v[214:217], v2 offset:512
	ds_read_b128 v[210:213], v2 offset:2048
	v_mfma_f32_32x32x16_bf16 v[50:65], v[82:85], v[240:243], v[50:65]
	v_add_f32_e32 v27, v27, v107
	v_exp_f32_e32 v110, v110
	v_add_f32_e32 v27, v27, v108
	v_exp_f32_e32 v111, v111
	v_add_f32_e32 v27, v27, v109
	ds_read_b128 v[206:209], v2 offset:2560
	ds_read_b128 v[202:205], v2 offset:4096
	ds_read_b128 v[198:201], v2 offset:4608
	v_mfma_f32_32x32x16_bf16 v[34:49], v[90:93], v[118:121], v[34:49]
	v_exp_f32_e32 v112, v112
	v_add_f32_e32 v27, v27, v110
	v_exp_f32_e32 v113, v113
	v_add_f32_e32 v27, v27, v111
	v_add_f32_e32 v27, v27, v112
	ds_read_b128 v[194:197], v2 offset:6144
	ds_read_b128 v[190:193], v2 offset:6656
	ds_read_b128 v[186:189], v2 offset:8192
	v_mfma_f32_32x32x16_bf16 v[50:65], v[90:93], v[244:247], v[50:65]
	v_add_f32_e32 v27, v27, v113
	v_cvt_pk_bf16_f32 v106, v106, v107
	v_cvt_pk_bf16_f32 v107, v108, v109
	v_cvt_pk_bf16_f32 v108, v110, v111
	v_cvt_pk_bf16_f32 v109, v112, v113
	v_add_f32_e32 v236, v236, v27
	ds_read_b128 v[182:185], v2 offset:8704
	ds_read_b128 v[178:181], v2 offset:10240
	ds_read_b128 v[174:177], v2 offset:10752
	v_mfma_f32_32x32x16_bf16 v[34:49], v[98:101], v[122:125], v[34:49]
	v_max3_f32 v19, v142, v143, v144
	v_max3_f32 v26, v145, v146, v147
	v_max3_f32 v19, v19, v148, v149
	v_max3_f32 v26, v26, v150, v151
	v_mfma_f32_32x32x16_bf16 v[50:65], v[98:101], v[248:251], v[50:65]
	v_max3_f32 v19, v19, v152, v153
	v_max3_f32 v26, v26, v154, v155
	v_max3_f32 v19, v19, v156, v157
	v_max3_f32 v26, v26, v158, v159
	v_mfma_f32_32x32x16_bf16 v[34:49], v[106:109], v[126:129], v[34:49]
	v_max3_f32 v19, v19, v160, v161
	v_max3_f32 v26, v26, v162, v163
	v_max3_f32 v19, v19, v164, v165
	v_max3_f32 v26, v26, v166, v167
	v_mfma_f32_32x32x16_bf16 v[50:65], v[106:109], v[20:23], v[50:65]
	v_max3_f32 v19, v19, v168, v169
	v_max3_f32 v26, v26, v170, v171
	v_max3_f32 v19, v19, v172, v173
	v_max_f32_e32 v19, v19, v26
	v_cmp_lt_f32_e32 vcc, s41, v19
	s_cbranch_vccz .Lmy_nors_3
	s_nop 15
	s_nop 15
	v_mov_b32_e32 v26, v19
	s_nop 1
	v_permlane32_swap_b32_e32 v19, v26
	v_max_f32_e32 v19, v19, v26
	v_max_f32_e32 v19, v19, v19
	v_max_f32_e32 v90, 0, v19
	v_exp_f32_e64 v91, -v90
	v_add_f32_e32 v239, v239, v90
	v_xor_b32_e32 v66, 0x80000000, v239
	v_mov_b32_e32 v67, v66
	v_mov_b32_e32 v68, v66
	v_mov_b32_e32 v69, v66
	v_mov_b32_e32 v70, v66
	v_mov_b32_e32 v71, v66
	v_mov_b32_e32 v72, v66
	v_mov_b32_e32 v73, v66
	v_mov_b32_e32 v74, v66
	v_mov_b32_e32 v75, v66
	v_mov_b32_e32 v76, v66
	v_mov_b32_e32 v77, v66
	v_mov_b32_e32 v78, v66
	v_mov_b32_e32 v79, v66
	v_mov_b32_e32 v80, v66
	v_mov_b32_e32 v81, v66
	v_sub_f32_e32 v142, v142, v90
	v_sub_f32_e32 v143, v143, v90
	v_sub_f32_e32 v144, v144, v90
	v_sub_f32_e32 v145, v145, v90
	v_sub_f32_e32 v146, v146, v90
	v_sub_f32_e32 v147, v147, v90
	v_sub_f32_e32 v148, v148, v90
	v_sub_f32_e32 v149, v149, v90
	v_sub_f32_e32 v150, v150, v90
	v_sub_f32_e32 v151, v151, v90
	v_sub_f32_e32 v152, v152, v90
	v_sub_f32_e32 v153, v153, v90
	v_sub_f32_e32 v154, v154, v90
	v_sub_f32_e32 v155, v155, v90
	v_sub_f32_e32 v156, v156, v90
	v_sub_f32_e32 v157, v157, v90
	v_sub_f32_e32 v158, v158, v90
	v_sub_f32_e32 v159, v159, v90
	v_sub_f32_e32 v160, v160, v90
	v_sub_f32_e32 v161, v161, v90
	v_sub_f32_e32 v162, v162, v90
	v_sub_f32_e32 v163, v163, v90
	v_sub_f32_e32 v164, v164, v90
	v_sub_f32_e32 v165, v165, v90
	v_sub_f32_e32 v166, v166, v90
	v_sub_f32_e32 v167, v167, v90
	v_sub_f32_e32 v168, v168, v90
	v_sub_f32_e32 v169, v169, v90
	v_sub_f32_e32 v170, v170, v90
	v_sub_f32_e32 v171, v171, v90
	v_sub_f32_e32 v172, v172, v90
	v_sub_f32_e32 v173, v173, v90
	v_mul_f32_e32 v236, v236, v91
	s_mov_b64 s[96:97], exec
	s_and_b64 exec, exec, s[8:9]
	ds_write_b32 v235, v91
	s_mov_b64 exec, s[96:97]
	v_lshl_add_u32 v2, v228, 4, s47
	ds_read_b128 v[94:97], v2 offset:0
	s_waitcnt lgkmcnt(0)
	v_mul_f32_e32 v34, v34, v94
	v_mul_f32_e32 v50, v50, v94
	v_mul_f32_e32 v35, v35, v95
	v_mul_f32_e32 v51, v51, v95
	v_mul_f32_e32 v36, v36, v96
	v_mul_f32_e32 v52, v52, v96
	v_mul_f32_e32 v37, v37, v97
	v_mul_f32_e32 v53, v53, v97
	ds_read_b128 v[94:97], v2 offset:32
	s_waitcnt lgkmcnt(0)
	v_mul_f32_e32 v38, v38, v94
	v_mul_f32_e32 v54, v54, v94
	v_mul_f32_e32 v39, v39, v95
	v_mul_f32_e32 v55, v55, v95
	v_mul_f32_e32 v40, v40, v96
	v_mul_f32_e32 v56, v56, v96
	v_mul_f32_e32 v41, v41, v97
	v_mul_f32_e32 v57, v57, v97
	ds_read_b128 v[94:97], v2 offset:64
	s_waitcnt lgkmcnt(0)
	v_mul_f32_e32 v42, v42, v94
	v_mul_f32_e32 v58, v58, v94
	v_mul_f32_e32 v43, v43, v95
	v_mul_f32_e32 v59, v59, v95
	v_mul_f32_e32 v44, v44, v96
	v_mul_f32_e32 v60, v60, v96
	v_mul_f32_e32 v45, v45, v97
	v_mul_f32_e32 v61, v61, v97
	ds_read_b128 v[94:97], v2 offset:96
	s_waitcnt lgkmcnt(0)
	v_mul_f32_e32 v46, v46, v94
	v_mul_f32_e32 v62, v62, v94
	v_mul_f32_e32 v47, v47, v95
	v_mul_f32_e32 v63, v63, v95
	v_mul_f32_e32 v48, v48, v96
	v_mul_f32_e32 v64, v64, v96
	v_mul_f32_e32 v49, v49, v97
	v_mul_f32_e32 v65, v65, v97

.Lmy_gl_5:
	v_exp_f32_e32 v158, v158
	v_exp_f32_e32 v159, v159
	v_exp_f32_e32 v160, v160
	v_add_f32_e32 v27, v27, v158
	v_exp_f32_e32 v161, v161
	v_mfma_f32_32x32x16_bf16 v[98:113], v[182:185], v[134:137], v[98:113]
	v_add_f32_e32 v27, v27, v159
	v_exp_f32_e32 v162, v162
	v_add_f32_e32 v27, v27, v160
	v_exp_f32_e32 v163, v163
	v_add_f32_e32 v27, v27, v161
	v_mfma_f32_32x32x16_bf16 v[82:97], v[178:181], v[138:141], v[82:97]
	v_exp_f32_e32 v164, v164
	v_add_f32_e32 v27, v27, v162
	v_exp_f32_e32 v165, v165
	v_add_f32_e32 v27, v27, v163
	v_add_f32_e32 v27, v27, v164
	v_mfma_f32_32x32x16_bf16 v[98:113], v[174:177], v[138:141], v[98:113]
	v_add_f32_e32 v27, v27, v165
	v_cvt_pk_bf16_f32 v158, v158, v159
	v_cvt_pk_bf16_f32 v159, v160, v161
	v_cvt_pk_bf16_f32 v160, v162, v163
	v_cvt_pk_bf16_f32 v161, v164, v165
	s_waitcnt lgkmcnt(0)
	v_add_u32_e32 v2, 0x3000, v238
	v_mfma_f32_32x32x16_bf16 v[34:49], v[142:145], v[114:117], v[34:49]
	v_exp_f32_e32 v166, v166
	v_exp_f32_e32 v167, v167
	v_exp_f32_e32 v168, v168
	v_add_f32_e32 v27, v27, v166
	v_exp_f32_e32 v169, v169
	ds_read_b128 v[218:221], v2
	ds_read_b128 v[214:217], v2 offset:512
	ds_read_b128 v[210:213], v2 offset:2048
	v_mfma_f32_32x32x16_bf16 v[50:65], v[142:145], v[240:243], v[50:65]
	v_add_f32_e32 v27, v27, v167
	v_exp_f32_e32 v170, v170
	v_add_f32_e32 v27, v27, v168
	v_exp_f32_e32 v171, v171
	v_add_f32_e32 v27, v27, v169
	ds_read_b128 v[206:209], v2 offset:2560
	ds_read_b128 v[202:205], v2 offset:4096
	ds_read_b128 v[198:201], v2 offset:4608
	v_mfma_f32_32x32x16_bf16 v[34:49], v[150:153], v[118:121], v[34:49]
	v_exp_f32_e32 v172, v172
	v_add_f32_e32 v27, v27, v170
	v_exp_f32_e32 v173, v173
	v_add_f32_e32 v27, v27, v171
	v_add_f32_e32 v27, v27, v172
	ds_read_b128 v[194:197], v2 offset:6144
	ds_read_b128 v[190:193], v2 offset:6656
	ds_read_b128 v[186:189], v2 offset:8192
	v_mfma_f32_32x32x16_bf16 v[50:65], v[150:153], v[244:247], v[50:65]
	v_add_f32_e32 v27, v27, v173
	v_cvt_pk_bf16_f32 v166, v166, v167
	v_cvt_pk_bf16_f32 v167, v168, v169
	v_cvt_pk_bf16_f32 v168, v170, v171
	v_cvt_pk_bf16_f32 v169, v172, v173
	v_add_f32_e32 v236, v236, v27
	ds_read_b128 v[182:185], v2 offset:8704
	ds_read_b128 v[178:181], v2 offset:10240
	ds_read_b128 v[174:177], v2 offset:10752
	v_mfma_f32_32x32x16_bf16 v[34:49], v[158:161], v[122:125], v[34:49]
	v_max3_f32 v19, v82, v83, v84
	v_max3_f32 v26, v85, v86, v87
	v_max3_f32 v19, v19, v88, v89
	v_max3_f32 v26, v26, v90, v91
	v_mfma_f32_32x32x16_bf16 v[50:65], v[158:161], v[248:251], v[50:65]
	v_max3_f32 v19, v19, v92, v93
	v_max3_f32 v26, v26, v94, v95
	v_max3_f32 v19, v19, v96, v97
	v_max3_f32 v26, v26, v98, v99
	v_mfma_f32_32x32x16_bf16 v[34:49], v[166:169], v[126:129], v[34:49]
	v_max3_f32 v19, v19, v100, v101
	v_max3_f32 v26, v26, v102, v103
	v_max3_f32 v19, v19, v104, v105
	v_max3_f32 v26, v26, v106, v107
	v_mfma_f32_32x32x16_bf16 v[50:65], v[166:169], v[20:23], v[50:65]
	v_max3_f32 v19, v19, v108, v109
	v_max3_f32 v26, v26, v110, v111
	v_max3_f32 v19, v19, v112, v113
	v_max_f32_e32 v19, v19, v26
	v_cmp_lt_f32_e32 vcc, s41, v19
	s_cbranch_vccz .Lmy_nors_6
	s_nop 15
	s_nop 15
	v_mov_b32_e32 v26, v19
	s_nop 1
	v_permlane32_swap_b32_e32 v19, v26
	v_max_f32_e32 v19, v19, v26
	v_max_f32_e32 v19, v19, v19
	v_max_f32_e32 v150, 0, v19
	v_exp_f32_e64 v151, -v150
	v_add_f32_e32 v239, v239, v150
	v_xor_b32_e32 v66, 0x80000000, v239
	v_mov_b32_e32 v67, v66
	v_mov_b32_e32 v68, v66
	v_mov_b32_e32 v69, v66
	v_mov_b32_e32 v70, v66
	v_mov_b32_e32 v71, v66
	v_mov_b32_e32 v72, v66
	v_mov_b32_e32 v73, v66
	v_mov_b32_e32 v74, v66
	v_mov_b32_e32 v75, v66
	v_mov_b32_e32 v76, v66
	v_mov_b32_e32 v77, v66
	v_mov_b32_e32 v78, v66
	v_mov_b32_e32 v79, v66
	v_mov_b32_e32 v80, v66
	v_mov_b32_e32 v81, v66
	v_sub_f32_e32 v82, v82, v150
	v_sub_f32_e32 v83, v83, v150
	v_sub_f32_e32 v84, v84, v150
	v_sub_f32_e32 v85, v85, v150
	v_sub_f32_e32 v86, v86, v150
	v_sub_f32_e32 v87, v87, v150
	v_sub_f32_e32 v88, v88, v150
	v_sub_f32_e32 v89, v89, v150
	v_sub_f32_e32 v90, v90, v150
	v_sub_f32_e32 v91, v91, v150
	v_sub_f32_e32 v92, v92, v150
	v_sub_f32_e32 v93, v93, v150
	v_sub_f32_e32 v94, v94, v150
	v_sub_f32_e32 v95, v95, v150
	v_sub_f32_e32 v96, v96, v150
	v_sub_f32_e32 v97, v97, v150
	v_sub_f32_e32 v98, v98, v150
	v_sub_f32_e32 v99, v99, v150
	v_sub_f32_e32 v100, v100, v150
	v_sub_f32_e32 v101, v101, v150
	v_sub_f32_e32 v102, v102, v150
	v_sub_f32_e32 v103, v103, v150
	v_sub_f32_e32 v104, v104, v150
	v_sub_f32_e32 v105, v105, v150
	v_sub_f32_e32 v106, v106, v150
	v_sub_f32_e32 v107, v107, v150
	v_sub_f32_e32 v108, v108, v150
	v_sub_f32_e32 v109, v109, v150
	v_sub_f32_e32 v110, v110, v150
	v_sub_f32_e32 v111, v111, v150
	v_sub_f32_e32 v112, v112, v150
	v_sub_f32_e32 v113, v113, v150
	v_mul_f32_e32 v236, v236, v151
	s_mov_b64 s[96:97], exec
	s_and_b64 exec, exec, s[8:9]
	ds_write_b32 v235, v151
	s_mov_b64 exec, s[96:97]
	v_lshl_add_u32 v2, v228, 4, s47
	ds_read_b128 v[154:157], v2 offset:0
	s_waitcnt lgkmcnt(0)
	v_mul_f32_e32 v34, v34, v154
	v_mul_f32_e32 v50, v50, v154
	v_mul_f32_e32 v35, v35, v155
	v_mul_f32_e32 v51, v51, v155
	v_mul_f32_e32 v36, v36, v156
	v_mul_f32_e32 v52, v52, v156
	v_mul_f32_e32 v37, v37, v157
	v_mul_f32_e32 v53, v53, v157
	ds_read_b128 v[154:157], v2 offset:32
	s_waitcnt lgkmcnt(0)
	v_mul_f32_e32 v38, v38, v154
	v_mul_f32_e32 v54, v54, v154
	v_mul_f32_e32 v39, v39, v155
	v_mul_f32_e32 v55, v55, v155
	v_mul_f32_e32 v40, v40, v156
	v_mul_f32_e32 v56, v56, v156
	v_mul_f32_e32 v41, v41, v157
	v_mul_f32_e32 v57, v57, v157
	ds_read_b128 v[154:157], v2 offset:64
	s_waitcnt lgkmcnt(0)
	v_mul_f32_e32 v42, v42, v154
	v_mul_f32_e32 v58, v58, v154
	v_mul_f32_e32 v43, v43, v155
	v_mul_f32_e32 v59, v59, v155
	v_mul_f32_e32 v44, v44, v156
	v_mul_f32_e32 v60, v60, v156
	v_mul_f32_e32 v45, v45, v157
	v_mul_f32_e32 v61, v61, v157
	ds_read_b128 v[154:157], v2 offset:96
	s_waitcnt lgkmcnt(0)
	v_mul_f32_e32 v46, v46, v154
	v_mul_f32_e32 v62, v62, v154
	v_mul_f32_e32 v47, v47, v155
	v_mul_f32_e32 v63, v63, v155
	v_mul_f32_e32 v48, v48, v156
	v_mul_f32_e32 v64, v64, v156
	v_mul_f32_e32 v49, v49, v157
	v_mul_f32_e32 v65, v65, v157

.Lmy_A_loop:
	s_waitcnt lgkmcnt(0)
	v_mov_b32_e32 v2, v237
	v_mfma_f32_32x32x16_bf16 v[142:157], v[218:221], v[4:7], v[66:81]
	v_exp_f32_e32 v82, v82
	v_exp_f32_e32 v83, v83
	v_exp_f32_e32 v84, v84
	v_add_f32_e32 v27, v82, v83
	v_exp_f32_e32 v85, v85
	ds_read_b64_tr_b16 v[114:115], v2 offset:49152
	ds_read_b64_tr_b16 v[116:117], v2 offset:49664
	ds_read_b64_tr_b16 v[118:119], v2 offset:50176
	ds_read_b64_tr_b16 v[120:121], v2 offset:50688
	v_mfma_f32_32x32x16_bf16 v[158:173], v[214:217], v[4:7], v[66:81]
	v_exp_f32_e32 v86, v86
	v_add_f32_e32 v27, v27, v84
	v_exp_f32_e32 v87, v87
	v_add_f32_e32 v27, v27, v85
	v_exp_f32_e32 v88, v88
	ds_read_b64_tr_b16 v[122:123], v2 offset:51200
	ds_read_b64_tr_b16 v[124:125], v2 offset:51712
	ds_read_b64_tr_b16 v[126:127], v2 offset:52224
	ds_read_b64_tr_b16 v[128:129], v2 offset:52736
	v_mfma_f32_32x32x16_bf16 v[142:157], v[210:213], v[8:11], v[142:157]
	v_add_f32_e32 v27, v27, v86
	v_exp_f32_e32 v89, v89
	v_add_f32_e32 v27, v27, v87
	v_add_f32_e32 v27, v27, v88
	v_add_f32_e32 v27, v27, v89
	ds_read_b64_tr_b16 v[240:241], v2 offset:53248
	ds_read_b64_tr_b16 v[242:243], v2 offset:53760
	ds_read_b64_tr_b16 v[244:245], v2 offset:54272
	ds_read_b64_tr_b16 v[246:247], v2 offset:54784
	v_mfma_f32_32x32x16_bf16 v[158:173], v[206:209], v[8:11], v[158:173]
	v_cvt_pk_bf16_f32 v82, v82, v83
	v_cvt_pk_bf16_f32 v83, v84, v85
	v_cvt_pk_bf16_f32 v84, v86, v87
	v_cvt_pk_bf16_f32 v85, v88, v89
	ds_read_b64_tr_b16 v[248:249], v2 offset:55296
	ds_read_b64_tr_b16 v[250:251], v2 offset:55808
	ds_read_b64_tr_b16 v[20:21], v2 offset:56320
	ds_read_b64_tr_b16 v[22:23], v2 offset:56832
	v_mfma_f32_32x32x16_bf16 v[142:157], v[202:205], v[12:15], v[142:157]
	v_exp_f32_e32 v90, v90
	v_exp_f32_e32 v91, v91
	v_exp_f32_e32 v92, v92
	v_add_f32_e32 v27, v27, v90
	v_exp_f32_e32 v93, v93
	v_mfma_f32_32x32x16_bf16 v[158:173], v[198:201], v[12:15], v[158:173]
	v_add_f32_e32 v27, v27, v91
	v_exp_f32_e32 v94, v94
	v_add_f32_e32 v27, v27, v92
	v_exp_f32_e32 v95, v95
	v_add_f32_e32 v27, v27, v93
	s_waitcnt vmcnt(6)
	s_barrier
	v_mfma_f32_32x32x16_bf16 v[142:157], v[194:197], v[130:133], v[142:157]
	s_add_u32 m0, s57, 0x6000
	v_exp_f32_e32 v96, v96
	v_add_f32_e32 v27, v27, v94
	global_load_lds_dwordx4 v[28:29], off
	v_lshl_add_u64 v[28:29], v[28:29], 0, s[30:31]
	v_exp_f32_e32 v97, v97
	v_add_f32_e32 v27, v27, v95
	v_add_f32_e32 v27, v27, v96
	v_mfma_f32_32x32x16_bf16 v[158:173], v[190:193], v[130:133], v[158:173]
	s_add_u32 m0, s40, 0x3000
	v_add_f32_e32 v27, v27, v97
	v_cvt_pk_bf16_f32 v90, v90, v91
	global_load_lds_dwordx4 v[24:25], off
	v_lshl_add_u64 v[24:25], v[24:25], 0, s[30:31]
	v_cvt_pk_bf16_f32 v91, v92, v93
	v_cvt_pk_bf16_f32 v92, v94, v95
	v_cvt_pk_bf16_f32 v93, v96, v97
	v_mfma_f32_32x32x16_bf16 v[142:157], v[186:189], v[134:137], v[142:157]
	s_add_u32 m0, s43, 0x3000
	v_exp_f32_e32 v98, v98
	v_exp_f32_e32 v99, v99
	global_load_lds_dwordx4 v[30:31], off
	v_lshl_add_u64 v[30:31], v[30:31], 0, s[12:13]
	v_exp_f32_e32 v100, v100
	v_add_f32_e32 v27, v27, v98
	v_exp_f32_e32 v101, v101
	v_mfma_f32_32x32x16_bf16 v[158:173], v[182:185], v[134:137], v[158:173]
	v_add_f32_e32 v27, v27, v99
	v_exp_f32_e32 v102, v102
	v_add_f32_e32 v27, v27, v100
	v_exp_f32_e32 v103, v103
	v_add_f32_e32 v27, v27, v101
	v_mfma_f32_32x32x16_bf16 v[142:157], v[178:181], v[138:141], v[142:157]
	v_exp_f32_e32 v104, v104
	v_add_f32_e32 v27, v27, v102
	v_exp_f32_e32 v105, v105
	v_add_f32_e32 v27, v27, v103
	v_add_f32_e32 v27, v27, v104
	v_mfma_f32_32x32x16_bf16 v[158:173], v[174:177], v[138:141], v[158:173]
	v_add_f32_e32 v27, v27, v105
	v_cvt_pk_bf16_f32 v98, v98, v99
	v_cvt_pk_bf16_f32 v99, v100, v101
	v_cvt_pk_bf16_f32 v100, v102, v103
	v_cvt_pk_bf16_f32 v101, v104, v105
	s_waitcnt lgkmcnt(0)
	v_add_u32_e32 v2, 0x6000, v238
	v_mfma_f32_32x32x16_bf16 v[34:49], v[82:85], v[114:117], v[34:49]
	v_exp_f32_e32 v106, v106
	v_exp_f32_e32 v107, v107
	v_exp_f32_e32 v108, v108
	v_add_f32_e32 v27, v27, v106
	v_exp_f32_e32 v109, v109
	ds_read_b128 v[218:221], v2
	ds_read_b128 v[214:217], v2 offset:512
	ds_read_b128 v[210:213], v2 offset:2048
	v_mfma_f32_32x32x16_bf16 v[50:65], v[82:85], v[240:243], v[50:65]
	v_add_f32_e32 v27, v27, v107
	v_exp_f32_e32 v110, v110
	v_add_f32_e32 v27, v27, v108
	v_exp_f32_e32 v111, v111
	v_add_f32_e32 v27, v27, v109
	ds_read_b128 v[206:209], v2 offset:2560
	ds_read_b128 v[202:205], v2 offset:4096
	ds_read_b128 v[198:201], v2 offset:4608
	v_mfma_f32_32x32x16_bf16 v[34:49], v[90:93], v[118:121], v[34:49]
	v_exp_f32_e32 v112, v112
	v_add_f32_e32 v27, v27, v110
	v_exp_f32_e32 v113, v113
	v_add_f32_e32 v27, v27, v111
	v_add_f32_e32 v27, v27, v112
	ds_read_b128 v[194:197], v2 offset:6144
	ds_read_b128 v[190:193], v2 offset:6656
	ds_read_b128 v[186:189], v2 offset:8192
	v_mfma_f32_32x32x16_bf16 v[50:65], v[90:93], v[244:247], v[50:65]
	v_add_f32_e32 v27, v27, v113
	v_cvt_pk_bf16_f32 v106, v106, v107
	v_cvt_pk_bf16_f32 v107, v108, v109
	v_cvt_pk_bf16_f32 v108, v110, v111
	v_cvt_pk_bf16_f32 v109, v112, v113
	v_add_f32_e32 v236, v236, v27
	ds_read_b128 v[182:185], v2 offset:8704
	ds_read_b128 v[178:181], v2 offset:10240
	ds_read_b128 v[174:177], v2 offset:10752
	v_mfma_f32_32x32x16_bf16 v[34:49], v[98:101], v[122:125], v[34:49]
	v_max3_f32 v19, v142, v143, v144
	v_max3_f32 v26, v145, v146, v147
	v_max3_f32 v19, v19, v148, v149
	v_max3_f32 v26, v26, v150, v151
	v_mfma_f32_32x32x16_bf16 v[50:65], v[98:101], v[248:251], v[50:65]
	v_max3_f32 v19, v19, v152, v153
	v_max3_f32 v26, v26, v154, v155
	v_max3_f32 v19, v19, v156, v157
	v_max3_f32 v26, v26, v158, v159
	v_mfma_f32_32x32x16_bf16 v[34:49], v[106:109], v[126:129], v[34:49]
	v_max3_f32 v19, v19, v160, v161
	v_max3_f32 v26, v26, v162, v163
	v_max3_f32 v19, v19, v164, v165
	v_max3_f32 v26, v26, v166, v167
	v_mfma_f32_32x32x16_bf16 v[50:65], v[106:109], v[20:23], v[50:65]
	v_max3_f32 v19, v19, v168, v169
	v_max3_f32 v26, v26, v170, v171
	v_max3_f32 v19, v19, v172, v173
	v_max_f32_e32 v19, v19, v26
	v_cmp_lt_f32_e32 vcc, s41, v19
	s_cbranch_vccz .Lmy_nors_7
	s_nop 15
	s_nop 15
	v_mov_b32_e32 v26, v19
	s_nop 1
	v_permlane32_swap_b32_e32 v19, v26
	v_max_f32_e32 v19, v19, v26
	v_max_f32_e32 v19, v19, v19
	v_max_f32_e32 v90, 0, v19
	v_exp_f32_e64 v91, -v90
	v_add_f32_e32 v239, v239, v90
	v_xor_b32_e32 v66, 0x80000000, v239
	v_mov_b32_e32 v67, v66
	v_mov_b32_e32 v68, v66
	v_mov_b32_e32 v69, v66
	v_mov_b32_e32 v70, v66
	v_mov_b32_e32 v71, v66
	v_mov_b32_e32 v72, v66
	v_mov_b32_e32 v73, v66
	v_mov_b32_e32 v74, v66
	v_mov_b32_e32 v75, v66
	v_mov_b32_e32 v76, v66
	v_mov_b32_e32 v77, v66
	v_mov_b32_e32 v78, v66
	v_mov_b32_e32 v79, v66
	v_mov_b32_e32 v80, v66
	v_mov_b32_e32 v81, v66
	v_sub_f32_e32 v142, v142, v90
	v_sub_f32_e32 v143, v143, v90
	v_sub_f32_e32 v144, v144, v90
	v_sub_f32_e32 v145, v145, v90
	v_sub_f32_e32 v146, v146, v90
	v_sub_f32_e32 v147, v147, v90
	v_sub_f32_e32 v148, v148, v90
	v_sub_f32_e32 v149, v149, v90
	v_sub_f32_e32 v150, v150, v90
	v_sub_f32_e32 v151, v151, v90
	v_sub_f32_e32 v152, v152, v90
	v_sub_f32_e32 v153, v153, v90
	v_sub_f32_e32 v154, v154, v90
	v_sub_f32_e32 v155, v155, v90
	v_sub_f32_e32 v156, v156, v90
	v_sub_f32_e32 v157, v157, v90
	v_sub_f32_e32 v158, v158, v90
	v_sub_f32_e32 v159, v159, v90
	v_sub_f32_e32 v160, v160, v90
	v_sub_f32_e32 v161, v161, v90
	v_sub_f32_e32 v162, v162, v90
	v_sub_f32_e32 v163, v163, v90
	v_sub_f32_e32 v164, v164, v90
	v_sub_f32_e32 v165, v165, v90
	v_sub_f32_e32 v166, v166, v90
	v_sub_f32_e32 v167, v167, v90
	v_sub_f32_e32 v168, v168, v90
	v_sub_f32_e32 v169, v169, v90
	v_sub_f32_e32 v170, v170, v90
	v_sub_f32_e32 v171, v171, v90
	v_sub_f32_e32 v172, v172, v90
	v_sub_f32_e32 v173, v173, v90
	v_mul_f32_e32 v236, v236, v91
	s_mov_b64 s[96:97], exec
	s_and_b64 exec, exec, s[8:9]
	ds_write_b32 v235, v91
	s_mov_b64 exec, s[96:97]
	v_lshl_add_u32 v2, v228, 4, s47
	ds_read_b128 v[94:97], v2 offset:0
	s_waitcnt lgkmcnt(0)
	v_mul_f32_e32 v34, v34, v94
	v_mul_f32_e32 v50, v50, v94
	v_mul_f32_e32 v35, v35, v95
	v_mul_f32_e32 v51, v51, v95
	v_mul_f32_e32 v36, v36, v96
	v_mul_f32_e32 v52, v52, v96
	v_mul_f32_e32 v37, v37, v97
	v_mul_f32_e32 v53, v53, v97
	ds_read_b128 v[94:97], v2 offset:32
	s_waitcnt lgkmcnt(0)
	v_mul_f32_e32 v38, v38, v94
	v_mul_f32_e32 v54, v54, v94
	v_mul_f32_e32 v39, v39, v95
	v_mul_f32_e32 v55, v55, v95
	v_mul_f32_e32 v40, v40, v96
	v_mul_f32_e32 v56, v56, v96
	v_mul_f32_e32 v41, v41, v97
	v_mul_f32_e32 v57, v57, v97
	ds_read_b128 v[94:97], v2 offset:64
	s_waitcnt lgkmcnt(0)
	v_mul_f32_e32 v42, v42, v94
	v_mul_f32_e32 v58, v58, v94
	v_mul_f32_e32 v43, v43, v95
	v_mul_f32_e32 v59, v59, v95
	v_mul_f32_e32 v44, v44, v96
	v_mul_f32_e32 v60, v60, v96
	v_mul_f32_e32 v45, v45, v97
	v_mul_f32_e32 v61, v61, v97
	ds_read_b128 v[94:97], v2 offset:96
	s_waitcnt lgkmcnt(0)
	v_mul_f32_e32 v46, v46, v94
	v_mul_f32_e32 v62, v62, v94
	v_mul_f32_e32 v47, v47, v95
	v_mul_f32_e32 v63, v63, v95
	v_mul_f32_e32 v48, v48, v96
	v_mul_f32_e32 v64, v64, v96
	v_mul_f32_e32 v49, v49, v97
	v_mul_f32_e32 v65, v65, v97
.Lmy_nors_7:
	s_waitcnt lgkmcnt(0)
	v_add_u32_e32 v2, 0x2000, v237
	v_mfma_f32_32x32x16_bf16 v[82:97], v[218:221], v[4:7], v[66:81]
	v_exp_f32_e32 v142, v142
	v_exp_f32_e32 v143, v143
	v_exp_f32_e32 v144, v144
	v_add_f32_e32 v27, v142, v143
	v_exp_f32_e32 v145, v145
	ds_read_b64_tr_b16 v[114:115], v2 offset:49152
	ds_read_b64_tr_b16 v[116:117], v2 offset:49664
	ds_read_b64_tr_b16 v[118:119], v2 offset:50176
	ds_read_b64_tr_b16 v[120:121], v2 offset:50688
	v_mfma_f32_32x32x16_bf16 v[98:113], v[214:217], v[4:7], v[66:81]
	v_exp_f32_e32 v146, v146
	v_add_f32_e32 v27, v27, v144
	v_exp_f32_e32 v147, v147
	v_add_f32_e32 v27, v27, v145
	v_exp_f32_e32 v148, v148
	ds_read_b64_tr_b16 v[122:123], v2 offset:51200
	ds_read_b64_tr_b16 v[124:125], v2 offset:51712
	ds_read_b64_tr_b16 v[126:127], v2 offset:52224
	ds_read_b64_tr_b16 v[128:129], v2 offset:52736
	v_mfma_f32_32x32x16_bf16 v[82:97], v[210:213], v[8:11], v[82:97]
	v_add_f32_e32 v27, v27, v146
	v_exp_f32_e32 v149, v149
	v_add_f32_e32 v27, v27, v147
	v_add_f32_e32 v27, v27, v148
	v_add_f32_e32 v27, v27, v149
	ds_read_b64_tr_b16 v[240:241], v2 offset:53248
	ds_read_b64_tr_b16 v[242:243], v2 offset:53760
	ds_read_b64_tr_b16 v[244:245], v2 offset:54272
	ds_read_b64_tr_b16 v[246:247], v2 offset:54784
	v_mfma_f32_32x32x16_bf16 v[98:113], v[206:209], v[8:11], v[98:113]
	v_cvt_pk_bf16_f32 v142, v142, v143
	v_cvt_pk_bf16_f32 v143, v144, v145
	v_cvt_pk_bf16_f32 v144, v146, v147
	v_cvt_pk_bf16_f32 v145, v148, v149
	ds_read_b64_tr_b16 v[248:249], v2 offset:55296
	ds_read_b64_tr_b16 v[250:251], v2 offset:55808
	ds_read_b64_tr_b16 v[20:21], v2 offset:56320
	ds_read_b64_tr_b16 v[22:23], v2 offset:56832
	v_mfma_f32_32x32x16_bf16 v[82:97], v[202:205], v[12:15], v[82:97]
	v_exp_f32_e32 v150, v150
	v_exp_f32_e32 v151, v151
	v_exp_f32_e32 v152, v152
	v_add_f32_e32 v27, v27, v150
	v_exp_f32_e32 v153, v153
	v_mfma_f32_32x32x16_bf16 v[98:113], v[198:201], v[12:15], v[98:113]
	v_add_f32_e32 v27, v27, v151
	v_exp_f32_e32 v154, v154
	v_add_f32_e32 v27, v27, v152
	v_exp_f32_e32 v155, v155
	v_add_f32_e32 v27, v27, v153
	s_waitcnt vmcnt(6)
	s_barrier
	v_mfma_f32_32x32x16_bf16 v[82:97], v[194:197], v[130:133], v[82:97]
	s_add_u32 m0, s57, 0x0
	v_exp_f32_e32 v156, v156
	v_add_f32_e32 v27, v27, v154
	global_load_lds_dwordx4 v[28:29], off
	v_lshl_add_u64 v[28:29], v[28:29], 0, s[30:31]
	v_exp_f32_e32 v157, v157
	v_add_f32_e32 v27, v27, v155
	v_add_f32_e32 v27, v27, v156
	v_mfma_f32_32x32x16_bf16 v[98:113], v[190:193], v[130:133], v[98:113]
	s_add_u32 m0, s40, 0x6000
	v_add_f32_e32 v27, v27, v157
	v_cvt_pk_bf16_f32 v150, v150, v151
	global_load_lds_dwordx4 v[24:25], off
	v_lshl_add_u64 v[24:25], v[24:25], 0, s[30:31]
	v_cvt_pk_bf16_f32 v151, v152, v153
	v_cvt_pk_bf16_f32 v152, v154, v155
	v_cvt_pk_bf16_f32 v153, v156, v157
	v_mfma_f32_32x32x16_bf16 v[82:97], v[186:189], v[134:137], v[82:97]
	s_add_u32 m0, s43, 0x6000
	v_exp_f32_e32 v158, v158
	v_exp_f32_e32 v159, v159
	global_load_lds_dwordx4 v[30:31], off
	v_lshl_add_u64 v[30:31], v[30:31], 0, s[12:13]
	v_exp_f32_e32 v160, v160
	v_add_f32_e32 v27, v27, v158
	v_exp_f32_e32 v161, v161
	v_mfma_f32_32x32x16_bf16 v[98:113], v[182:185], v[134:137], v[98:113]
	v_add_f32_e32 v27, v27, v159
	v_exp_f32_e32 v162, v162
	v_add_f32_e32 v27, v27, v160
	v_exp_f32_e32 v163, v163
	v_add_f32_e32 v27, v27, v161
	v_mfma_f32_32x32x16_bf16 v[82:97], v[178:181], v[138:141], v[82:97]
	v_exp_f32_e32 v164, v164
	v_add_f32_e32 v27, v27, v162
	v_exp_f32_e32 v165, v165
	v_add_f32_e32 v27, v27, v163
	v_add_f32_e32 v27, v27, v164
	v_mfma_f32_32x32x16_bf16 v[98:113], v[174:177], v[138:141], v[98:113]
	v_add_f32_e32 v27, v27, v165
	v_cvt_pk_bf16_f32 v158, v158, v159
	v_cvt_pk_bf16_f32 v159, v160, v161
	v_cvt_pk_bf16_f32 v160, v162, v163
	v_cvt_pk_bf16_f32 v161, v164, v165
	s_waitcnt lgkmcnt(0)
	v_add_u32_e32 v2, 0x9000, v238
	v_mfma_f32_32x32x16_bf16 v[34:49], v[142:145], v[114:117], v[34:49]
	v_exp_f32_e32 v166, v166
	v_exp_f32_e32 v167, v167
	v_exp_f32_e32 v168, v168
	v_add_f32_e32 v27, v27, v166
	v_exp_f32_e32 v169, v169
	ds_read_b128 v[218:221], v2
	ds_read_b128 v[214:217], v2 offset:512
	ds_read_b128 v[210:213], v2 offset:2048
	v_mfma_f32_32x32x16_bf16 v[50:65], v[142:145], v[240:243], v[50:65]
	v_add_f32_e32 v27, v27, v167
	v_exp_f32_e32 v170, v170
	v_add_f32_e32 v27, v27, v168
	v_exp_f32_e32 v171, v171
	v_add_f32_e32 v27, v27, v169
	ds_read_b128 v[206:209], v2 offset:2560
	ds_read_b128 v[202:205], v2 offset:4096
	ds_read_b128 v[198:201], v2 offset:4608
	v_mfma_f32_32x32x16_bf16 v[34:49], v[150:153], v[118:121], v[34:49]
	v_exp_f32_e32 v172, v172
	v_add_f32_e32 v27, v27, v170
	v_exp_f32_e32 v173, v173
	v_add_f32_e32 v27, v27, v171
	v_add_f32_e32 v27, v27, v172
	ds_read_b128 v[194:197], v2 offset:6144
	ds_read_b128 v[190:193], v2 offset:6656
	ds_read_b128 v[186:189], v2 offset:8192
	v_mfma_f32_32x32x16_bf16 v[50:65], v[150:153], v[244:247], v[50:65]
	v_add_f32_e32 v27, v27, v173
	v_cvt_pk_bf16_f32 v166, v166, v167
	v_cvt_pk_bf16_f32 v167, v168, v169
	v_cvt_pk_bf16_f32 v168, v170, v171
	v_cvt_pk_bf16_f32 v169, v172, v173
	v_add_f32_e32 v236, v236, v27
	ds_read_b128 v[182:185], v2 offset:8704
	ds_read_b128 v[178:181], v2 offset:10240
	ds_read_b128 v[174:177], v2 offset:10752
	v_mfma_f32_32x32x16_bf16 v[34:49], v[158:161], v[122:125], v[34:49]
	v_max3_f32 v19, v82, v83, v84
	v_max3_f32 v26, v85, v86, v87
	v_max3_f32 v19, v19, v88, v89
	v_max3_f32 v26, v26, v90, v91
	v_mfma_f32_32x32x16_bf16 v[50:65], v[158:161], v[248:251], v[50:65]
	v_max3_f32 v19, v19, v92, v93
	v_max3_f32 v26, v26, v94, v95
	v_max3_f32 v19, v19, v96, v97
	v_max3_f32 v26, v26, v98, v99
	v_mfma_f32_32x32x16_bf16 v[34:49], v[166:169], v[126:129], v[34:49]
	v_max3_f32 v19, v19, v100, v101
	v_max3_f32 v26, v26, v102, v103
	v_max3_f32 v19, v19, v104, v105
	v_max3_f32 v26, v26, v106, v107
	v_mfma_f32_32x32x16_bf16 v[50:65], v[166:169], v[20:23], v[50:65]
	v_max3_f32 v19, v19, v108, v109
	v_max3_f32 v26, v26, v110, v111
	v_max3_f32 v19, v19, v112, v113
	v_max_f32_e32 v19, v19, v26
	v_cmp_lt_f32_e32 vcc, s41, v19
	s_cbranch_vccz .Lmy_nors_8
	s_nop 15
	s_nop 15
	v_mov_b32_e32 v26, v19
	s_nop 1
	v_permlane32_swap_b32_e32 v19, v26
	v_max_f32_e32 v19, v19, v26
	v_max_f32_e32 v19, v19, v19
	v_max_f32_e32 v150, 0, v19
	v_exp_f32_e64 v151, -v150
	v_add_f32_e32 v239, v239, v150
	v_xor_b32_e32 v66, 0x80000000, v239
	v_mov_b32_e32 v67, v66
	v_mov_b32_e32 v68, v66
	v_mov_b32_e32 v69, v66
	v_mov_b32_e32 v70, v66
	v_mov_b32_e32 v71, v66
	v_mov_b32_e32 v72, v66
	v_mov_b32_e32 v73, v66
	v_mov_b32_e32 v74, v66
	v_mov_b32_e32 v75, v66
	v_mov_b32_e32 v76, v66
	v_mov_b32_e32 v77, v66
	v_mov_b32_e32 v78, v66
	v_mov_b32_e32 v79, v66
	v_mov_b32_e32 v80, v66
	v_mov_b32_e32 v81, v66
	v_sub_f32_e32 v82, v82, v150
	v_sub_f32_e32 v83, v83, v150
	v_sub_f32_e32 v84, v84, v150
	v_sub_f32_e32 v85, v85, v150
	v_sub_f32_e32 v86, v86, v150
	v_sub_f32_e32 v87, v87, v150
	v_sub_f32_e32 v88, v88, v150
	v_sub_f32_e32 v89, v89, v150
	v_sub_f32_e32 v90, v90, v150
	v_sub_f32_e32 v91, v91, v150
	v_sub_f32_e32 v92, v92, v150
	v_sub_f32_e32 v93, v93, v150
	v_sub_f32_e32 v94, v94, v150
	v_sub_f32_e32 v95, v95, v150
	v_sub_f32_e32 v96, v96, v150
	v_sub_f32_e32 v97, v97, v150
	v_sub_f32_e32 v98, v98, v150
	v_sub_f32_e32 v99, v99, v150
	v_sub_f32_e32 v100, v100, v150
	v_sub_f32_e32 v101, v101, v150
	v_sub_f32_e32 v102, v102, v150
	v_sub_f32_e32 v103, v103, v150
	v_sub_f32_e32 v104, v104, v150
	v_sub_f32_e32 v105, v105, v150
	v_sub_f32_e32 v106, v106, v150
	v_sub_f32_e32 v107, v107, v150
	v_sub_f32_e32 v108, v108, v150
	v_sub_f32_e32 v109, v109, v150
	v_sub_f32_e32 v110, v110, v150
	v_sub_f32_e32 v111, v111, v150
	v_sub_f32_e32 v112, v112, v150
	v_sub_f32_e32 v113, v113, v150
	v_mul_f32_e32 v236, v236, v151
	s_mov_b64 s[96:97], exec
	s_and_b64 exec, exec, s[8:9]
	ds_write_b32 v235, v151
	s_mov_b64 exec, s[96:97]
	v_lshl_add_u32 v2, v228, 4, s47
	ds_read_b128 v[154:157], v2 offset:0
	s_waitcnt lgkmcnt(0)
	v_mul_f32_e32 v34, v34, v154
	v_mul_f32_e32 v50, v50, v154
	v_mul_f32_e32 v35, v35, v155
	v_mul_f32_e32 v51, v51, v155
	v_mul_f32_e32 v36, v36, v156
	v_mul_f32_e32 v52, v52, v156
	v_mul_f32_e32 v37, v37, v157
	v_mul_f32_e32 v53, v53, v157
	ds_read_b128 v[154:157], v2 offset:32
	s_waitcnt lgkmcnt(0)
	v_mul_f32_e32 v38, v38, v154
	v_mul_f32_e32 v54, v54, v154
	v_mul_f32_e32 v39, v39, v155
	v_mul_f32_e32 v55, v55, v155
	v_mul_f32_e32 v40, v40, v156
	v_mul_f32_e32 v56, v56, v156
	v_mul_f32_e32 v41, v41, v157
	v_mul_f32_e32 v57, v57, v157
	ds_read_b128 v[154:157], v2 offset:64
	s_waitcnt lgkmcnt(0)
	v_mul_f32_e32 v42, v42, v154
	v_mul_f32_e32 v58, v58, v154
	v_mul_f32_e32 v43, v43, v155
	v_mul_f32_e32 v59, v59, v155
	v_mul_f32_e32 v44, v44, v156
	v_mul_f32_e32 v60, v60, v156
	v_mul_f32_e32 v45, v45, v157
	v_mul_f32_e32 v61, v61, v157
	ds_read_b128 v[154:157], v2 offset:96
	s_waitcnt lgkmcnt(0)
	v_mul_f32_e32 v46, v46, v154
	v_mul_f32_e32 v62, v62, v154
	v_mul_f32_e32 v47, v47, v155
	v_mul_f32_e32 v63, v63, v155
	v_mul_f32_e32 v48, v48, v156
	v_mul_f32_e32 v64, v64, v156
	v_mul_f32_e32 v49, v49, v157
	v_mul_f32_e32 v65, v65, v157
.Lmy_nors_8:
	s_waitcnt lgkmcnt(0)
	v_add_u32_e32 v2, 0x4000, v237
	v_mfma_f32_32x32x16_bf16 v[142:157], v[218:221], v[4:7], v[66:81]
	v_exp_f32_e32 v82, v82
	v_exp_f32_e32 v83, v83
	v_exp_f32_e32 v84, v84
	v_add_f32_e32 v27, v82, v83
	v_exp_f32_e32 v85, v85
	ds_read_b64_tr_b16 v[114:115], v2 offset:49152
	ds_read_b64_tr_b16 v[116:117], v2 offset:49664
	ds_read_b64_tr_b16 v[118:119], v2 offset:50176
	ds_read_b64_tr_b16 v[120:121], v2 offset:50688
	v_mfma_f32_32x32x16_bf16 v[158:173], v[214:217], v[4:7], v[66:81]
	v_exp_f32_e32 v86, v86
	v_add_f32_e32 v27, v27, v84
	v_exp_f32_e32 v87, v87
	v_add_f32_e32 v27, v27, v85
	v_exp_f32_e32 v88, v88
	ds_read_b64_tr_b16 v[122:123], v2 offset:51200
	ds_read_b64_tr_b16 v[124:125], v2 offset:51712
	ds_read_b64_tr_b16 v[126:127], v2 offset:52224
	ds_read_b64_tr_b16 v[128:129], v2 offset:52736
	v_mfma_f32_32x32x16_bf16 v[142:157], v[210:213], v[8:11], v[142:157]
	v_add_f32_e32 v27, v27, v86
	v_exp_f32_e32 v89, v89
	v_add_f32_e32 v27, v27, v87
	v_add_f32_e32 v27, v27, v88
	v_add_f32_e32 v27, v27, v89
	ds_read_b64_tr_b16 v[240:241], v2 offset:53248
	ds_read_b64_tr_b16 v[242:243], v2 offset:53760
	ds_read_b64_tr_b16 v[244:245], v2 offset:54272
	ds_read_b64_tr_b16 v[246:247], v2 offset:54784
	v_mfma_f32_32x32x16_bf16 v[158:173], v[206:209], v[8:11], v[158:173]
	v_cvt_pk_bf16_f32 v82, v82, v83
	v_cvt_pk_bf16_f32 v83, v84, v85
	v_cvt_pk_bf16_f32 v84, v86, v87
	v_cvt_pk_bf16_f32 v85, v88, v89
	ds_read_b64_tr_b16 v[248:249], v2 offset:55296
	ds_read_b64_tr_b16 v[250:251], v2 offset:55808
	ds_read_b64_tr_b16 v[20:21], v2 offset:56320
	ds_read_b64_tr_b16 v[22:23], v2 offset:56832
	v_mfma_f32_32x32x16_bf16 v[142:157], v[202:205], v[12:15], v[142:157]
	v_exp_f32_e32 v90, v90
	v_exp_f32_e32 v91, v91
	v_exp_f32_e32 v92, v92
	v_add_f32_e32 v27, v27, v90
	v_exp_f32_e32 v93, v93
	v_mfma_f32_32x32x16_bf16 v[158:173], v[198:201], v[12:15], v[158:173]
	v_add_f32_e32 v27, v27, v91
	v_exp_f32_e32 v94, v94
	v_add_f32_e32 v27, v27, v92
	v_exp_f32_e32 v95, v95
	v_add_f32_e32 v27, v27, v93
	s_waitcnt vmcnt(6)
	s_barrier
	v_mfma_f32_32x32x16_bf16 v[142:157], v[194:197], v[130:133], v[142:157]
	s_add_u32 m0, s57, 0x2000
	v_exp_f32_e32 v96, v96
	v_add_f32_e32 v27, v27, v94
	global_load_lds_dwordx4 v[28:29], off
	v_lshl_add_u64 v[28:29], v[28:29], 0, s[30:31]
	v_exp_f32_e32 v97, v97
	v_add_f32_e32 v27, v27, v95
	v_add_f32_e32 v27, v27, v96
	v_mfma_f32_32x32x16_bf16 v[158:173], v[190:193], v[130:133], v[158:173]
	s_add_u32 m0, s40, 0x9000
	v_add_f32_e32 v27, v27, v97
	v_cvt_pk_bf16_f32 v90, v90, v91
	global_load_lds_dwordx4 v[24:25], off
	v_lshl_add_u64 v[24:25], v[24:25], 0, s[30:31]
	v_cvt_pk_bf16_f32 v91, v92, v93
	v_cvt_pk_bf16_f32 v92, v94, v95
	v_cvt_pk_bf16_f32 v93, v96, v97
	v_mfma_f32_32x32x16_bf16 v[142:157], v[186:189], v[134:137], v[142:157]
	s_add_u32 m0, s43, 0x9000
	v_exp_f32_e32 v98, v98
	v_exp_f32_e32 v99, v99
	global_load_lds_dwordx4 v[30:31], off
	v_lshl_add_u64 v[30:31], v[30:31], 0, s[12:13]
	v_exp_f32_e32 v100, v100
	v_add_f32_e32 v27, v27, v98
	v_exp_f32_e32 v101, v101
	v_mfma_f32_32x32x16_bf16 v[158:173], v[182:185], v[134:137], v[158:173]
	v_add_f32_e32 v27, v27, v99
	v_exp_f32_e32 v102, v102
	v_add_f32_e32 v27, v27, v100
	v_exp_f32_e32 v103, v103
	v_add_f32_e32 v27, v27, v101
	v_mfma_f32_32x32x16_bf16 v[142:157], v[178:181], v[138:141], v[142:157]
	v_exp_f32_e32 v104, v104
	v_add_f32_e32 v27, v27, v102
	v_exp_f32_e32 v105, v105
	v_add_f32_e32 v27, v27, v103
	v_add_f32_e32 v27, v27, v104
	v_mfma_f32_32x32x16_bf16 v[158:173], v[174:177], v[138:141], v[158:173]
	v_add_f32_e32 v27, v27, v105
	v_cvt_pk_bf16_f32 v98, v98, v99
	v_cvt_pk_bf16_f32 v99, v100, v101
	v_cvt_pk_bf16_f32 v100, v102, v103
	v_cvt_pk_bf16_f32 v101, v104, v105
	s_waitcnt lgkmcnt(0)
	v_mov_b32_e32 v2, v238
	v_mfma_f32_32x32x16_bf16 v[34:49], v[82:85], v[114:117], v[34:49]
	v_exp_f32_e32 v106, v106
	v_exp_f32_e32 v107, v107
	v_exp_f32_e32 v108, v108
	v_add_f32_e32 v27, v27, v106
	v_exp_f32_e32 v109, v109
	ds_read_b128 v[218:221], v2
	ds_read_b128 v[214:217], v2 offset:512
	ds_read_b128 v[210:213], v2 offset:2048
	v_mfma_f32_32x32x16_bf16 v[50:65], v[82:85], v[240:243], v[50:65]
	v_add_f32_e32 v27, v27, v107
	v_exp_f32_e32 v110, v110
	v_add_f32_e32 v27, v27, v108
	v_exp_f32_e32 v111, v111
	v_add_f32_e32 v27, v27, v109
	ds_read_b128 v[206:209], v2 offset:2560
	ds_read_b128 v[202:205], v2 offset:4096
	ds_read_b128 v[198:201], v2 offset:4608
	v_mfma_f32_32x32x16_bf16 v[34:49], v[90:93], v[118:121], v[34:49]
	v_exp_f32_e32 v112, v112
	v_add_f32_e32 v27, v27, v110
	v_exp_f32_e32 v113, v113
	v_add_f32_e32 v27, v27, v111
	v_add_f32_e32 v27, v27, v112
	ds_read_b128 v[194:197], v2 offset:6144
	ds_read_b128 v[190:193], v2 offset:6656
	ds_read_b128 v[186:189], v2 offset:8192
	v_mfma_f32_32x32x16_bf16 v[50:65], v[90:93], v[244:247], v[50:65]
	v_add_f32_e32 v27, v27, v113
	v_cvt_pk_bf16_f32 v106, v106, v107
	v_cvt_pk_bf16_f32 v107, v108, v109
	v_cvt_pk_bf16_f32 v108, v110, v111
	v_cvt_pk_bf16_f32 v109, v112, v113
	v_add_f32_e32 v236, v236, v27
	ds_read_b128 v[182:185], v2 offset:8704
	ds_read_b128 v[178:181], v2 offset:10240
	ds_read_b128 v[174:177], v2 offset:10752
	v_mfma_f32_32x32x16_bf16 v[34:49], v[98:101], v[122:125], v[34:49]
	v_max3_f32 v19, v142, v143, v144
	v_max3_f32 v26, v145, v146, v147
	v_max3_f32 v19, v19, v148, v149
	v_max3_f32 v26, v26, v150, v151
	v_mfma_f32_32x32x16_bf16 v[50:65], v[98:101], v[248:251], v[50:65]
	v_max3_f32 v19, v19, v152, v153
	v_max3_f32 v26, v26, v154, v155
	v_max3_f32 v19, v19, v156, v157
	v_max3_f32 v26, v26, v158, v159
	v_mfma_f32_32x32x16_bf16 v[34:49], v[106:109], v[126:129], v[34:49]
	v_max3_f32 v19, v19, v160, v161
	v_max3_f32 v26, v26, v162, v163
	v_max3_f32 v19, v19, v164, v165
	v_max3_f32 v26, v26, v166, v167
	v_mfma_f32_32x32x16_bf16 v[50:65], v[106:109], v[20:23], v[50:65]
	v_max3_f32 v19, v19, v168, v169
	v_max3_f32 v26, v26, v170, v171
	v_max3_f32 v19, v19, v172, v173
	v_max_f32_e32 v19, v19, v26
	v_cmp_lt_f32_e32 vcc, s41, v19
	s_cbranch_vccz .Lmy_nors_9
	s_nop 15
	s_nop 15
	v_mov_b32_e32 v26, v19
	s_nop 1
	v_permlane32_swap_b32_e32 v19, v26
	v_max_f32_e32 v19, v19, v26
	v_max_f32_e32 v19, v19, v19
	v_max_f32_e32 v90, 0, v19
	v_exp_f32_e64 v91, -v90
	v_add_f32_e32 v239, v239, v90
	v_xor_b32_e32 v66, 0x80000000, v239
	v_mov_b32_e32 v67, v66
	v_mov_b32_e32 v68, v66
	v_mov_b32_e32 v69, v66
	v_mov_b32_e32 v70, v66
	v_mov_b32_e32 v71, v66
	v_mov_b32_e32 v72, v66
	v_mov_b32_e32 v73, v66
	v_mov_b32_e32 v74, v66
	v_mov_b32_e32 v75, v66
	v_mov_b32_e32 v76, v66
	v_mov_b32_e32 v77, v66
	v_mov_b32_e32 v78, v66
	v_mov_b32_e32 v79, v66
	v_mov_b32_e32 v80, v66
	v_mov_b32_e32 v81, v66
	v_sub_f32_e32 v142, v142, v90
	v_sub_f32_e32 v143, v143, v90
	v_sub_f32_e32 v144, v144, v90
	v_sub_f32_e32 v145, v145, v90
	v_sub_f32_e32 v146, v146, v90
	v_sub_f32_e32 v147, v147, v90
	v_sub_f32_e32 v148, v148, v90
	v_sub_f32_e32 v149, v149, v90
	v_sub_f32_e32 v150, v150, v90
	v_sub_f32_e32 v151, v151, v90
	v_sub_f32_e32 v152, v152, v90
	v_sub_f32_e32 v153, v153, v90
	v_sub_f32_e32 v154, v154, v90
	v_sub_f32_e32 v155, v155, v90
	v_sub_f32_e32 v156, v156, v90
	v_sub_f32_e32 v157, v157, v90
	v_sub_f32_e32 v158, v158, v90
	v_sub_f32_e32 v159, v159, v90
	v_sub_f32_e32 v160, v160, v90
	v_sub_f32_e32 v161, v161, v90
	v_sub_f32_e32 v162, v162, v90
	v_sub_f32_e32 v163, v163, v90
	v_sub_f32_e32 v164, v164, v90
	v_sub_f32_e32 v165, v165, v90
	v_sub_f32_e32 v166, v166, v90
	v_sub_f32_e32 v167, v167, v90
	v_sub_f32_e32 v168, v168, v90
	v_sub_f32_e32 v169, v169, v90
	v_sub_f32_e32 v170, v170, v90
	v_sub_f32_e32 v171, v171, v90
	v_sub_f32_e32 v172, v172, v90
	v_sub_f32_e32 v173, v173, v90
	v_mul_f32_e32 v236, v236, v91
	s_mov_b64 s[96:97], exec
	s_and_b64 exec, exec, s[8:9]
	ds_write_b32 v235, v91
	s_mov_b64 exec, s[96:97]
	v_lshl_add_u32 v2, v228, 4, s47
	ds_read_b128 v[94:97], v2 offset:0
	s_waitcnt lgkmcnt(0)
	v_mul_f32_e32 v34, v34, v94
	v_mul_f32_e32 v50, v50, v94
	v_mul_f32_e32 v35, v35, v95
	v_mul_f32_e32 v51, v51, v95
	v_mul_f32_e32 v36, v36, v96
	v_mul_f32_e32 v52, v52, v96
	v_mul_f32_e32 v37, v37, v97
	v_mul_f32_e32 v53, v53, v97
	ds_read_b128 v[94:97], v2 offset:32
	s_waitcnt lgkmcnt(0)
	v_mul_f32_e32 v38, v38, v94
	v_mul_f32_e32 v54, v54, v94
	v_mul_f32_e32 v39, v39, v95
	v_mul_f32_e32 v55, v55, v95
	v_mul_f32_e32 v40, v40, v96
	v_mul_f32_e32 v56, v56, v96
	v_mul_f32_e32 v41, v41, v97
	v_mul_f32_e32 v57, v57, v97
	ds_read_b128 v[94:97], v2 offset:64
	s_waitcnt lgkmcnt(0)
	v_mul_f32_e32 v42, v42, v94
	v_mul_f32_e32 v58, v58, v94
	v_mul_f32_e32 v43, v43, v95
	v_mul_f32_e32 v59, v59, v95
	v_mul_f32_e32 v44, v44, v96
	v_mul_f32_e32 v60, v60, v96
	v_mul_f32_e32 v45, v45, v97
	v_mul_f32_e32 v61, v61, v97
	ds_read_b128 v[94:97], v2 offset:96
	s_waitcnt lgkmcnt(0)
	v_mul_f32_e32 v46, v46, v94
	v_mul_f32_e32 v62, v62, v94
	v_mul_f32_e32 v47, v47, v95
	v_mul_f32_e32 v63, v63, v95
	v_mul_f32_e32 v48, v48, v96
	v_mul_f32_e32 v64, v64, v96
	v_mul_f32_e32 v49, v49, v97
	v_mul_f32_e32 v65, v65, v97

.Lmy_tf_13:
	s_waitcnt lgkmcnt(0)
	v_mov_b32_e32 v2, v237
	v_mfma_f32_32x32x16_bf16 v[142:157], v[218:221], v[4:7], v[66:81]
	v_exp_f32_e32 v82, v82
	v_exp_f32_e32 v83, v83
	v_exp_f32_e32 v84, v84
	v_add_f32_e32 v27, v82, v83
	v_exp_f32_e32 v85, v85
	ds_read_b64_tr_b16 v[114:115], v2 offset:49152
	ds_read_b64_tr_b16 v[116:117], v2 offset:49664
	ds_read_b64_tr_b16 v[118:119], v2 offset:50176
	ds_read_b64_tr_b16 v[120:121], v2 offset:50688
	v_mfma_f32_32x32x16_bf16 v[158:173], v[214:217], v[4:7], v[66:81]
	v_exp_f32_e32 v86, v86
	v_add_f32_e32 v27, v27, v84
	v_exp_f32_e32 v87, v87
	v_add_f32_e32 v27, v27, v85
	v_exp_f32_e32 v88, v88
	ds_read_b64_tr_b16 v[122:123], v2 offset:51200
	ds_read_b64_tr_b16 v[124:125], v2 offset:51712
	ds_read_b64_tr_b16 v[126:127], v2 offset:52224
	ds_read_b64_tr_b16 v[128:129], v2 offset:52736
	v_mfma_f32_32x32x16_bf16 v[142:157], v[210:213], v[8:11], v[142:157]
	v_add_f32_e32 v27, v27, v86
	v_exp_f32_e32 v89, v89
	v_add_f32_e32 v27, v27, v87
	v_add_f32_e32 v27, v27, v88
	v_add_f32_e32 v27, v27, v89
	ds_read_b64_tr_b16 v[240:241], v2 offset:53248
	ds_read_b64_tr_b16 v[242:243], v2 offset:53760
	ds_read_b64_tr_b16 v[244:245], v2 offset:54272
	ds_read_b64_tr_b16 v[246:247], v2 offset:54784
	v_mfma_f32_32x32x16_bf16 v[158:173], v[206:209], v[8:11], v[158:173]
	v_cvt_pk_bf16_f32 v82, v82, v83
	v_cvt_pk_bf16_f32 v83, v84, v85
	v_cvt_pk_bf16_f32 v84, v86, v87
	v_cvt_pk_bf16_f32 v85, v88, v89
	ds_read_b64_tr_b16 v[248:249], v2 offset:55296
	ds_read_b64_tr_b16 v[250:251], v2 offset:55808
	ds_read_b64_tr_b16 v[20:21], v2 offset:56320
	ds_read_b64_tr_b16 v[22:23], v2 offset:56832
	v_mfma_f32_32x32x16_bf16 v[142:157], v[202:205], v[12:15], v[142:157]
	v_exp_f32_e32 v90, v90
	v_exp_f32_e32 v91, v91
	v_exp_f32_e32 v92, v92
	v_add_f32_e32 v27, v27, v90
	v_exp_f32_e32 v93, v93
	v_mfma_f32_32x32x16_bf16 v[158:173], v[198:201], v[12:15], v[158:173]
	v_add_f32_e32 v27, v27, v91
	v_exp_f32_e32 v94, v94
	v_add_f32_e32 v27, v27, v92
	v_exp_f32_e32 v95, v95
	v_add_f32_e32 v27, v27, v93
	s_waitcnt vmcnt(3)
	s_barrier
	v_mfma_f32_32x32x16_bf16 v[142:157], v[194:197], v[130:133], v[142:157]
	s_add_u32 m0, s57, 0x6000
	v_exp_f32_e32 v96, v96
	v_add_f32_e32 v27, v27, v94
	global_load_lds_dwordx4 v[28:29], off
	v_lshl_add_u64 v[28:29], v[28:29], 0, s[30:31]
	v_exp_f32_e32 v97, v97
	v_add_f32_e32 v27, v27, v95
	v_add_f32_e32 v27, v27, v96
	v_mfma_f32_32x32x16_bf16 v[158:173], v[190:193], v[130:133], v[158:173]
	v_add_f32_e32 v27, v27, v97
	v_cvt_pk_bf16_f32 v90, v90, v91
	v_cvt_pk_bf16_f32 v91, v92, v93
	v_cvt_pk_bf16_f32 v92, v94, v95
	v_cvt_pk_bf16_f32 v93, v96, v97
	v_mfma_f32_32x32x16_bf16 v[142:157], v[186:189], v[134:137], v[142:157]
	v_exp_f32_e32 v98, v98
	v_exp_f32_e32 v99, v99
	v_exp_f32_e32 v100, v100
	v_add_f32_e32 v27, v27, v98
	v_exp_f32_e32 v101, v101
	v_mfma_f32_32x32x16_bf16 v[158:173], v[182:185], v[134:137], v[158:173]
	v_add_f32_e32 v27, v27, v99
	v_exp_f32_e32 v102, v102
	v_add_f32_e32 v27, v27, v100
	v_exp_f32_e32 v103, v103
	v_add_f32_e32 v27, v27, v101
	v_mfma_f32_32x32x16_bf16 v[142:157], v[178:181], v[138:141], v[142:157]
	v_exp_f32_e32 v104, v104
	v_add_f32_e32 v27, v27, v102
	v_exp_f32_e32 v105, v105
	v_add_f32_e32 v27, v27, v103
	v_add_f32_e32 v27, v27, v104
	v_mfma_f32_32x32x16_bf16 v[158:173], v[174:177], v[138:141], v[158:173]
	v_add_f32_e32 v27, v27, v105
	v_cvt_pk_bf16_f32 v98, v98, v99
	v_cvt_pk_bf16_f32 v99, v100, v101
	v_cvt_pk_bf16_f32 v100, v102, v103
	v_cvt_pk_bf16_f32 v101, v104, v105
	s_waitcnt lgkmcnt(0)
	v_add_u32_e32 v2, 0x6000, v238
	v_mfma_f32_32x32x16_bf16 v[34:49], v[82:85], v[114:117], v[34:49]
	v_exp_f32_e32 v106, v106
	v_exp_f32_e32 v107, v107
	v_exp_f32_e32 v108, v108
	v_add_f32_e32 v27, v27, v106
	v_exp_f32_e32 v109, v109
	s_cmp_gt_u32 s71, 1
	s_cbranch_scc0 .Lmy_nok_16
	ds_read_b128 v[218:221], v2
	ds_read_b128 v[214:217], v2 offset:512
	ds_read_b128 v[210:213], v2 offset:2048
	ds_read_b128 v[206:209], v2 offset:2560
	ds_read_b128 v[202:205], v2 offset:4096
	ds_read_b128 v[198:201], v2 offset:4608
	ds_read_b128 v[194:197], v2 offset:6144
	ds_read_b128 v[190:193], v2 offset:6656
	ds_read_b128 v[186:189], v2 offset:8192
	ds_read_b128 v[182:185], v2 offset:8704
	ds_read_b128 v[178:181], v2 offset:10240
	ds_read_b128 v[174:177], v2 offset:10752
.Lmy_nok_16:
	v_mfma_f32_32x32x16_bf16 v[50:65], v[82:85], v[240:243], v[50:65]
	v_add_f32_e32 v27, v27, v107
	v_exp_f32_e32 v110, v110
	v_add_f32_e32 v27, v27, v108
	v_exp_f32_e32 v111, v111
	v_add_f32_e32 v27, v27, v109
	v_mfma_f32_32x32x16_bf16 v[34:49], v[90:93], v[118:121], v[34:49]
	v_exp_f32_e32 v112, v112
	v_add_f32_e32 v27, v27, v110
	v_exp_f32_e32 v113, v113
	v_add_f32_e32 v27, v27, v111
	v_add_f32_e32 v27, v27, v112
	v_mfma_f32_32x32x16_bf16 v[50:65], v[90:93], v[244:247], v[50:65]
	v_add_f32_e32 v27, v27, v113
	v_cvt_pk_bf16_f32 v106, v106, v107
	v_cvt_pk_bf16_f32 v107, v108, v109
	v_cvt_pk_bf16_f32 v108, v110, v111
	v_cvt_pk_bf16_f32 v109, v112, v113
	v_add_f32_e32 v236, v236, v27
	v_mfma_f32_32x32x16_bf16 v[34:49], v[98:101], v[122:125], v[34:49]
	v_max3_f32 v19, v142, v143, v144
	v_max3_f32 v26, v145, v146, v147
	v_max3_f32 v19, v19, v148, v149
	v_max3_f32 v26, v26, v150, v151
	v_mfma_f32_32x32x16_bf16 v[50:65], v[98:101], v[248:251], v[50:65]
	v_max3_f32 v19, v19, v152, v153
	v_max3_f32 v26, v26, v154, v155
	v_max3_f32 v19, v19, v156, v157
	v_max3_f32 v26, v26, v158, v159
	v_mfma_f32_32x32x16_bf16 v[34:49], v[106:109], v[126:129], v[34:49]
	v_max3_f32 v19, v19, v160, v161
	v_max3_f32 v26, v26, v162, v163
	v_max3_f32 v19, v19, v164, v165
	v_max3_f32 v26, v26, v166, v167
	v_mfma_f32_32x32x16_bf16 v[50:65], v[106:109], v[20:23], v[50:65]
	v_max3_f32 v19, v19, v168, v169
	v_max3_f32 v26, v26, v170, v171
	v_max3_f32 v19, v19, v172, v173
	v_max_f32_e32 v19, v19, v26
	v_cmp_lt_f32_e32 vcc, s41, v19
	s_cbranch_vccz .Lmy_nors_17
	s_nop 15
	s_nop 15
	v_mov_b32_e32 v26, v19
	s_nop 1
	v_permlane32_swap_b32_e32 v19, v26
	v_max_f32_e32 v19, v19, v26
	v_max_f32_e32 v19, v19, v19
	v_max_f32_e32 v90, 0, v19
	v_exp_f32_e64 v91, -v90
	v_add_f32_e32 v239, v239, v90
	v_xor_b32_e32 v66, 0x80000000, v239
	v_mov_b32_e32 v67, v66
	v_mov_b32_e32 v68, v66
	v_mov_b32_e32 v69, v66
	v_mov_b32_e32 v70, v66
	v_mov_b32_e32 v71, v66
	v_mov_b32_e32 v72, v66
	v_mov_b32_e32 v73, v66
	v_mov_b32_e32 v74, v66
	v_mov_b32_e32 v75, v66
	v_mov_b32_e32 v76, v66
	v_mov_b32_e32 v77, v66
	v_mov_b32_e32 v78, v66
	v_mov_b32_e32 v79, v66
	v_mov_b32_e32 v80, v66
	v_mov_b32_e32 v81, v66
	v_sub_f32_e32 v142, v142, v90
	v_sub_f32_e32 v143, v143, v90
	v_sub_f32_e32 v144, v144, v90
	v_sub_f32_e32 v145, v145, v90
	v_sub_f32_e32 v146, v146, v90
	v_sub_f32_e32 v147, v147, v90
	v_sub_f32_e32 v148, v148, v90
	v_sub_f32_e32 v149, v149, v90
	v_sub_f32_e32 v150, v150, v90
	v_sub_f32_e32 v151, v151, v90
	v_sub_f32_e32 v152, v152, v90
	v_sub_f32_e32 v153, v153, v90
	v_sub_f32_e32 v154, v154, v90
	v_sub_f32_e32 v155, v155, v90
	v_sub_f32_e32 v156, v156, v90
	v_sub_f32_e32 v157, v157, v90
	v_sub_f32_e32 v158, v158, v90
	v_sub_f32_e32 v159, v159, v90
	v_sub_f32_e32 v160, v160, v90
	v_sub_f32_e32 v161, v161, v90
	v_sub_f32_e32 v162, v162, v90
	v_sub_f32_e32 v163, v163, v90
	v_sub_f32_e32 v164, v164, v90
	v_sub_f32_e32 v165, v165, v90
	v_sub_f32_e32 v166, v166, v90
	v_sub_f32_e32 v167, v167, v90
	v_sub_f32_e32 v168, v168, v90
	v_sub_f32_e32 v169, v169, v90
	v_sub_f32_e32 v170, v170, v90
	v_sub_f32_e32 v171, v171, v90
	v_sub_f32_e32 v172, v172, v90
	v_sub_f32_e32 v173, v173, v90
	v_mul_f32_e32 v236, v236, v91
	s_mov_b64 s[96:97], exec
	s_and_b64 exec, exec, s[8:9]
	ds_write_b32 v235, v91
	s_mov_b64 exec, s[96:97]
	v_lshl_add_u32 v2, v228, 4, s47
	ds_read_b128 v[94:97], v2 offset:0
	s_waitcnt lgkmcnt(0)
	v_mul_f32_e32 v34, v34, v94
	v_mul_f32_e32 v50, v50, v94
	v_mul_f32_e32 v35, v35, v95
	v_mul_f32_e32 v51, v51, v95
	v_mul_f32_e32 v36, v36, v96
	v_mul_f32_e32 v52, v52, v96
	v_mul_f32_e32 v37, v37, v97
	v_mul_f32_e32 v53, v53, v97
	ds_read_b128 v[94:97], v2 offset:32
	s_waitcnt lgkmcnt(0)
	v_mul_f32_e32 v38, v38, v94
	v_mul_f32_e32 v54, v54, v94
	v_mul_f32_e32 v39, v39, v95
	v_mul_f32_e32 v55, v55, v95
	v_mul_f32_e32 v40, v40, v96
	v_mul_f32_e32 v56, v56, v96
	v_mul_f32_e32 v41, v41, v97
	v_mul_f32_e32 v57, v57, v97
	ds_read_b128 v[94:97], v2 offset:64
	s_waitcnt lgkmcnt(0)
	v_mul_f32_e32 v42, v42, v94
	v_mul_f32_e32 v58, v58, v94
	v_mul_f32_e32 v43, v43, v95
	v_mul_f32_e32 v59, v59, v95
	v_mul_f32_e32 v44, v44, v96
	v_mul_f32_e32 v60, v60, v96
	v_mul_f32_e32 v45, v45, v97
	v_mul_f32_e32 v61, v61, v97
	ds_read_b128 v[94:97], v2 offset:96
	s_waitcnt lgkmcnt(0)
	v_mul_f32_e32 v46, v46, v94
	v_mul_f32_e32 v62, v62, v94
	v_mul_f32_e32 v47, v47, v95
	v_mul_f32_e32 v63, v63, v95
	v_mul_f32_e32 v48, v48, v96
	v_mul_f32_e32 v64, v64, v96
	v_mul_f32_e32 v49, v49, v97
	v_mul_f32_e32 v65, v65, v97

.Lmy_tf_18:
	s_waitcnt lgkmcnt(0)
	v_add_u32_e32 v2, 0x2000, v237
	v_mfma_f32_32x32x16_bf16 v[82:97], v[218:221], v[4:7], v[66:81]
	v_exp_f32_e32 v142, v142
	v_exp_f32_e32 v143, v143
	v_exp_f32_e32 v144, v144
	v_add_f32_e32 v27, v142, v143
	v_exp_f32_e32 v145, v145
	ds_read_b64_tr_b16 v[114:115], v2 offset:49152
	ds_read_b64_tr_b16 v[116:117], v2 offset:49664
	ds_read_b64_tr_b16 v[118:119], v2 offset:50176
	ds_read_b64_tr_b16 v[120:121], v2 offset:50688
	v_mfma_f32_32x32x16_bf16 v[98:113], v[214:217], v[4:7], v[66:81]
	v_exp_f32_e32 v146, v146
	v_add_f32_e32 v27, v27, v144
	v_exp_f32_e32 v147, v147
	v_add_f32_e32 v27, v27, v145
	v_exp_f32_e32 v148, v148
	ds_read_b64_tr_b16 v[122:123], v2 offset:51200
	ds_read_b64_tr_b16 v[124:125], v2 offset:51712
	ds_read_b64_tr_b16 v[126:127], v2 offset:52224
	ds_read_b64_tr_b16 v[128:129], v2 offset:52736
	v_mfma_f32_32x32x16_bf16 v[82:97], v[210:213], v[8:11], v[82:97]
	v_add_f32_e32 v27, v27, v146
	v_exp_f32_e32 v149, v149
	v_add_f32_e32 v27, v27, v147
	v_add_f32_e32 v27, v27, v148
	v_add_f32_e32 v27, v27, v149
	ds_read_b64_tr_b16 v[240:241], v2 offset:53248
	ds_read_b64_tr_b16 v[242:243], v2 offset:53760
	ds_read_b64_tr_b16 v[244:245], v2 offset:54272
	ds_read_b64_tr_b16 v[246:247], v2 offset:54784
	v_mfma_f32_32x32x16_bf16 v[98:113], v[206:209], v[8:11], v[98:113]
	v_cvt_pk_bf16_f32 v142, v142, v143
	v_cvt_pk_bf16_f32 v143, v144, v145
	v_cvt_pk_bf16_f32 v144, v146, v147
	v_cvt_pk_bf16_f32 v145, v148, v149
	ds_read_b64_tr_b16 v[248:249], v2 offset:55296
	ds_read_b64_tr_b16 v[250:251], v2 offset:55808
	ds_read_b64_tr_b16 v[20:21], v2 offset:56320
	ds_read_b64_tr_b16 v[22:23], v2 offset:56832
	v_mfma_f32_32x32x16_bf16 v[82:97], v[202:205], v[12:15], v[82:97]
	v_exp_f32_e32 v150, v150
	v_exp_f32_e32 v151, v151
	v_exp_f32_e32 v152, v152
	v_add_f32_e32 v27, v27, v150
	v_exp_f32_e32 v153, v153
	v_mfma_f32_32x32x16_bf16 v[98:113], v[198:201], v[12:15], v[98:113]
	v_add_f32_e32 v27, v27, v151
	v_exp_f32_e32 v154, v154
	v_add_f32_e32 v27, v27, v152
	v_exp_f32_e32 v155, v155
	v_add_f32_e32 v27, v27, v153
	s_waitcnt vmcnt(1)
	s_barrier
	v_mfma_f32_32x32x16_bf16 v[82:97], v[194:197], v[130:133], v[82:97]
	v_exp_f32_e32 v156, v156
	v_add_f32_e32 v27, v27, v154
	v_exp_f32_e32 v157, v157
	v_add_f32_e32 v27, v27, v155
	v_add_f32_e32 v27, v27, v156
	v_mfma_f32_32x32x16_bf16 v[98:113], v[190:193], v[130:133], v[98:113]
	v_add_f32_e32 v27, v27, v157
	v_cvt_pk_bf16_f32 v150, v150, v151
	v_cvt_pk_bf16_f32 v151, v152, v153
	v_cvt_pk_bf16_f32 v152, v154, v155
	v_cvt_pk_bf16_f32 v153, v156, v157
	v_mfma_f32_32x32x16_bf16 v[82:97], v[186:189], v[134:137], v[82:97]
	v_exp_f32_e32 v158, v158
	v_exp_f32_e32 v159, v159
	v_exp_f32_e32 v160, v160
	v_add_f32_e32 v27, v27, v158
	v_exp_f32_e32 v161, v161
	v_mfma_f32_32x32x16_bf16 v[98:113], v[182:185], v[134:137], v[98:113]
	v_add_f32_e32 v27, v27, v159
	v_exp_f32_e32 v162, v162
	v_add_f32_e32 v27, v27, v160
	v_exp_f32_e32 v163, v163
	v_add_f32_e32 v27, v27, v161
	v_mfma_f32_32x32x16_bf16 v[82:97], v[178:181], v[138:141], v[82:97]
	v_exp_f32_e32 v164, v164
	v_add_f32_e32 v27, v27, v162
	v_exp_f32_e32 v165, v165
	v_add_f32_e32 v27, v27, v163
	v_add_f32_e32 v27, v27, v164
	v_mfma_f32_32x32x16_bf16 v[98:113], v[174:177], v[138:141], v[98:113]
	v_add_f32_e32 v27, v27, v165
	v_cvt_pk_bf16_f32 v158, v158, v159
	v_cvt_pk_bf16_f32 v159, v160, v161
	v_cvt_pk_bf16_f32 v160, v162, v163
	v_cvt_pk_bf16_f32 v161, v164, v165
	s_waitcnt lgkmcnt(0)
	v_add_u32_e32 v2, 0x9000, v238
	v_mfma_f32_32x32x16_bf16 v[34:49], v[142:145], v[114:117], v[34:49]
	v_exp_f32_e32 v166, v166
	v_exp_f32_e32 v167, v167
	v_exp_f32_e32 v168, v168
	v_add_f32_e32 v27, v27, v166
	v_exp_f32_e32 v169, v169
	s_cmp_gt_u32 s71, 2
	s_cbranch_scc0 .Lmy_nok_21
	ds_read_b128 v[218:221], v2
	ds_read_b128 v[214:217], v2 offset:512
	ds_read_b128 v[210:213], v2 offset:2048
	ds_read_b128 v[206:209], v2 offset:2560
	ds_read_b128 v[202:205], v2 offset:4096
	ds_read_b128 v[198:201], v2 offset:4608
	ds_read_b128 v[194:197], v2 offset:6144
	ds_read_b128 v[190:193], v2 offset:6656
	ds_read_b128 v[186:189], v2 offset:8192
	ds_read_b128 v[182:185], v2 offset:8704
	ds_read_b128 v[178:181], v2 offset:10240
	ds_read_b128 v[174:177], v2 offset:10752
.Lmy_nok_21:
	v_mfma_f32_32x32x16_bf16 v[50:65], v[142:145], v[240:243], v[50:65]
	v_add_f32_e32 v27, v27, v167
	v_exp_f32_e32 v170, v170
	v_add_f32_e32 v27, v27, v168
	v_exp_f32_e32 v171, v171
	v_add_f32_e32 v27, v27, v169
	v_mfma_f32_32x32x16_bf16 v[34:49], v[150:153], v[118:121], v[34:49]
	v_exp_f32_e32 v172, v172
	v_add_f32_e32 v27, v27, v170
	v_exp_f32_e32 v173, v173
	v_add_f32_e32 v27, v27, v171
	v_add_f32_e32 v27, v27, v172
	v_mfma_f32_32x32x16_bf16 v[50:65], v[150:153], v[244:247], v[50:65]
	v_add_f32_e32 v27, v27, v173
	v_cvt_pk_bf16_f32 v166, v166, v167
	v_cvt_pk_bf16_f32 v167, v168, v169
	v_cvt_pk_bf16_f32 v168, v170, v171
	v_cvt_pk_bf16_f32 v169, v172, v173
	v_add_f32_e32 v236, v236, v27
	v_mfma_f32_32x32x16_bf16 v[34:49], v[158:161], v[122:125], v[34:49]
	v_max3_f32 v19, v82, v83, v84
	v_max3_f32 v26, v85, v86, v87
	v_max3_f32 v19, v19, v88, v89
	v_max3_f32 v26, v26, v90, v91
	v_mfma_f32_32x32x16_bf16 v[50:65], v[158:161], v[248:251], v[50:65]
	v_max3_f32 v19, v19, v92, v93
	v_max3_f32 v26, v26, v94, v95
	v_max3_f32 v19, v19, v96, v97
	v_max3_f32 v26, v26, v98, v99
	v_mfma_f32_32x32x16_bf16 v[34:49], v[166:169], v[126:129], v[34:49]
	v_max3_f32 v19, v19, v100, v101
	v_max3_f32 v26, v26, v102, v103
	v_max3_f32 v19, v19, v104, v105
	v_max3_f32 v26, v26, v106, v107
	v_mfma_f32_32x32x16_bf16 v[50:65], v[166:169], v[20:23], v[50:65]
	v_max3_f32 v19, v19, v108, v109
	v_max3_f32 v26, v26, v110, v111
	v_max3_f32 v19, v19, v112, v113
	v_max_f32_e32 v19, v19, v26
	v_cmp_lt_f32_e32 vcc, s41, v19
	s_cbranch_vccz .Lmy_nors_22
	s_nop 15
	s_nop 15
	v_mov_b32_e32 v26, v19
	s_nop 1
	v_permlane32_swap_b32_e32 v19, v26
	v_max_f32_e32 v19, v19, v26
	v_max_f32_e32 v19, v19, v19
	v_max_f32_e32 v150, 0, v19
	v_exp_f32_e64 v151, -v150
	v_add_f32_e32 v239, v239, v150
	v_xor_b32_e32 v66, 0x80000000, v239
	v_mov_b32_e32 v67, v66
	v_mov_b32_e32 v68, v66
	v_mov_b32_e32 v69, v66
	v_mov_b32_e32 v70, v66
	v_mov_b32_e32 v71, v66
	v_mov_b32_e32 v72, v66
	v_mov_b32_e32 v73, v66
	v_mov_b32_e32 v74, v66
	v_mov_b32_e32 v75, v66
	v_mov_b32_e32 v76, v66
	v_mov_b32_e32 v77, v66
	v_mov_b32_e32 v78, v66
	v_mov_b32_e32 v79, v66
	v_mov_b32_e32 v80, v66
	v_mov_b32_e32 v81, v66
	v_sub_f32_e32 v82, v82, v150
	v_sub_f32_e32 v83, v83, v150
	v_sub_f32_e32 v84, v84, v150
	v_sub_f32_e32 v85, v85, v150
	v_sub_f32_e32 v86, v86, v150
	v_sub_f32_e32 v87, v87, v150
	v_sub_f32_e32 v88, v88, v150
	v_sub_f32_e32 v89, v89, v150
	v_sub_f32_e32 v90, v90, v150
	v_sub_f32_e32 v91, v91, v150
	v_sub_f32_e32 v92, v92, v150
	v_sub_f32_e32 v93, v93, v150
	v_sub_f32_e32 v94, v94, v150
	v_sub_f32_e32 v95, v95, v150
	v_sub_f32_e32 v96, v96, v150
	v_sub_f32_e32 v97, v97, v150
	v_sub_f32_e32 v98, v98, v150
	v_sub_f32_e32 v99, v99, v150
	v_sub_f32_e32 v100, v100, v150
	v_sub_f32_e32 v101, v101, v150
	v_sub_f32_e32 v102, v102, v150
	v_sub_f32_e32 v103, v103, v150
	v_sub_f32_e32 v104, v104, v150
	v_sub_f32_e32 v105, v105, v150
	v_sub_f32_e32 v106, v106, v150
	v_sub_f32_e32 v107, v107, v150
	v_sub_f32_e32 v108, v108, v150
	v_sub_f32_e32 v109, v109, v150
	v_sub_f32_e32 v110, v110, v150
	v_sub_f32_e32 v111, v111, v150
	v_sub_f32_e32 v112, v112, v150
	v_sub_f32_e32 v113, v113, v150
	v_mul_f32_e32 v236, v236, v151
	s_mov_b64 s[96:97], exec
	s_and_b64 exec, exec, s[8:9]
	ds_write_b32 v235, v151
	s_mov_b64 exec, s[96:97]
	v_lshl_add_u32 v2, v228, 4, s47
	ds_read_b128 v[154:157], v2 offset:0
	s_waitcnt lgkmcnt(0)
	v_mul_f32_e32 v34, v34, v154
	v_mul_f32_e32 v50, v50, v154
	v_mul_f32_e32 v35, v35, v155
	v_mul_f32_e32 v51, v51, v155
	v_mul_f32_e32 v36, v36, v156
	v_mul_f32_e32 v52, v52, v156
	v_mul_f32_e32 v37, v37, v157
	v_mul_f32_e32 v53, v53, v157
	ds_read_b128 v[154:157], v2 offset:32
	s_waitcnt lgkmcnt(0)
	v_mul_f32_e32 v38, v38, v154
	v_mul_f32_e32 v54, v54, v154
	v_mul_f32_e32 v39, v39, v155
	v_mul_f32_e32 v55, v55, v155
	v_mul_f32_e32 v40, v40, v156
	v_mul_f32_e32 v56, v56, v156
	v_mul_f32_e32 v41, v41, v157
	v_mul_f32_e32 v57, v57, v157
	ds_read_b128 v[154:157], v2 offset:64
	s_waitcnt lgkmcnt(0)
	v_mul_f32_e32 v42, v42, v154
	v_mul_f32_e32 v58, v58, v154
	v_mul_f32_e32 v43, v43, v155
	v_mul_f32_e32 v59, v59, v155
	v_mul_f32_e32 v44, v44, v156
	v_mul_f32_e32 v60, v60, v156
	v_mul_f32_e32 v45, v45, v157
	v_mul_f32_e32 v61, v61, v157
	ds_read_b128 v[154:157], v2 offset:96
	s_waitcnt lgkmcnt(0)
	v_mul_f32_e32 v46, v46, v154
	v_mul_f32_e32 v62, v62, v154
	v_mul_f32_e32 v47, v47, v155
	v_mul_f32_e32 v63, v63, v155
	v_mul_f32_e32 v48, v48, v156
	v_mul_f32_e32 v64, v64, v156
	v_mul_f32_e32 v49, v49, v157
	v_mul_f32_e32 v65, v65, v157

.Lmy_tf_23:
	s_waitcnt lgkmcnt(0)
	v_add_u32_e32 v2, 0x4000, v237
	v_mfma_f32_32x32x16_bf16 v[142:157], v[218:221], v[4:7], v[66:81]
	v_exp_f32_e32 v82, v82
	v_exp_f32_e32 v83, v83
	v_exp_f32_e32 v84, v84
	v_add_f32_e32 v27, v82, v83
	v_exp_f32_e32 v85, v85
	ds_read_b64_tr_b16 v[114:115], v2 offset:49152
	ds_read_b64_tr_b16 v[116:117], v2 offset:49664
	ds_read_b64_tr_b16 v[118:119], v2 offset:50176
	ds_read_b64_tr_b16 v[120:121], v2 offset:50688
	v_mfma_f32_32x32x16_bf16 v[158:173], v[214:217], v[4:7], v[66:81]
	v_exp_f32_e32 v86, v86
	v_add_f32_e32 v27, v27, v84
	v_exp_f32_e32 v87, v87
	v_add_f32_e32 v27, v27, v85
	v_exp_f32_e32 v88, v88
	ds_read_b64_tr_b16 v[122:123], v2 offset:51200
	ds_read_b64_tr_b16 v[124:125], v2 offset:51712
	ds_read_b64_tr_b16 v[126:127], v2 offset:52224
	ds_read_b64_tr_b16 v[128:129], v2 offset:52736
	v_mfma_f32_32x32x16_bf16 v[142:157], v[210:213], v[8:11], v[142:157]
	v_add_f32_e32 v27, v27, v86
	v_exp_f32_e32 v89, v89
	v_add_f32_e32 v27, v27, v87
	v_add_f32_e32 v27, v27, v88
	v_add_f32_e32 v27, v27, v89
	ds_read_b64_tr_b16 v[240:241], v2 offset:53248
	ds_read_b64_tr_b16 v[242:243], v2 offset:53760
	ds_read_b64_tr_b16 v[244:245], v2 offset:54272
	ds_read_b64_tr_b16 v[246:247], v2 offset:54784
	v_mfma_f32_32x32x16_bf16 v[158:173], v[206:209], v[8:11], v[158:173]
	v_cvt_pk_bf16_f32 v82, v82, v83
	v_cvt_pk_bf16_f32 v83, v84, v85
	v_cvt_pk_bf16_f32 v84, v86, v87
	v_cvt_pk_bf16_f32 v85, v88, v89
	ds_read_b64_tr_b16 v[248:249], v2 offset:55296
	ds_read_b64_tr_b16 v[250:251], v2 offset:55808
	ds_read_b64_tr_b16 v[20:21], v2 offset:56320
	ds_read_b64_tr_b16 v[22:23], v2 offset:56832
	v_mfma_f32_32x32x16_bf16 v[142:157], v[202:205], v[12:15], v[142:157]
	v_exp_f32_e32 v90, v90
	v_exp_f32_e32 v91, v91
	v_exp_f32_e32 v92, v92
	v_add_f32_e32 v27, v27, v90
	v_exp_f32_e32 v93, v93
	v_mfma_f32_32x32x16_bf16 v[158:173], v[198:201], v[12:15], v[158:173]
	v_add_f32_e32 v27, v27, v91
	v_exp_f32_e32 v94, v94
	v_add_f32_e32 v27, v27, v92
	v_exp_f32_e32 v95, v95
	v_add_f32_e32 v27, v27, v93
	s_waitcnt vmcnt(0)
	s_barrier
	v_mfma_f32_32x32x16_bf16 v[142:157], v[194:197], v[130:133], v[142:157]
	v_exp_f32_e32 v96, v96
	v_add_f32_e32 v27, v27, v94
	v_exp_f32_e32 v97, v97
	v_add_f32_e32 v27, v27, v95
	v_add_f32_e32 v27, v27, v96
	v_mfma_f32_32x32x16_bf16 v[158:173], v[190:193], v[130:133], v[158:173]
	v_add_f32_e32 v27, v27, v97
	v_cvt_pk_bf16_f32 v90, v90, v91
	v_cvt_pk_bf16_f32 v91, v92, v93
	v_cvt_pk_bf16_f32 v92, v94, v95
	v_cvt_pk_bf16_f32 v93, v96, v97
	v_mfma_f32_32x32x16_bf16 v[142:157], v[186:189], v[134:137], v[142:157]
	v_exp_f32_e32 v98, v98
	v_exp_f32_e32 v99, v99
	v_exp_f32_e32 v100, v100
	v_add_f32_e32 v27, v27, v98
	v_exp_f32_e32 v101, v101
	v_mfma_f32_32x32x16_bf16 v[158:173], v[182:185], v[134:137], v[158:173]
	v_add_f32_e32 v27, v27, v99
	v_exp_f32_e32 v102, v102
	v_add_f32_e32 v27, v27, v100
	v_exp_f32_e32 v103, v103
	v_add_f32_e32 v27, v27, v101
	v_mfma_f32_32x32x16_bf16 v[142:157], v[178:181], v[138:141], v[142:157]
	v_exp_f32_e32 v104, v104
	v_add_f32_e32 v27, v27, v102
	v_exp_f32_e32 v105, v105
	v_add_f32_e32 v27, v27, v103
	v_add_f32_e32 v27, v27, v104
	v_mfma_f32_32x32x16_bf16 v[158:173], v[174:177], v[138:141], v[158:173]
	v_add_f32_e32 v27, v27, v105
	v_cvt_pk_bf16_f32 v98, v98, v99
	v_cvt_pk_bf16_f32 v99, v100, v101
	v_cvt_pk_bf16_f32 v100, v102, v103
	v_cvt_pk_bf16_f32 v101, v104, v105
	s_waitcnt lgkmcnt(0)
	v_mov_b32_e32 v2, v238
	v_mfma_f32_32x32x16_bf16 v[34:49], v[82:85], v[114:117], v[34:49]
	v_exp_f32_e32 v106, v106
	v_exp_f32_e32 v107, v107
	v_exp_f32_e32 v108, v108
	v_add_f32_e32 v27, v27, v106
	v_exp_f32_e32 v109, v109
	s_cmp_gt_u32 s71, 3
	s_cbranch_scc0 .Lmy_nok_26
	ds_read_b128 v[218:221], v2
	ds_read_b128 v[214:217], v2 offset:512
	ds_read_b128 v[210:213], v2 offset:2048
	ds_read_b128 v[206:209], v2 offset:2560
	ds_read_b128 v[202:205], v2 offset:4096
	ds_read_b128 v[198:201], v2 offset:4608
	ds_read_b128 v[194:197], v2 offset:6144
	ds_read_b128 v[190:193], v2 offset:6656
	ds_read_b128 v[186:189], v2 offset:8192
	ds_read_b128 v[182:185], v2 offset:8704
	ds_read_b128 v[178:181], v2 offset:10240
	ds_read_b128 v[174:177], v2 offset:10752

.Lmy_B_entry:
	s_mov_b32 s30, 0x20000
	s_mov_b32 s31, 0
	s_mov_b32 s12, 0x1000
	s_mov_b32 s13, 0
	s_lshr_b32 s71, s24, 1
	s_lshr_b32 s79, s25, 2
	s_add_i32 s79, s79, -1
	s_mov_b32 s0, 0x80000
	s_mov_b32 s1, 0
	v_lshl_add_u64 v[24:25], v[16:17], 0, s[0:1]
	s_mov_b32 s0, 0x60000
	v_lshl_add_u64 v[28:29], v[224:225], 0, s[0:1]
	s_mov_b32 s0, 0x4000
	v_lshl_add_u64 v[30:31], v[222:223], 0, s[0:1]
	s_waitcnt lgkmcnt(0)
	v_mfma_f32_32x32x16_bf16 v[82:97], v[218:221], v[4:7], v[66:81]
	v_mfma_f32_32x32x16_bf16 v[98:113], v[214:217], v[4:7], v[66:81]
	v_mfma_f32_32x32x16_bf16 v[82:97], v[210:213], v[8:11], v[82:97]
	v_mfma_f32_32x32x16_bf16 v[98:113], v[206:209], v[8:11], v[98:113]
	v_mfma_f32_32x32x16_bf16 v[82:97], v[202:205], v[12:15], v[82:97]
	v_mfma_f32_32x32x16_bf16 v[98:113], v[198:201], v[12:15], v[98:113]
	v_mfma_f32_32x32x16_bf16 v[82:97], v[194:197], v[130:133], v[82:97]
	v_mfma_f32_32x32x16_bf16 v[98:113], v[190:193], v[130:133], v[98:113]
	v_mfma_f32_32x32x16_bf16 v[82:97], v[186:189], v[134:137], v[82:97]
	v_mfma_f32_32x32x16_bf16 v[98:113], v[182:185], v[134:137], v[98:113]
	v_mfma_f32_32x32x16_bf16 v[82:97], v[178:181], v[138:141], v[82:97]
	v_mfma_f32_32x32x16_bf16 v[98:113], v[174:177], v[138:141], v[98:113]
	v_add_u32_e32 v2, 0x3000, v238
	ds_read_b128 v[218:221], v2
	ds_read_b128 v[214:217], v2 offset:512
	ds_read_b128 v[210:213], v2 offset:2048
	ds_read_b128 v[206:209], v2 offset:2560
	ds_read_b128 v[202:205], v2 offset:4096
	ds_read_b128 v[198:201], v2 offset:4608
	ds_read_b128 v[194:197], v2 offset:6144
	ds_read_b128 v[190:193], v2 offset:6656
	ds_read_b128 v[186:189], v2 offset:8192
	ds_read_b128 v[182:185], v2 offset:8704
	ds_read_b128 v[178:181], v2 offset:10240
	ds_read_b128 v[174:177], v2 offset:10752
	s_nop 7
	v_max3_f32 v19, v82, v83, v84
	v_max3_f32 v26, v85, v86, v87
	v_max3_f32 v19, v19, v88, v89
	v_max3_f32 v26, v26, v90, v91
	v_max3_f32 v19, v19, v92, v93
	v_max3_f32 v26, v26, v94, v95
	v_max3_f32 v19, v19, v96, v97
	v_max3_f32 v26, v26, v98, v99
	v_max3_f32 v19, v19, v100, v101
	v_max3_f32 v26, v26, v102, v103
	v_max3_f32 v19, v19, v104, v105
	v_max3_f32 v26, v26, v106, v107
	v_max3_f32 v19, v19, v108, v109
	v_max3_f32 v26, v26, v110, v111
	v_max3_f32 v19, v19, v112, v113
	v_max_f32_e32 v19, v19, v26
	v_mov_b32_e32 v26, v19
	s_nop 1
	v_permlane32_swap_b32_e32 v19, v26
	v_max_f32_e32 v19, v19, v26
	v_max_f32_e32 v19, v19, v19
	v_mov_b32_e32 v239, v19
	v_xor_b32_e32 v66, 0x80000000, v19
	v_mov_b32_e32 v67, v66
	v_mov_b32_e32 v68, v66
	v_mov_b32_e32 v69, v66
	v_mov_b32_e32 v70, v66
	v_mov_b32_e32 v71, v66
	v_mov_b32_e32 v72, v66
	v_mov_b32_e32 v73, v66
	v_mov_b32_e32 v74, v66
	v_mov_b32_e32 v75, v66
	v_mov_b32_e32 v76, v66
	v_mov_b32_e32 v77, v66
	v_mov_b32_e32 v78, v66
	v_mov_b32_e32 v79, v66
	v_mov_b32_e32 v80, v66
	v_mov_b32_e32 v81, v66
	v_sub_f32_e32 v82, v82, v19
	v_sub_f32_e32 v83, v83, v19
	v_sub_f32_e32 v84, v84, v19
	v_sub_f32_e32 v85, v85, v19
	v_sub_f32_e32 v86, v86, v19
	v_sub_f32_e32 v87, v87, v19
	v_sub_f32_e32 v88, v88, v19
	v_sub_f32_e32 v89, v89, v19
	v_sub_f32_e32 v90, v90, v19
	v_sub_f32_e32 v91, v91, v19
	v_sub_f32_e32 v92, v92, v19
	v_sub_f32_e32 v93, v93, v19
	v_sub_f32_e32 v94, v94, v19
	v_sub_f32_e32 v95, v95, v19
	v_sub_f32_e32 v96, v96, v19
	v_sub_f32_e32 v97, v97, v19
	v_sub_f32_e32 v98, v98, v19
	v_sub_f32_e32 v99, v99, v19
	v_sub_f32_e32 v100, v100, v19
	v_sub_f32_e32 v101, v101, v19
	v_sub_f32_e32 v102, v102, v19
	v_sub_f32_e32 v103, v103, v19
	v_sub_f32_e32 v104, v104, v19
	v_sub_f32_e32 v105, v105, v19
	v_sub_f32_e32 v106, v106, v19
	v_sub_f32_e32 v107, v107, v19
	v_sub_f32_e32 v108, v108, v19
	v_sub_f32_e32 v109, v109, v19
	v_sub_f32_e32 v110, v110, v19
	v_sub_f32_e32 v111, v111, v19
	v_sub_f32_e32 v112, v112, v19
	v_sub_f32_e32 v113, v113, v19
	s_cmp_lt_i32 s79, 1
	s_cbranch_scc1 .Lmy_B_tail
	s_waitcnt lgkmcnt(0)
	v_mov_b32_e32 v2, v237
	v_mfma_f32_32x32x16_bf16 v[142:157], v[218:221], v[4:7], v[66:81]
	v_exp_f32_e32 v82, v82
	v_exp_f32_e32 v83, v83
	v_exp_f32_e32 v84, v84
	v_add_f32_e32 v27, v82, v83
	v_exp_f32_e32 v85, v85
	ds_read_b64_tr_b16 v[114:115], v2 offset:49152
	ds_read_b64_tr_b16 v[116:117], v2 offset:49664
	ds_read_b64_tr_b16 v[118:119], v2 offset:50176
	ds_read_b64_tr_b16 v[120:121], v2 offset:50688
	v_mfma_f32_32x32x16_bf16 v[158:173], v[214:217], v[4:7], v[66:81]
	v_exp_f32_e32 v86, v86
	v_add_f32_e32 v27, v27, v84
	v_exp_f32_e32 v87, v87
	v_add_f32_e32 v27, v27, v85
	v_exp_f32_e32 v88, v88
	ds_read_b64_tr_b16 v[122:123], v2 offset:51200
	ds_read_b64_tr_b16 v[124:125], v2 offset:51712
	ds_read_b64_tr_b16 v[126:127], v2 offset:52224
	ds_read_b64_tr_b16 v[128:129], v2 offset:52736
	v_mfma_f32_32x32x16_bf16 v[142:157], v[210:213], v[8:11], v[142:157]
	v_add_f32_e32 v27, v27, v86
	v_exp_f32_e32 v89, v89
	v_add_f32_e32 v27, v27, v87
	v_add_f32_e32 v27, v27, v88
	v_add_f32_e32 v27, v27, v89
	ds_read_b64_tr_b16 v[240:241], v2 offset:53248
	ds_read_b64_tr_b16 v[242:243], v2 offset:53760
	ds_read_b64_tr_b16 v[244:245], v2 offset:54272
	ds_read_b64_tr_b16 v[246:247], v2 offset:54784
	v_mfma_f32_32x32x16_bf16 v[158:173], v[206:209], v[8:11], v[158:173]
	v_cvt_pk_bf16_f32 v82, v82, v83
	v_cvt_pk_bf16_f32 v83, v84, v85
	v_cvt_pk_bf16_f32 v84, v86, v87
	v_cvt_pk_bf16_f32 v85, v88, v89
	ds_read_b64_tr_b16 v[248:249], v2 offset:55296
	ds_read_b64_tr_b16 v[250:251], v2 offset:55808
	ds_read_b64_tr_b16 v[20:21], v2 offset:56320
	ds_read_b64_tr_b16 v[22:23], v2 offset:56832
	v_mfma_f32_32x32x16_bf16 v[142:157], v[202:205], v[12:15], v[142:157]
	v_exp_f32_e32 v90, v90
	v_exp_f32_e32 v91, v91
	v_exp_f32_e32 v92, v92
	v_add_f32_e32 v27, v27, v90
	v_exp_f32_e32 v93, v93
	v_mfma_f32_32x32x16_bf16 v[158:173], v[198:201], v[12:15], v[158:173]
	v_add_f32_e32 v27, v27, v91
	v_exp_f32_e32 v94, v94
	v_add_f32_e32 v27, v27, v92
	v_exp_f32_e32 v95, v95
	v_add_f32_e32 v27, v27, v93
	s_waitcnt vmcnt(2)
	s_barrier
	v_mfma_f32_32x32x16_bf16 v[142:157], v[194:197], v[130:133], v[142:157]
	s_add_u32 m0, s57, 0x6000
	v_exp_f32_e32 v96, v96
	v_add_f32_e32 v27, v27, v94
	global_load_lds_dwordx4 v[28:29], off
	v_lshl_add_u64 v[28:29], v[28:29], 0, s[30:31]
	v_exp_f32_e32 v97, v97
	v_add_f32_e32 v27, v27, v95
	v_add_f32_e32 v27, v27, v96
	v_mfma_f32_32x32x16_bf16 v[158:173], v[190:193], v[130:133], v[158:173]
	s_add_u32 m0, s40, 0x0
	v_add_f32_e32 v27, v27, v97
	v_cvt_pk_bf16_f32 v90, v90, v91
	global_load_lds_dwordx4 v[24:25], off
	v_lshl_add_u64 v[24:25], v[24:25], 0, s[30:31]
	v_cvt_pk_bf16_f32 v91, v92, v93
	v_cvt_pk_bf16_f32 v92, v94, v95
	v_cvt_pk_bf16_f32 v93, v96, v97
	v_mfma_f32_32x32x16_bf16 v[142:157], v[186:189], v[134:137], v[142:157]
	s_add_u32 m0, s40, 0x3000
	v_exp_f32_e32 v98, v98
	v_exp_f32_e32 v99, v99
	global_load_lds_dwordx4 v[24:25], off
	v_lshl_add_u64 v[24:25], v[24:25], 0, s[30:31]
	v_exp_f32_e32 v100, v100
	v_add_f32_e32 v27, v27, v98
	v_exp_f32_e32 v101, v101
	v_mfma_f32_32x32x16_bf16 v[158:173], v[182:185], v[134:137], v[158:173]
	v_add_f32_e32 v27, v27, v99
	v_exp_f32_e32 v102, v102
	v_add_f32_e32 v27, v27, v100
	v_exp_f32_e32 v103, v103
	v_add_f32_e32 v27, v27, v101
	v_mfma_f32_32x32x16_bf16 v[142:157], v[178:181], v[138:141], v[142:157]
	v_exp_f32_e32 v104, v104
	v_add_f32_e32 v27, v27, v102
	v_exp_f32_e32 v105, v105
	v_add_f32_e32 v27, v27, v103
	v_add_f32_e32 v27, v27, v104
	v_mfma_f32_32x32x16_bf16 v[158:173], v[174:177], v[138:141], v[158:173]
	v_add_f32_e32 v27, v27, v105
	v_cvt_pk_bf16_f32 v98, v98, v99
	v_cvt_pk_bf16_f32 v99, v100, v101
	v_cvt_pk_bf16_f32 v100, v102, v103
	v_cvt_pk_bf16_f32 v101, v104, v105
	s_waitcnt lgkmcnt(0)
	v_add_u32_e32 v2, 0x6000, v238
	v_mfma_f32_32x32x16_bf16 v[34:49], v[82:85], v[114:117], v[34:49]
	v_exp_f32_e32 v106, v106
	v_exp_f32_e32 v107, v107
	v_exp_f32_e32 v108, v108
	v_add_f32_e32 v27, v27, v106
	v_exp_f32_e32 v109, v109
	ds_read_b128 v[218:221], v2
	ds_read_b128 v[214:217], v2 offset:512
	ds_read_b128 v[210:213], v2 offset:2048
	v_mfma_f32_32x32x16_bf16 v[50:65], v[82:85], v[240:243], v[50:65]
	v_add_f32_e32 v27, v27, v107
	v_exp_f32_e32 v110, v110
	v_add_f32_e32 v27, v27, v108
	v_exp_f32_e32 v111, v111
	v_add_f32_e32 v27, v27, v109
	ds_read_b128 v[206:209], v2 offset:2560
	ds_read_b128 v[202:205], v2 offset:4096
	ds_read_b128 v[198:201], v2 offset:4608
	v_mfma_f32_32x32x16_bf16 v[34:49], v[90:93], v[118:121], v[34:49]
	v_exp_f32_e32 v112, v112
	v_add_f32_e32 v27, v27, v110
	v_exp_f32_e32 v113, v113
	v_add_f32_e32 v27, v27, v111
	v_add_f32_e32 v27, v27, v112
	ds_read_b128 v[194:197], v2 offset:6144
	ds_read_b128 v[190:193], v2 offset:6656
	ds_read_b128 v[186:189], v2 offset:8192
	v_mfma_f32_32x32x16_bf16 v[50:65], v[90:93], v[244:247], v[50:65]
	v_add_f32_e32 v27, v27, v113
	v_cvt_pk_bf16_f32 v106, v106, v107
	v_cvt_pk_bf16_f32 v107, v108, v109
	v_cvt_pk_bf16_f32 v108, v110, v111
	v_cvt_pk_bf16_f32 v109, v112, v113
	v_add_f32_e32 v236, v236, v27
	ds_read_b128 v[182:185], v2 offset:8704
	ds_read_b128 v[178:181], v2 offset:10240
	ds_read_b128 v[174:177], v2 offset:10752
	v_mfma_f32_32x32x16_bf16 v[34:49], v[98:101], v[122:125], v[34:49]
	v_max3_f32 v19, v142, v143, v144
	v_max3_f32 v26, v145, v146, v147
	v_max3_f32 v19, v19, v148, v149
	v_max3_f32 v26, v26, v150, v151
	v_mfma_f32_32x32x16_bf16 v[50:65], v[98:101], v[248:251], v[50:65]
	v_max3_f32 v19, v19, v152, v153
	v_max3_f32 v26, v26, v154, v155
	v_max3_f32 v19, v19, v156, v157
	v_max3_f32 v26, v26, v158, v159
	v_mfma_f32_32x32x16_bf16 v[34:49], v[106:109], v[126:129], v[34:49]
	v_max3_f32 v19, v19, v160, v161
	v_max3_f32 v26, v26, v162, v163
	v_max3_f32 v19, v19, v164, v165
	v_max3_f32 v26, v26, v166, v167
	v_mfma_f32_32x32x16_bf16 v[50:65], v[106:109], v[20:23], v[50:65]
	v_max3_f32 v19, v19, v168, v169
	v_max3_f32 v26, v26, v170, v171
	v_max3_f32 v19, v19, v172, v173
	v_max_f32_e32 v19, v19, v26
	v_cmp_lt_f32_e32 vcc, s41, v19
	s_cbranch_vccz .Lmy_nors_31
	s_nop 15
	s_nop 15
	v_mov_b32_e32 v26, v19
	s_nop 1
	v_permlane32_swap_b32_e32 v19, v26
	v_max_f32_e32 v19, v19, v26
	v_max_f32_e32 v19, v19, v19
	v_max_f32_e32 v90, 0, v19
	v_exp_f32_e64 v91, -v90
	v_add_f32_e32 v239, v239, v90
	v_xor_b32_e32 v66, 0x80000000, v239
	v_mov_b32_e32 v67, v66
	v_mov_b32_e32 v68, v66
	v_mov_b32_e32 v69, v66
	v_mov_b32_e32 v70, v66
	v_mov_b32_e32 v71, v66
	v_mov_b32_e32 v72, v66
	v_mov_b32_e32 v73, v66
	v_mov_b32_e32 v74, v66
	v_mov_b32_e32 v75, v66
	v_mov_b32_e32 v76, v66
	v_mov_b32_e32 v77, v66
	v_mov_b32_e32 v78, v66
	v_mov_b32_e32 v79, v66
	v_mov_b32_e32 v80, v66
	v_mov_b32_e32 v81, v66
	v_sub_f32_e32 v142, v142, v90
	v_sub_f32_e32 v143, v143, v90
	v_sub_f32_e32 v144, v144, v90
	v_sub_f32_e32 v145, v145, v90
	v_sub_f32_e32 v146, v146, v90
	v_sub_f32_e32 v147, v147, v90
	v_sub_f32_e32 v148, v148, v90
	v_sub_f32_e32 v149, v149, v90
	v_sub_f32_e32 v150, v150, v90
	v_sub_f32_e32 v151, v151, v90
	v_sub_f32_e32 v152, v152, v90
	v_sub_f32_e32 v153, v153, v90
	v_sub_f32_e32 v154, v154, v90
	v_sub_f32_e32 v155, v155, v90
	v_sub_f32_e32 v156, v156, v90
	v_sub_f32_e32 v157, v157, v90
	v_sub_f32_e32 v158, v158, v90
	v_sub_f32_e32 v159, v159, v90
	v_sub_f32_e32 v160, v160, v90
	v_sub_f32_e32 v161, v161, v90
	v_sub_f32_e32 v162, v162, v90
	v_sub_f32_e32 v163, v163, v90
	v_sub_f32_e32 v164, v164, v90
	v_sub_f32_e32 v165, v165, v90
	v_sub_f32_e32 v166, v166, v90
	v_sub_f32_e32 v167, v167, v90
	v_sub_f32_e32 v168, v168, v90
	v_sub_f32_e32 v169, v169, v90
	v_sub_f32_e32 v170, v170, v90
	v_sub_f32_e32 v171, v171, v90
	v_sub_f32_e32 v172, v172, v90
	v_sub_f32_e32 v173, v173, v90
	v_mul_f32_e32 v236, v236, v91
	s_mov_b64 s[96:97], exec
	s_and_b64 exec, exec, s[8:9]
	ds_write_b32 v235, v91
	s_mov_b64 exec, s[96:97]
	v_lshl_add_u32 v2, v228, 4, s47
	ds_read_b128 v[94:97], v2 offset:0
	s_waitcnt lgkmcnt(0)
	v_mul_f32_e32 v34, v34, v94
	v_mul_f32_e32 v50, v50, v94
	v_mul_f32_e32 v35, v35, v95
	v_mul_f32_e32 v51, v51, v95
	v_mul_f32_e32 v36, v36, v96
	v_mul_f32_e32 v52, v52, v96
	v_mul_f32_e32 v37, v37, v97
	v_mul_f32_e32 v53, v53, v97
	ds_read_b128 v[94:97], v2 offset:32
	s_waitcnt lgkmcnt(0)
	v_mul_f32_e32 v38, v38, v94
	v_mul_f32_e32 v54, v54, v94
	v_mul_f32_e32 v39, v39, v95
	v_mul_f32_e32 v55, v55, v95
	v_mul_f32_e32 v40, v40, v96
	v_mul_f32_e32 v56, v56, v96
	v_mul_f32_e32 v41, v41, v97
	v_mul_f32_e32 v57, v57, v97
	ds_read_b128 v[94:97], v2 offset:64
	s_waitcnt lgkmcnt(0)
	v_mul_f32_e32 v42, v42, v94
	v_mul_f32_e32 v58, v58, v94
	v_mul_f32_e32 v43, v43, v95
	v_mul_f32_e32 v59, v59, v95
	v_mul_f32_e32 v44, v44, v96
	v_mul_f32_e32 v60, v60, v96
	v_mul_f32_e32 v45, v45, v97
	v_mul_f32_e32 v61, v61, v97
	ds_read_b128 v[94:97], v2 offset:96
	s_waitcnt lgkmcnt(0)
	v_mul_f32_e32 v46, v46, v94
	v_mul_f32_e32 v62, v62, v94
	v_mul_f32_e32 v47, v47, v95
	v_mul_f32_e32 v63, v63, v95
	v_mul_f32_e32 v48, v48, v96
	v_mul_f32_e32 v64, v64, v96
	v_mul_f32_e32 v49, v49, v97
	v_mul_f32_e32 v65, v65, v97
.Lmy_nors_31:
	s_waitcnt lgkmcnt(0)
	v_add_u32_e32 v2, 0x2000, v237
	v_mfma_f32_32x32x16_bf16 v[82:97], v[218:221], v[4:7], v[66:81]
	v_exp_f32_e32 v142, v142
	v_exp_f32_e32 v143, v143
	v_exp_f32_e32 v144, v144
	v_add_f32_e32 v27, v142, v143
	v_exp_f32_e32 v145, v145
	ds_read_b64_tr_b16 v[114:115], v2 offset:49152
	ds_read_b64_tr_b16 v[116:117], v2 offset:49664
	ds_read_b64_tr_b16 v[118:119], v2 offset:50176
	ds_read_b64_tr_b16 v[120:121], v2 offset:50688
	v_mfma_f32_32x32x16_bf16 v[98:113], v[214:217], v[4:7], v[66:81]
	v_exp_f32_e32 v146, v146
	v_add_f32_e32 v27, v27, v144
	v_exp_f32_e32 v147, v147
	v_add_f32_e32 v27, v27, v145
	v_exp_f32_e32 v148, v148
	ds_read_b64_tr_b16 v[122:123], v2 offset:51200
	ds_read_b64_tr_b16 v[124:125], v2 offset:51712
	ds_read_b64_tr_b16 v[126:127], v2 offset:52224
	ds_read_b64_tr_b16 v[128:129], v2 offset:52736
	v_mfma_f32_32x32x16_bf16 v[82:97], v[210:213], v[8:11], v[82:97]
	v_add_f32_e32 v27, v27, v146
	v_exp_f32_e32 v149, v149
	v_add_f32_e32 v27, v27, v147
	v_add_f32_e32 v27, v27, v148
	v_add_f32_e32 v27, v27, v149
	ds_read_b64_tr_b16 v[240:241], v2 offset:53248
	ds_read_b64_tr_b16 v[242:243], v2 offset:53760
	ds_read_b64_tr_b16 v[244:245], v2 offset:54272
	ds_read_b64_tr_b16 v[246:247], v2 offset:54784
	v_mfma_f32_32x32x16_bf16 v[98:113], v[206:209], v[8:11], v[98:113]
	v_cvt_pk_bf16_f32 v142, v142, v143
	v_cvt_pk_bf16_f32 v143, v144, v145
	v_cvt_pk_bf16_f32 v144, v146, v147
	v_cvt_pk_bf16_f32 v145, v148, v149
	ds_read_b64_tr_b16 v[248:249], v2 offset:55296
	ds_read_b64_tr_b16 v[250:251], v2 offset:55808
	ds_read_b64_tr_b16 v[20:21], v2 offset:56320
	ds_read_b64_tr_b16 v[22:23], v2 offset:56832
	v_mfma_f32_32x32x16_bf16 v[82:97], v[202:205], v[12:15], v[82:97]
	v_exp_f32_e32 v150, v150
	v_exp_f32_e32 v151, v151
	v_exp_f32_e32 v152, v152
	v_add_f32_e32 v27, v27, v150
	v_exp_f32_e32 v153, v153
	v_mfma_f32_32x32x16_bf16 v[98:113], v[198:201], v[12:15], v[98:113]
	v_add_f32_e32 v27, v27, v151
	v_exp_f32_e32 v154, v154
	v_add_f32_e32 v27, v27, v152
	v_exp_f32_e32 v155, v155
	v_add_f32_e32 v27, v27, v153
	s_waitcnt vmcnt(4)
	s_barrier
	v_mfma_f32_32x32x16_bf16 v[82:97], v[194:197], v[130:133], v[82:97]
	s_add_u32 m0, s57, 0x0
	v_exp_f32_e32 v156, v156
	v_add_f32_e32 v27, v27, v154
	global_load_lds_dwordx4 v[28:29], off
	v_lshl_add_u64 v[28:29], v[28:29], 0, s[30:31]
	v_exp_f32_e32 v157, v157
	v_add_f32_e32 v27, v27, v155
	v_add_f32_e32 v27, v27, v156
	v_mfma_f32_32x32x16_bf16 v[98:113], v[190:193], v[130:133], v[98:113]
	s_add_u32 m0, s40, 0x6000
	v_add_f32_e32 v27, v27, v157
	v_cvt_pk_bf16_f32 v150, v150, v151
	global_load_lds_dwordx4 v[24:25], off
	v_lshl_add_u64 v[24:25], v[24:25], 0, s[30:31]
	v_cvt_pk_bf16_f32 v151, v152, v153
	v_cvt_pk_bf16_f32 v152, v154, v155
	v_cvt_pk_bf16_f32 v153, v156, v157
	v_mfma_f32_32x32x16_bf16 v[82:97], v[186:189], v[134:137], v[82:97]
	v_exp_f32_e32 v158, v158
	v_exp_f32_e32 v159, v159
	v_exp_f32_e32 v160, v160
	v_add_f32_e32 v27, v27, v158
	v_exp_f32_e32 v161, v161
	v_mfma_f32_32x32x16_bf16 v[98:113], v[182:185], v[134:137], v[98:113]
	v_add_f32_e32 v27, v27, v159
	v_exp_f32_e32 v162, v162
	v_add_f32_e32 v27, v27, v160
	v_exp_f32_e32 v163, v163
	v_add_f32_e32 v27, v27, v161
	v_mfma_f32_32x32x16_bf16 v[82:97], v[178:181], v[138:141], v[82:97]
	v_exp_f32_e32 v164, v164
	v_add_f32_e32 v27, v27, v162
	v_exp_f32_e32 v165, v165
	v_add_f32_e32 v27, v27, v163
	v_add_f32_e32 v27, v27, v164
	v_mfma_f32_32x32x16_bf16 v[98:113], v[174:177], v[138:141], v[98:113]
	v_add_f32_e32 v27, v27, v165
	v_cvt_pk_bf16_f32 v158, v158, v159
	v_cvt_pk_bf16_f32 v159, v160, v161
	v_cvt_pk_bf16_f32 v160, v162, v163
	v_cvt_pk_bf16_f32 v161, v164, v165
	s_waitcnt lgkmcnt(0)
	v_add_u32_e32 v2, 0x9000, v238
	v_mfma_f32_32x32x16_bf16 v[34:49], v[142:145], v[114:117], v[34:49]
	v_exp_f32_e32 v166, v166
	v_exp_f32_e32 v167, v167
	v_exp_f32_e32 v168, v168
	v_add_f32_e32 v27, v27, v166
	v_exp_f32_e32 v169, v169
	ds_read_b128 v[218:221], v2
	ds_read_b128 v[214:217], v2 offset:512
	ds_read_b128 v[210:213], v2 offset:2048
	v_mfma_f32_32x32x16_bf16 v[50:65], v[142:145], v[240:243], v[50:65]
	v_add_f32_e32 v27, v27, v167
	v_exp_f32_e32 v170, v170
	v_add_f32_e32 v27, v27, v168
	v_exp_f32_e32 v171, v171
	v_add_f32_e32 v27, v27, v169
	ds_read_b128 v[206:209], v2 offset:2560
	ds_read_b128 v[202:205], v2 offset:4096
	ds_read_b128 v[198:201], v2 offset:4608
	v_mfma_f32_32x32x16_bf16 v[34:49], v[150:153], v[118:121], v[34:49]
	v_exp_f32_e32 v172, v172
	v_add_f32_e32 v27, v27, v170
	v_exp_f32_e32 v173, v173
	v_add_f32_e32 v27, v27, v171
	v_add_f32_e32 v27, v27, v172
	ds_read_b128 v[194:197], v2 offset:6144
	ds_read_b128 v[190:193], v2 offset:6656
	ds_read_b128 v[186:189], v2 offset:8192
	v_mfma_f32_32x32x16_bf16 v[50:65], v[150:153], v[244:247], v[50:65]
	v_add_f32_e32 v27, v27, v173
	v_cvt_pk_bf16_f32 v166, v166, v167
	v_cvt_pk_bf16_f32 v167, v168, v169
	v_cvt_pk_bf16_f32 v168, v170, v171
	v_cvt_pk_bf16_f32 v169, v172, v173
	v_add_f32_e32 v236, v236, v27
	ds_read_b128 v[182:185], v2 offset:8704
	ds_read_b128 v[178:181], v2 offset:10240
	ds_read_b128 v[174:177], v2 offset:10752
	v_mfma_f32_32x32x16_bf16 v[34:49], v[158:161], v[122:125], v[34:49]
	v_max3_f32 v19, v82, v83, v84
	v_max3_f32 v26, v85, v86, v87
	v_max3_f32 v19, v19, v88, v89
	v_max3_f32 v26, v26, v90, v91
	v_mfma_f32_32x32x16_bf16 v[50:65], v[158:161], v[248:251], v[50:65]
	v_max3_f32 v19, v19, v92, v93
	v_max3_f32 v26, v26, v94, v95
	v_max3_f32 v19, v19, v96, v97
	v_max3_f32 v26, v26, v98, v99
	v_mfma_f32_32x32x16_bf16 v[34:49], v[166:169], v[126:129], v[34:49]
	v_max3_f32 v19, v19, v100, v101
	v_max3_f32 v26, v26, v102, v103
	v_max3_f32 v19, v19, v104, v105
	v_max3_f32 v26, v26, v106, v107
	v_mfma_f32_32x32x16_bf16 v[50:65], v[166:169], v[20:23], v[50:65]
	v_max3_f32 v19, v19, v108, v109
	v_max3_f32 v26, v26, v110, v111
	v_max3_f32 v19, v19, v112, v113
	v_max_f32_e32 v19, v19, v26
	v_cmp_lt_f32_e32 vcc, s41, v19
	s_cbranch_vccz .Lmy_nors_32
	s_nop 15
	s_nop 15
	v_mov_b32_e32 v26, v19
	s_nop 1
	v_permlane32_swap_b32_e32 v19, v26
	v_max_f32_e32 v19, v19, v26
	v_max_f32_e32 v19, v19, v19
	v_max_f32_e32 v150, 0, v19
	v_exp_f32_e64 v151, -v150
	v_add_f32_e32 v239, v239, v150
	v_xor_b32_e32 v66, 0x80000000, v239
	v_mov_b32_e32 v67, v66
	v_mov_b32_e32 v68, v66
	v_mov_b32_e32 v69, v66
	v_mov_b32_e32 v70, v66
	v_mov_b32_e32 v71, v66
	v_mov_b32_e32 v72, v66
	v_mov_b32_e32 v73, v66
	v_mov_b32_e32 v74, v66
	v_mov_b32_e32 v75, v66
	v_mov_b32_e32 v76, v66
	v_mov_b32_e32 v77, v66
	v_mov_b32_e32 v78, v66
	v_mov_b32_e32 v79, v66
	v_mov_b32_e32 v80, v66
	v_mov_b32_e32 v81, v66
	v_sub_f32_e32 v82, v82, v150
	v_sub_f32_e32 v83, v83, v150
	v_sub_f32_e32 v84, v84, v150
	v_sub_f32_e32 v85, v85, v150
	v_sub_f32_e32 v86, v86, v150
	v_sub_f32_e32 v87, v87, v150
	v_sub_f32_e32 v88, v88, v150
	v_sub_f32_e32 v89, v89, v150
	v_sub_f32_e32 v90, v90, v150
	v_sub_f32_e32 v91, v91, v150
	v_sub_f32_e32 v92, v92, v150
	v_sub_f32_e32 v93, v93, v150
	v_sub_f32_e32 v94, v94, v150
	v_sub_f32_e32 v95, v95, v150
	v_sub_f32_e32 v96, v96, v150
	v_sub_f32_e32 v97, v97, v150
	v_sub_f32_e32 v98, v98, v150
	v_sub_f32_e32 v99, v99, v150
	v_sub_f32_e32 v100, v100, v150
	v_sub_f32_e32 v101, v101, v150
	v_sub_f32_e32 v102, v102, v150
	v_sub_f32_e32 v103, v103, v150
	v_sub_f32_e32 v104, v104, v150
	v_sub_f32_e32 v105, v105, v150
	v_sub_f32_e32 v106, v106, v150
	v_sub_f32_e32 v107, v107, v150
	v_sub_f32_e32 v108, v108, v150
	v_sub_f32_e32 v109, v109, v150
	v_sub_f32_e32 v110, v110, v150
	v_sub_f32_e32 v111, v111, v150
	v_sub_f32_e32 v112, v112, v150
	v_sub_f32_e32 v113, v113, v150
	v_mul_f32_e32 v236, v236, v151
	s_mov_b64 s[96:97], exec
	s_and_b64 exec, exec, s[8:9]
	ds_write_b32 v235, v151
	s_mov_b64 exec, s[96:97]
	v_lshl_add_u32 v2, v228, 4, s47
	ds_read_b128 v[154:157], v2 offset:0
	s_waitcnt lgkmcnt(0)
	v_mul_f32_e32 v34, v34, v154
	v_mul_f32_e32 v50, v50, v154
	v_mul_f32_e32 v35, v35, v155
	v_mul_f32_e32 v51, v51, v155
	v_mul_f32_e32 v36, v36, v156
	v_mul_f32_e32 v52, v52, v156
	v_mul_f32_e32 v37, v37, v157
	v_mul_f32_e32 v53, v53, v157
	ds_read_b128 v[154:157], v2 offset:32
	s_waitcnt lgkmcnt(0)
	v_mul_f32_e32 v38, v38, v154
	v_mul_f32_e32 v54, v54, v154
	v_mul_f32_e32 v39, v39, v155
	v_mul_f32_e32 v55, v55, v155
	v_mul_f32_e32 v40, v40, v156
	v_mul_f32_e32 v56, v56, v156
	v_mul_f32_e32 v41, v41, v157
	v_mul_f32_e32 v57, v57, v157
	ds_read_b128 v[154:157], v2 offset:64
	s_waitcnt lgkmcnt(0)
	v_mul_f32_e32 v42, v42, v154
	v_mul_f32_e32 v58, v58, v154
	v_mul_f32_e32 v43, v43, v155
	v_mul_f32_e32 v59, v59, v155
	v_mul_f32_e32 v44, v44, v156
	v_mul_f32_e32 v60, v60, v156
	v_mul_f32_e32 v45, v45, v157
	v_mul_f32_e32 v61, v61, v157
	ds_read_b128 v[154:157], v2 offset:96
	s_waitcnt lgkmcnt(0)
	v_mul_f32_e32 v46, v46, v154
	v_mul_f32_e32 v62, v62, v154
	v_mul_f32_e32 v47, v47, v155
	v_mul_f32_e32 v63, v63, v155
	v_mul_f32_e32 v48, v48, v156
	v_mul_f32_e32 v64, v64, v156
	v_mul_f32_e32 v49, v49, v157
	v_mul_f32_e32 v65, v65, v157
.Lmy_nors_32:
	s_waitcnt lgkmcnt(0)
	v_add_u32_e32 v2, 0x4000, v237
	v_mfma_f32_32x32x16_bf16 v[142:157], v[218:221], v[4:7], v[66:81]
	v_exp_f32_e32 v82, v82
	v_exp_f32_e32 v83, v83
	v_exp_f32_e32 v84, v84
	v_add_f32_e32 v27, v82, v83
	v_exp_f32_e32 v85, v85
	ds_read_b64_tr_b16 v[114:115], v2 offset:49152
	ds_read_b64_tr_b16 v[116:117], v2 offset:49664
	ds_read_b64_tr_b16 v[118:119], v2 offset:50176
	ds_read_b64_tr_b16 v[120:121], v2 offset:50688
	v_mfma_f32_32x32x16_bf16 v[158:173], v[214:217], v[4:7], v[66:81]
	v_exp_f32_e32 v86, v86
	v_add_f32_e32 v27, v27, v84
	v_exp_f32_e32 v87, v87
	v_add_f32_e32 v27, v27, v85
	v_exp_f32_e32 v88, v88
	ds_read_b64_tr_b16 v[122:123], v2 offset:51200
	ds_read_b64_tr_b16 v[124:125], v2 offset:51712
	ds_read_b64_tr_b16 v[126:127], v2 offset:52224
	ds_read_b64_tr_b16 v[128:129], v2 offset:52736
	v_mfma_f32_32x32x16_bf16 v[142:157], v[210:213], v[8:11], v[142:157]
	v_add_f32_e32 v27, v27, v86
	v_exp_f32_e32 v89, v89
	v_add_f32_e32 v27, v27, v87
	v_add_f32_e32 v27, v27, v88
	v_add_f32_e32 v27, v27, v89
	ds_read_b64_tr_b16 v[240:241], v2 offset:53248
	ds_read_b64_tr_b16 v[242:243], v2 offset:53760
	ds_read_b64_tr_b16 v[244:245], v2 offset:54272
	ds_read_b64_tr_b16 v[246:247], v2 offset:54784
	v_mfma_f32_32x32x16_bf16 v[158:173], v[206:209], v[8:11], v[158:173]
	v_cvt_pk_bf16_f32 v82, v82, v83
	v_cvt_pk_bf16_f32 v83, v84, v85
	v_cvt_pk_bf16_f32 v84, v86, v87
	v_cvt_pk_bf16_f32 v85, v88, v89
	ds_read_b64_tr_b16 v[248:249], v2 offset:55296
	ds_read_b64_tr_b16 v[250:251], v2 offset:55808
	ds_read_b64_tr_b16 v[20:21], v2 offset:56320
	ds_read_b64_tr_b16 v[22:23], v2 offset:56832
	v_mfma_f32_32x32x16_bf16 v[142:157], v[202:205], v[12:15], v[142:157]
	v_exp_f32_e32 v90, v90
	v_exp_f32_e32 v91, v91
	v_exp_f32_e32 v92, v92
	v_add_f32_e32 v27, v27, v90
	v_exp_f32_e32 v93, v93
	v_mfma_f32_32x32x16_bf16 v[158:173], v[198:201], v[12:15], v[158:173]
	v_add_f32_e32 v27, v27, v91
	v_exp_f32_e32 v94, v94
	v_add_f32_e32 v27, v27, v92
	v_exp_f32_e32 v95, v95
	v_add_f32_e32 v27, v27, v93
	s_waitcnt vmcnt(3)
	s_barrier
	v_mfma_f32_32x32x16_bf16 v[142:157], v[194:197], v[130:133], v[142:157]
	s_add_u32 m0, s57, 0x2000
	v_exp_f32_e32 v96, v96
	v_add_f32_e32 v27, v27, v94
	global_load_lds_dwordx4 v[28:29], off
	v_lshl_add_u64 v[28:29], v[28:29], 0, s[30:31]
	v_exp_f32_e32 v97, v97
	v_add_f32_e32 v27, v27, v95
	v_add_f32_e32 v27, v27, v96
	v_mfma_f32_32x32x16_bf16 v[158:173], v[190:193], v[130:133], v[158:173]
	s_add_u32 m0, s40, 0x9000
	v_add_f32_e32 v27, v27, v97
	v_cvt_pk_bf16_f32 v90, v90, v91
	global_load_lds_dwordx4 v[24:25], off
	v_lshl_add_u64 v[24:25], v[24:25], 0, s[30:31]
	v_cvt_pk_bf16_f32 v91, v92, v93
	v_cvt_pk_bf16_f32 v92, v94, v95
	v_cvt_pk_bf16_f32 v93, v96, v97
	v_mfma_f32_32x32x16_bf16 v[142:157], v[186:189], v[134:137], v[142:157]
	v_exp_f32_e32 v98, v98
	v_exp_f32_e32 v99, v99
	v_exp_f32_e32 v100, v100
	v_add_f32_e32 v27, v27, v98
	v_exp_f32_e32 v101, v101
	v_mfma_f32_32x32x16_bf16 v[158:173], v[182:185], v[134:137], v[158:173]
	v_add_f32_e32 v27, v27, v99
	v_exp_f32_e32 v102, v102
	v_add_f32_e32 v27, v27, v100
	v_exp_f32_e32 v103, v103
	v_add_f32_e32 v27, v27, v101
	v_mfma_f32_32x32x16_bf16 v[142:157], v[178:181], v[138:141], v[142:157]
	v_exp_f32_e32 v104, v104
	v_add_f32_e32 v27, v27, v102
	v_exp_f32_e32 v105, v105
	v_add_f32_e32 v27, v27, v103
	v_add_f32_e32 v27, v27, v104
	v_mfma_f32_32x32x16_bf16 v[158:173], v[174:177], v[138:141], v[158:173]
	v_add_f32_e32 v27, v27, v105
	v_cvt_pk_bf16_f32 v98, v98, v99
	v_cvt_pk_bf16_f32 v99, v100, v101
	v_cvt_pk_bf16_f32 v100, v102, v103
	v_cvt_pk_bf16_f32 v101, v104, v105
	s_waitcnt lgkmcnt(0)
	v_mov_b32_e32 v2, v238
	v_mfma_f32_32x32x16_bf16 v[34:49], v[82:85], v[114:117], v[34:49]
	v_exp_f32_e32 v106, v106
	v_exp_f32_e32 v107, v107
	v_exp_f32_e32 v108, v108
	v_add_f32_e32 v27, v27, v106
	v_exp_f32_e32 v109, v109
	ds_read_b128 v[218:221], v2
	ds_read_b128 v[214:217], v2 offset:512
	ds_read_b128 v[210:213], v2 offset:2048
	v_mfma_f32_32x32x16_bf16 v[50:65], v[82:85], v[240:243], v[50:65]
	v_add_f32_e32 v27, v27, v107
	v_exp_f32_e32 v110, v110
	v_add_f32_e32 v27, v27, v108
	v_exp_f32_e32 v111, v111
	v_add_f32_e32 v27, v27, v109
	ds_read_b128 v[206:209], v2 offset:2560
	ds_read_b128 v[202:205], v2 offset:4096
	ds_read_b128 v[198:201], v2 offset:4608
	v_mfma_f32_32x32x16_bf16 v[34:49], v[90:93], v[118:121], v[34:49]
	v_exp_f32_e32 v112, v112
	v_add_f32_e32 v27, v27, v110
	v_exp_f32_e32 v113, v113
	v_add_f32_e32 v27, v27, v111
	v_add_f32_e32 v27, v27, v112
	ds_read_b128 v[194:197], v2 offset:6144
	ds_read_b128 v[190:193], v2 offset:6656
	ds_read_b128 v[186:189], v2 offset:8192
	v_mfma_f32_32x32x16_bf16 v[50:65], v[90:93], v[244:247], v[50:65]
	v_add_f32_e32 v27, v27, v113
	v_cvt_pk_bf16_f32 v106, v106, v107
	v_cvt_pk_bf16_f32 v107, v108, v109
	v_cvt_pk_bf16_f32 v108, v110, v111
	v_cvt_pk_bf16_f32 v109, v112, v113
	v_add_f32_e32 v236, v236, v27
	ds_read_b128 v[182:185], v2 offset:8704
	ds_read_b128 v[178:181], v2 offset:10240
	ds_read_b128 v[174:177], v2 offset:10752
	v_mfma_f32_32x32x16_bf16 v[34:49], v[98:101], v[122:125], v[34:49]
	v_max3_f32 v19, v142, v143, v144
	v_max3_f32 v26, v145, v146, v147
	v_max3_f32 v19, v19, v148, v149
	v_max3_f32 v26, v26, v150, v151
	v_mfma_f32_32x32x16_bf16 v[50:65], v[98:101], v[248:251], v[50:65]
	v_max3_f32 v19, v19, v152, v153
	v_max3_f32 v26, v26, v154, v155
	v_max3_f32 v19, v19, v156, v157
	v_max3_f32 v26, v26, v158, v159
	v_mfma_f32_32x32x16_bf16 v[34:49], v[106:109], v[126:129], v[34:49]
	v_max3_f32 v19, v19, v160, v161
	v_max3_f32 v26, v26, v162, v163
	v_max3_f32 v19, v19, v164, v165
	v_max3_f32 v26, v26, v166, v167
	v_mfma_f32_32x32x16_bf16 v[50:65], v[106:109], v[20:23], v[50:65]
	v_max3_f32 v19, v19, v168, v169
	v_max3_f32 v26, v26, v170, v171
	v_max3_f32 v19, v19, v172, v173
	v_max_f32_e32 v19, v19, v26
	v_cmp_lt_f32_e32 vcc, s41, v19
	s_cbranch_vccz .Lmy_nors_33
	s_nop 15
	s_nop 15
	v_mov_b32_e32 v26, v19
	s_nop 1
	v_permlane32_swap_b32_e32 v19, v26
	v_max_f32_e32 v19, v19, v26
	v_max_f32_e32 v19, v19, v19
	v_max_f32_e32 v90, 0, v19
	v_exp_f32_e64 v91, -v90
	v_add_f32_e32 v239, v239, v90
	v_xor_b32_e32 v66, 0x80000000, v239
	v_mov_b32_e32 v67, v66
	v_mov_b32_e32 v68, v66
	v_mov_b32_e32 v69, v66
	v_mov_b32_e32 v70, v66
	v_mov_b32_e32 v71, v66
	v_mov_b32_e32 v72, v66
	v_mov_b32_e32 v73, v66
	v_mov_b32_e32 v74, v66
	v_mov_b32_e32 v75, v66
	v_mov_b32_e32 v76, v66
	v_mov_b32_e32 v77, v66
	v_mov_b32_e32 v78, v66
	v_mov_b32_e32 v79, v66
	v_mov_b32_e32 v80, v66
	v_mov_b32_e32 v81, v66
	v_sub_f32_e32 v142, v142, v90
	v_sub_f32_e32 v143, v143, v90
	v_sub_f32_e32 v144, v144, v90
	v_sub_f32_e32 v145, v145, v90
	v_sub_f32_e32 v146, v146, v90
	v_sub_f32_e32 v147, v147, v90
	v_sub_f32_e32 v148, v148, v90
	v_sub_f32_e32 v149, v149, v90
	v_sub_f32_e32 v150, v150, v90
	v_sub_f32_e32 v151, v151, v90
	v_sub_f32_e32 v152, v152, v90
	v_sub_f32_e32 v153, v153, v90
	v_sub_f32_e32 v154, v154, v90
	v_sub_f32_e32 v155, v155, v90
	v_sub_f32_e32 v156, v156, v90
	v_sub_f32_e32 v157, v157, v90
	v_sub_f32_e32 v158, v158, v90
	v_sub_f32_e32 v159, v159, v90
	v_sub_f32_e32 v160, v160, v90
	v_sub_f32_e32 v161, v161, v90
	v_sub_f32_e32 v162, v162, v90
	v_sub_f32_e32 v163, v163, v90
	v_sub_f32_e32 v164, v164, v90
	v_sub_f32_e32 v165, v165, v90
	v_sub_f32_e32 v166, v166, v90
	v_sub_f32_e32 v167, v167, v90
	v_sub_f32_e32 v168, v168, v90
	v_sub_f32_e32 v169, v169, v90
	v_sub_f32_e32 v170, v170, v90
	v_sub_f32_e32 v171, v171, v90
	v_sub_f32_e32 v172, v172, v90
	v_sub_f32_e32 v173, v173, v90
	v_mul_f32_e32 v236, v236, v91
	s_mov_b64 s[96:97], exec
	s_and_b64 exec, exec, s[8:9]
	ds_write_b32 v235, v91
	s_mov_b64 exec, s[96:97]
	v_lshl_add_u32 v2, v228, 4, s47
	ds_read_b128 v[94:97], v2 offset:0
	s_waitcnt lgkmcnt(0)
	v_mul_f32_e32 v34, v34, v94
	v_mul_f32_e32 v50, v50, v94
	v_mul_f32_e32 v35, v35, v95
	v_mul_f32_e32 v51, v51, v95
	v_mul_f32_e32 v36, v36, v96
	v_mul_f32_e32 v52, v52, v96
	v_mul_f32_e32 v37, v37, v97
	v_mul_f32_e32 v53, v53, v97
	ds_read_b128 v[94:97], v2 offset:32
	s_waitcnt lgkmcnt(0)
	v_mul_f32_e32 v38, v38, v94
	v_mul_f32_e32 v54, v54, v94
	v_mul_f32_e32 v39, v39, v95
	v_mul_f32_e32 v55, v55, v95
	v_mul_f32_e32 v40, v40, v96
	v_mul_f32_e32 v56, v56, v96
	v_mul_f32_e32 v41, v41, v97
	v_mul_f32_e32 v57, v57, v97
	ds_read_b128 v[94:97], v2 offset:64
	s_waitcnt lgkmcnt(0)
	v_mul_f32_e32 v42, v42, v94
	v_mul_f32_e32 v58, v58, v94
	v_mul_f32_e32 v43, v43, v95
	v_mul_f32_e32 v59, v59, v95
	v_mul_f32_e32 v44, v44, v96
	v_mul_f32_e32 v60, v60, v96
	v_mul_f32_e32 v45, v45, v97
	v_mul_f32_e32 v61, v61, v97
	ds_read_b128 v[94:97], v2 offset:96
	s_waitcnt lgkmcnt(0)
	v_mul_f32_e32 v46, v46, v94
	v_mul_f32_e32 v62, v62, v94
	v_mul_f32_e32 v47, v47, v95
	v_mul_f32_e32 v63, v63, v95
	v_mul_f32_e32 v48, v48, v96
	v_mul_f32_e32 v64, v64, v96
	v_mul_f32_e32 v49, v49, v97
	v_mul_f32_e32 v65, v65, v97

.Lmy_gl_34:
	v_add_f32_e32 v27, v27, v157
	v_cvt_pk_bf16_f32 v150, v150, v151
	v_cvt_pk_bf16_f32 v151, v152, v153
	v_cvt_pk_bf16_f32 v152, v154, v155
	v_cvt_pk_bf16_f32 v153, v156, v157
	v_mfma_f32_32x32x16_bf16 v[82:97], v[186:189], v[134:137], v[82:97]
	v_exp_f32_e32 v158, v158
	v_exp_f32_e32 v159, v159
	v_exp_f32_e32 v160, v160
	v_add_f32_e32 v27, v27, v158
	v_exp_f32_e32 v161, v161
	v_mfma_f32_32x32x16_bf16 v[98:113], v[182:185], v[134:137], v[98:113]
	v_add_f32_e32 v27, v27, v159
	v_exp_f32_e32 v162, v162
	v_add_f32_e32 v27, v27, v160
	v_exp_f32_e32 v163, v163
	v_add_f32_e32 v27, v27, v161
	v_mfma_f32_32x32x16_bf16 v[82:97], v[178:181], v[138:141], v[82:97]
	v_exp_f32_e32 v164, v164
	v_add_f32_e32 v27, v27, v162
	v_exp_f32_e32 v165, v165
	v_add_f32_e32 v27, v27, v163
	v_add_f32_e32 v27, v27, v164
	v_mfma_f32_32x32x16_bf16 v[98:113], v[174:177], v[138:141], v[98:113]
	v_add_f32_e32 v27, v27, v165
	v_cvt_pk_bf16_f32 v158, v158, v159
	v_cvt_pk_bf16_f32 v159, v160, v161
	v_cvt_pk_bf16_f32 v160, v162, v163
	v_cvt_pk_bf16_f32 v161, v164, v165
	s_waitcnt lgkmcnt(0)
	v_add_u32_e32 v2, 0x3000, v238
	v_mfma_f32_32x32x16_bf16 v[34:49], v[142:145], v[114:117], v[34:49]
	v_exp_f32_e32 v166, v166
	v_exp_f32_e32 v167, v167
	v_exp_f32_e32 v168, v168
	v_add_f32_e32 v27, v27, v166
	v_exp_f32_e32 v169, v169
	ds_read_b128 v[218:221], v2
	ds_read_b128 v[214:217], v2 offset:512
	ds_read_b128 v[210:213], v2 offset:2048
	v_mfma_f32_32x32x16_bf16 v[50:65], v[142:145], v[240:243], v[50:65]
	v_add_f32_e32 v27, v27, v167
	v_exp_f32_e32 v170, v170
	v_add_f32_e32 v27, v27, v168
	v_exp_f32_e32 v171, v171
	v_add_f32_e32 v27, v27, v169
	ds_read_b128 v[206:209], v2 offset:2560
	ds_read_b128 v[202:205], v2 offset:4096
	ds_read_b128 v[198:201], v2 offset:4608
	v_mfma_f32_32x32x16_bf16 v[34:49], v[150:153], v[118:121], v[34:49]
	v_exp_f32_e32 v172, v172
	v_add_f32_e32 v27, v27, v170
	v_exp_f32_e32 v173, v173
	v_add_f32_e32 v27, v27, v171
	v_add_f32_e32 v27, v27, v172
	ds_read_b128 v[194:197], v2 offset:6144
	ds_read_b128 v[190:193], v2 offset:6656
	ds_read_b128 v[186:189], v2 offset:8192
	v_mfma_f32_32x32x16_bf16 v[50:65], v[150:153], v[244:247], v[50:65]
	v_add_f32_e32 v27, v27, v173
	v_cvt_pk_bf16_f32 v166, v166, v167
	v_cvt_pk_bf16_f32 v167, v168, v169
	v_cvt_pk_bf16_f32 v168, v170, v171
	v_cvt_pk_bf16_f32 v169, v172, v173
	v_add_f32_e32 v236, v236, v27
	ds_read_b128 v[182:185], v2 offset:8704
	ds_read_b128 v[178:181], v2 offset:10240
	ds_read_b128 v[174:177], v2 offset:10752
	v_mfma_f32_32x32x16_bf16 v[34:49], v[158:161], v[122:125], v[34:49]
	v_max3_f32 v19, v82, v83, v84
	v_max3_f32 v26, v85, v86, v87
	v_max3_f32 v19, v19, v88, v89
	v_max3_f32 v26, v26, v90, v91
	v_mfma_f32_32x32x16_bf16 v[50:65], v[158:161], v[248:251], v[50:65]
	v_max3_f32 v19, v19, v92, v93
	v_max3_f32 v26, v26, v94, v95
	v_max3_f32 v19, v19, v96, v97
	v_max3_f32 v26, v26, v98, v99
	v_mfma_f32_32x32x16_bf16 v[34:49], v[166:169], v[126:129], v[34:49]
	v_max3_f32 v19, v19, v100, v101
	v_max3_f32 v26, v26, v102, v103
	v_max3_f32 v19, v19, v104, v105
	v_max3_f32 v26, v26, v106, v107
	v_mfma_f32_32x32x16_bf16 v[50:65], v[166:169], v[20:23], v[50:65]
	v_max3_f32 v19, v19, v108, v109
	v_max3_f32 v26, v26, v110, v111
	v_max3_f32 v19, v19, v112, v113
	v_max_f32_e32 v19, v19, v26
	v_cmp_lt_f32_e32 vcc, s41, v19
	s_cbranch_vccz .Lmy_nors_35
	s_nop 15
	s_nop 15
	v_mov_b32_e32 v26, v19
	s_nop 1
	v_permlane32_swap_b32_e32 v19, v26
	v_max_f32_e32 v19, v19, v26
	v_max_f32_e32 v19, v19, v19
	v_max_f32_e32 v150, 0, v19
	v_exp_f32_e64 v151, -v150
	v_add_f32_e32 v239, v239, v150
	v_xor_b32_e32 v66, 0x80000000, v239
	v_mov_b32_e32 v67, v66
	v_mov_b32_e32 v68, v66
	v_mov_b32_e32 v69, v66
	v_mov_b32_e32 v70, v66
	v_mov_b32_e32 v71, v66
	v_mov_b32_e32 v72, v66
	v_mov_b32_e32 v73, v66
	v_mov_b32_e32 v74, v66
	v_mov_b32_e32 v75, v66
	v_mov_b32_e32 v76, v66
	v_mov_b32_e32 v77, v66
	v_mov_b32_e32 v78, v66
	v_mov_b32_e32 v79, v66
	v_mov_b32_e32 v80, v66
	v_mov_b32_e32 v81, v66
	v_sub_f32_e32 v82, v82, v150
	v_sub_f32_e32 v83, v83, v150
	v_sub_f32_e32 v84, v84, v150
	v_sub_f32_e32 v85, v85, v150
	v_sub_f32_e32 v86, v86, v150
	v_sub_f32_e32 v87, v87, v150
	v_sub_f32_e32 v88, v88, v150
	v_sub_f32_e32 v89, v89, v150
	v_sub_f32_e32 v90, v90, v150
	v_sub_f32_e32 v91, v91, v150
	v_sub_f32_e32 v92, v92, v150
	v_sub_f32_e32 v93, v93, v150
	v_sub_f32_e32 v94, v94, v150
	v_sub_f32_e32 v95, v95, v150
	v_sub_f32_e32 v96, v96, v150
	v_sub_f32_e32 v97, v97, v150
	v_sub_f32_e32 v98, v98, v150
	v_sub_f32_e32 v99, v99, v150
	v_sub_f32_e32 v100, v100, v150
	v_sub_f32_e32 v101, v101, v150
	v_sub_f32_e32 v102, v102, v150
	v_sub_f32_e32 v103, v103, v150
	v_sub_f32_e32 v104, v104, v150
	v_sub_f32_e32 v105, v105, v150
	v_sub_f32_e32 v106, v106, v150
	v_sub_f32_e32 v107, v107, v150
	v_sub_f32_e32 v108, v108, v150
	v_sub_f32_e32 v109, v109, v150
	v_sub_f32_e32 v110, v110, v150
	v_sub_f32_e32 v111, v111, v150
	v_sub_f32_e32 v112, v112, v150
	v_sub_f32_e32 v113, v113, v150
	v_mul_f32_e32 v236, v236, v151
	s_mov_b64 s[96:97], exec
	s_and_b64 exec, exec, s[8:9]
	ds_write_b32 v235, v151
	s_mov_b64 exec, s[96:97]
	v_lshl_add_u32 v2, v228, 4, s47
	ds_read_b128 v[154:157], v2 offset:0
	s_waitcnt lgkmcnt(0)
	v_mul_f32_e32 v34, v34, v154
	v_mul_f32_e32 v50, v50, v154
	v_mul_f32_e32 v35, v35, v155
	v_mul_f32_e32 v51, v51, v155
	v_mul_f32_e32 v36, v36, v156
	v_mul_f32_e32 v52, v52, v156
	v_mul_f32_e32 v37, v37, v157
	v_mul_f32_e32 v53, v53, v157
	ds_read_b128 v[154:157], v2 offset:32
	s_waitcnt lgkmcnt(0)
	v_mul_f32_e32 v38, v38, v154
	v_mul_f32_e32 v54, v54, v154
	v_mul_f32_e32 v39, v39, v155
	v_mul_f32_e32 v55, v55, v155
	v_mul_f32_e32 v40, v40, v156
	v_mul_f32_e32 v56, v56, v156
	v_mul_f32_e32 v41, v41, v157
	v_mul_f32_e32 v57, v57, v157
	ds_read_b128 v[154:157], v2 offset:64
	s_waitcnt lgkmcnt(0)
	v_mul_f32_e32 v42, v42, v154
	v_mul_f32_e32 v58, v58, v154
	v_mul_f32_e32 v43, v43, v155
	v_mul_f32_e32 v59, v59, v155
	v_mul_f32_e32 v44, v44, v156
	v_mul_f32_e32 v60, v60, v156
	v_mul_f32_e32 v45, v45, v157
	v_mul_f32_e32 v61, v61, v157
	ds_read_b128 v[154:157], v2 offset:96
	s_waitcnt lgkmcnt(0)
	v_mul_f32_e32 v46, v46, v154
	v_mul_f32_e32 v62, v62, v154
	v_mul_f32_e32 v47, v47, v155
	v_mul_f32_e32 v63, v63, v155
	v_mul_f32_e32 v48, v48, v156
	v_mul_f32_e32 v64, v64, v156
	v_mul_f32_e32 v49, v49, v157
	v_mul_f32_e32 v65, v65, v157

.Lmy_B_loop:
	s_waitcnt lgkmcnt(0)
	v_mov_b32_e32 v2, v237
	v_mfma_f32_32x32x16_bf16 v[142:157], v[218:221], v[4:7], v[66:81]
	v_exp_f32_e32 v82, v82
	v_exp_f32_e32 v83, v83
	v_exp_f32_e32 v84, v84
	v_add_f32_e32 v27, v82, v83
	v_exp_f32_e32 v85, v85
	ds_read_b64_tr_b16 v[114:115], v2 offset:49152
	ds_read_b64_tr_b16 v[116:117], v2 offset:49664
	ds_read_b64_tr_b16 v[118:119], v2 offset:50176
	ds_read_b64_tr_b16 v[120:121], v2 offset:50688
	v_mfma_f32_32x32x16_bf16 v[158:173], v[214:217], v[4:7], v[66:81]
	v_exp_f32_e32 v86, v86
	v_add_f32_e32 v27, v27, v84
	v_exp_f32_e32 v87, v87
	v_add_f32_e32 v27, v27, v85
	v_exp_f32_e32 v88, v88
	ds_read_b64_tr_b16 v[122:123], v2 offset:51200
	ds_read_b64_tr_b16 v[124:125], v2 offset:51712
	ds_read_b64_tr_b16 v[126:127], v2 offset:52224
	ds_read_b64_tr_b16 v[128:129], v2 offset:52736
	v_mfma_f32_32x32x16_bf16 v[142:157], v[210:213], v[8:11], v[142:157]
	v_add_f32_e32 v27, v27, v86
	v_exp_f32_e32 v89, v89
	v_add_f32_e32 v27, v27, v87
	v_add_f32_e32 v27, v27, v88
	v_add_f32_e32 v27, v27, v89
	ds_read_b64_tr_b16 v[240:241], v2 offset:53248
	ds_read_b64_tr_b16 v[242:243], v2 offset:53760
	ds_read_b64_tr_b16 v[244:245], v2 offset:54272
	ds_read_b64_tr_b16 v[246:247], v2 offset:54784
	v_mfma_f32_32x32x16_bf16 v[158:173], v[206:209], v[8:11], v[158:173]
	v_cvt_pk_bf16_f32 v82, v82, v83
	v_cvt_pk_bf16_f32 v83, v84, v85
	v_cvt_pk_bf16_f32 v84, v86, v87
	v_cvt_pk_bf16_f32 v85, v88, v89
	ds_read_b64_tr_b16 v[248:249], v2 offset:55296
	ds_read_b64_tr_b16 v[250:251], v2 offset:55808
	ds_read_b64_tr_b16 v[20:21], v2 offset:56320
	ds_read_b64_tr_b16 v[22:23], v2 offset:56832
	v_mfma_f32_32x32x16_bf16 v[142:157], v[202:205], v[12:15], v[142:157]
	v_exp_f32_e32 v90, v90
	v_exp_f32_e32 v91, v91
	v_exp_f32_e32 v92, v92
	v_add_f32_e32 v27, v27, v90
	v_exp_f32_e32 v93, v93
	v_mfma_f32_32x32x16_bf16 v[158:173], v[198:201], v[12:15], v[158:173]
	v_add_f32_e32 v27, v27, v91
	v_exp_f32_e32 v94, v94
	v_add_f32_e32 v27, v27, v92
	v_exp_f32_e32 v95, v95
	v_add_f32_e32 v27, v27, v93
	s_waitcnt vmcnt(4)
	s_barrier
	v_mfma_f32_32x32x16_bf16 v[142:157], v[194:197], v[130:133], v[142:157]
	s_add_u32 m0, s57, 0x6000
	v_exp_f32_e32 v96, v96
	v_add_f32_e32 v27, v27, v94
	global_load_lds_dwordx4 v[28:29], off
	v_lshl_add_u64 v[28:29], v[28:29], 0, s[30:31]
	v_exp_f32_e32 v97, v97
	v_add_f32_e32 v27, v27, v95
	v_add_f32_e32 v27, v27, v96
	v_mfma_f32_32x32x16_bf16 v[158:173], v[190:193], v[130:133], v[158:173]
	s_add_u32 m0, s40, 0x3000
	v_add_f32_e32 v27, v27, v97
	v_cvt_pk_bf16_f32 v90, v90, v91
	global_load_lds_dwordx4 v[24:25], off
	v_lshl_add_u64 v[24:25], v[24:25], 0, s[30:31]
	v_cvt_pk_bf16_f32 v91, v92, v93
	v_cvt_pk_bf16_f32 v92, v94, v95
	v_cvt_pk_bf16_f32 v93, v96, v97
	v_mfma_f32_32x32x16_bf16 v[142:157], v[186:189], v[134:137], v[142:157]
	v_exp_f32_e32 v98, v98
	v_exp_f32_e32 v99, v99
	v_exp_f32_e32 v100, v100
	v_add_f32_e32 v27, v27, v98
	v_exp_f32_e32 v101, v101
	v_mfma_f32_32x32x16_bf16 v[158:173], v[182:185], v[134:137], v[158:173]
	v_add_f32_e32 v27, v27, v99
	v_exp_f32_e32 v102, v102
	v_add_f32_e32 v27, v27, v100
	v_exp_f32_e32 v103, v103
	v_add_f32_e32 v27, v27, v101
	v_mfma_f32_32x32x16_bf16 v[142:157], v[178:181], v[138:141], v[142:157]
	v_exp_f32_e32 v104, v104
	v_add_f32_e32 v27, v27, v102
	v_exp_f32_e32 v105, v105
	v_add_f32_e32 v27, v27, v103
	v_add_f32_e32 v27, v27, v104
	v_mfma_f32_32x32x16_bf16 v[158:173], v[174:177], v[138:141], v[158:173]
	v_add_f32_e32 v27, v27, v105
	v_cvt_pk_bf16_f32 v98, v98, v99
	v_cvt_pk_bf16_f32 v99, v100, v101
	v_cvt_pk_bf16_f32 v100, v102, v103
	v_cvt_pk_bf16_f32 v101, v104, v105
	s_waitcnt lgkmcnt(0)
	v_add_u32_e32 v2, 0x6000, v238
	v_mfma_f32_32x32x16_bf16 v[34:49], v[82:85], v[114:117], v[34:49]
	v_exp_f32_e32 v106, v106
	v_exp_f32_e32 v107, v107
	v_exp_f32_e32 v108, v108
	v_add_f32_e32 v27, v27, v106
	v_exp_f32_e32 v109, v109
	ds_read_b128 v[218:221], v2
	ds_read_b128 v[214:217], v2 offset:512
	ds_read_b128 v[210:213], v2 offset:2048
	v_mfma_f32_32x32x16_bf16 v[50:65], v[82:85], v[240:243], v[50:65]
	v_add_f32_e32 v27, v27, v107
	v_exp_f32_e32 v110, v110
	v_add_f32_e32 v27, v27, v108
	v_exp_f32_e32 v111, v111
	v_add_f32_e32 v27, v27, v109
	ds_read_b128 v[206:209], v2 offset:2560
	ds_read_b128 v[202:205], v2 offset:4096
	ds_read_b128 v[198:201], v2 offset:4608
	v_mfma_f32_32x32x16_bf16 v[34:49], v[90:93], v[118:121], v[34:49]
	v_exp_f32_e32 v112, v112
	v_add_f32_e32 v27, v27, v110
	v_exp_f32_e32 v113, v113
	v_add_f32_e32 v27, v27, v111
	v_add_f32_e32 v27, v27, v112
	ds_read_b128 v[194:197], v2 offset:6144
	ds_read_b128 v[190:193], v2 offset:6656
	ds_read_b128 v[186:189], v2 offset:8192
	v_mfma_f32_32x32x16_bf16 v[50:65], v[90:93], v[244:247], v[50:65]
	v_add_f32_e32 v27, v27, v113
	v_cvt_pk_bf16_f32 v106, v106, v107
	v_cvt_pk_bf16_f32 v107, v108, v109
	v_cvt_pk_bf16_f32 v108, v110, v111
	v_cvt_pk_bf16_f32 v109, v112, v113
	v_add_f32_e32 v236, v236, v27
	ds_read_b128 v[182:185], v2 offset:8704
	ds_read_b128 v[178:181], v2 offset:10240
	ds_read_b128 v[174:177], v2 offset:10752
	v_mfma_f32_32x32x16_bf16 v[34:49], v[98:101], v[122:125], v[34:49]
	v_max3_f32 v19, v142, v143, v144
	v_max3_f32 v26, v145, v146, v147
	v_max3_f32 v19, v19, v148, v149
	v_max3_f32 v26, v26, v150, v151
	v_mfma_f32_32x32x16_bf16 v[50:65], v[98:101], v[248:251], v[50:65]
	v_max3_f32 v19, v19, v152, v153
	v_max3_f32 v26, v26, v154, v155
	v_max3_f32 v19, v19, v156, v157
	v_max3_f32 v26, v26, v158, v159
	v_mfma_f32_32x32x16_bf16 v[34:49], v[106:109], v[126:129], v[34:49]
	v_max3_f32 v19, v19, v160, v161
	v_max3_f32 v26, v26, v162, v163
	v_max3_f32 v19, v19, v164, v165
	v_max3_f32 v26, v26, v166, v167
	v_mfma_f32_32x32x16_bf16 v[50:65], v[106:109], v[20:23], v[50:65]
	v_max3_f32 v19, v19, v168, v169
	v_max3_f32 v26, v26, v170, v171
	v_max3_f32 v19, v19, v172, v173
	v_max_f32_e32 v19, v19, v26
	v_cmp_lt_f32_e32 vcc, s41, v19
	s_cbranch_vccz .Lmy_nors_36
	s_nop 15
	s_nop 15
	v_mov_b32_e32 v26, v19
	s_nop 1
	v_permlane32_swap_b32_e32 v19, v26
	v_max_f32_e32 v19, v19, v26
	v_max_f32_e32 v19, v19, v19
	v_max_f32_e32 v90, 0, v19
	v_exp_f32_e64 v91, -v90
	v_add_f32_e32 v239, v239, v90
	v_xor_b32_e32 v66, 0x80000000, v239
	v_mov_b32_e32 v67, v66
	v_mov_b32_e32 v68, v66
	v_mov_b32_e32 v69, v66
	v_mov_b32_e32 v70, v66
	v_mov_b32_e32 v71, v66
	v_mov_b32_e32 v72, v66
	v_mov_b32_e32 v73, v66
	v_mov_b32_e32 v74, v66
	v_mov_b32_e32 v75, v66
	v_mov_b32_e32 v76, v66
	v_mov_b32_e32 v77, v66
	v_mov_b32_e32 v78, v66
	v_mov_b32_e32 v79, v66
	v_mov_b32_e32 v80, v66
	v_mov_b32_e32 v81, v66
	v_sub_f32_e32 v142, v142, v90
	v_sub_f32_e32 v143, v143, v90
	v_sub_f32_e32 v144, v144, v90
	v_sub_f32_e32 v145, v145, v90
	v_sub_f32_e32 v146, v146, v90
	v_sub_f32_e32 v147, v147, v90
	v_sub_f32_e32 v148, v148, v90
	v_sub_f32_e32 v149, v149, v90
	v_sub_f32_e32 v150, v150, v90
	v_sub_f32_e32 v151, v151, v90
	v_sub_f32_e32 v152, v152, v90
	v_sub_f32_e32 v153, v153, v90
	v_sub_f32_e32 v154, v154, v90
	v_sub_f32_e32 v155, v155, v90
	v_sub_f32_e32 v156, v156, v90
	v_sub_f32_e32 v157, v157, v90
	v_sub_f32_e32 v158, v158, v90
	v_sub_f32_e32 v159, v159, v90
	v_sub_f32_e32 v160, v160, v90
	v_sub_f32_e32 v161, v161, v90
	v_sub_f32_e32 v162, v162, v90
	v_sub_f32_e32 v163, v163, v90
	v_sub_f32_e32 v164, v164, v90
	v_sub_f32_e32 v165, v165, v90
	v_sub_f32_e32 v166, v166, v90
	v_sub_f32_e32 v167, v167, v90
	v_sub_f32_e32 v168, v168, v90
	v_sub_f32_e32 v169, v169, v90
	v_sub_f32_e32 v170, v170, v90
	v_sub_f32_e32 v171, v171, v90
	v_sub_f32_e32 v172, v172, v90
	v_sub_f32_e32 v173, v173, v90
	v_mul_f32_e32 v236, v236, v91
	s_mov_b64 s[96:97], exec
	s_and_b64 exec, exec, s[8:9]
	ds_write_b32 v235, v91
	s_mov_b64 exec, s[96:97]
	v_lshl_add_u32 v2, v228, 4, s47
	ds_read_b128 v[94:97], v2 offset:0
	s_waitcnt lgkmcnt(0)
	v_mul_f32_e32 v34, v34, v94
	v_mul_f32_e32 v50, v50, v94
	v_mul_f32_e32 v35, v35, v95
	v_mul_f32_e32 v51, v51, v95
	v_mul_f32_e32 v36, v36, v96
	v_mul_f32_e32 v52, v52, v96
	v_mul_f32_e32 v37, v37, v97
	v_mul_f32_e32 v53, v53, v97
	ds_read_b128 v[94:97], v2 offset:32
	s_waitcnt lgkmcnt(0)
	v_mul_f32_e32 v38, v38, v94
	v_mul_f32_e32 v54, v54, v94
	v_mul_f32_e32 v39, v39, v95
	v_mul_f32_e32 v55, v55, v95
	v_mul_f32_e32 v40, v40, v96
	v_mul_f32_e32 v56, v56, v96
	v_mul_f32_e32 v41, v41, v97
	v_mul_f32_e32 v57, v57, v97
	ds_read_b128 v[94:97], v2 offset:64
	s_waitcnt lgkmcnt(0)
	v_mul_f32_e32 v42, v42, v94
	v_mul_f32_e32 v58, v58, v94
	v_mul_f32_e32 v43, v43, v95
	v_mul_f32_e32 v59, v59, v95
	v_mul_f32_e32 v44, v44, v96
	v_mul_f32_e32 v60, v60, v96
	v_mul_f32_e32 v45, v45, v97
	v_mul_f32_e32 v61, v61, v97
	ds_read_b128 v[94:97], v2 offset:96
	s_waitcnt lgkmcnt(0)
	v_mul_f32_e32 v46, v46, v94
	v_mul_f32_e32 v62, v62, v94
	v_mul_f32_e32 v47, v47, v95
	v_mul_f32_e32 v63, v63, v95
	v_mul_f32_e32 v48, v48, v96
	v_mul_f32_e32 v64, v64, v96
	v_mul_f32_e32 v49, v49, v97
	v_mul_f32_e32 v65, v65, v97

.Lmy_nors_37:
	s_waitcnt lgkmcnt(0)
	v_add_u32_e32 v2, 0x4000, v237
	v_mfma_f32_32x32x16_bf16 v[142:157], v[218:221], v[4:7], v[66:81]
	v_exp_f32_e32 v82, v82
	v_exp_f32_e32 v83, v83
	v_exp_f32_e32 v84, v84
	v_add_f32_e32 v27, v82, v83
	v_exp_f32_e32 v85, v85
	ds_read_b64_tr_b16 v[114:115], v2 offset:49152
	ds_read_b64_tr_b16 v[116:117], v2 offset:49664
	ds_read_b64_tr_b16 v[118:119], v2 offset:50176
	ds_read_b64_tr_b16 v[120:121], v2 offset:50688
	v_mfma_f32_32x32x16_bf16 v[158:173], v[214:217], v[4:7], v[66:81]
	v_exp_f32_e32 v86, v86
	v_add_f32_e32 v27, v27, v84
	v_exp_f32_e32 v87, v87
	v_add_f32_e32 v27, v27, v85
	v_exp_f32_e32 v88, v88
	ds_read_b64_tr_b16 v[122:123], v2 offset:51200
	ds_read_b64_tr_b16 v[124:125], v2 offset:51712
	ds_read_b64_tr_b16 v[126:127], v2 offset:52224
	ds_read_b64_tr_b16 v[128:129], v2 offset:52736
	v_mfma_f32_32x32x16_bf16 v[142:157], v[210:213], v[8:11], v[142:157]
	v_add_f32_e32 v27, v27, v86
	v_exp_f32_e32 v89, v89
	v_add_f32_e32 v27, v27, v87
	v_add_f32_e32 v27, v27, v88
	v_add_f32_e32 v27, v27, v89
	ds_read_b64_tr_b16 v[240:241], v2 offset:53248
	ds_read_b64_tr_b16 v[242:243], v2 offset:53760
	ds_read_b64_tr_b16 v[244:245], v2 offset:54272
	ds_read_b64_tr_b16 v[246:247], v2 offset:54784
	v_mfma_f32_32x32x16_bf16 v[158:173], v[206:209], v[8:11], v[158:173]
	v_cvt_pk_bf16_f32 v82, v82, v83
	v_cvt_pk_bf16_f32 v83, v84, v85
	v_cvt_pk_bf16_f32 v84, v86, v87
	v_cvt_pk_bf16_f32 v85, v88, v89
	ds_read_b64_tr_b16 v[248:249], v2 offset:55296
	ds_read_b64_tr_b16 v[250:251], v2 offset:55808
	ds_read_b64_tr_b16 v[20:21], v2 offset:56320
	ds_read_b64_tr_b16 v[22:23], v2 offset:56832
	v_mfma_f32_32x32x16_bf16 v[142:157], v[202:205], v[12:15], v[142:157]
	v_exp_f32_e32 v90, v90
	v_exp_f32_e32 v91, v91
	v_exp_f32_e32 v92, v92
	v_add_f32_e32 v27, v27, v90
	v_exp_f32_e32 v93, v93
	v_mfma_f32_32x32x16_bf16 v[158:173], v[198:201], v[12:15], v[158:173]
	v_add_f32_e32 v27, v27, v91
	v_exp_f32_e32 v94, v94
	v_add_f32_e32 v27, v27, v92
	v_exp_f32_e32 v95, v95
	v_add_f32_e32 v27, v27, v93
	s_waitcnt vmcnt(4)
	s_barrier
	v_mfma_f32_32x32x16_bf16 v[142:157], v[194:197], v[130:133], v[142:157]
	s_add_u32 m0, s57, 0x2000
	v_exp_f32_e32 v96, v96
	v_add_f32_e32 v27, v27, v94
	global_load_lds_dwordx4 v[28:29], off
	v_lshl_add_u64 v[28:29], v[28:29], 0, s[30:31]
	v_exp_f32_e32 v97, v97
	v_add_f32_e32 v27, v27, v95
	v_add_f32_e32 v27, v27, v96
	v_mfma_f32_32x32x16_bf16 v[158:173], v[190:193], v[130:133], v[158:173]
	s_add_u32 m0, s40, 0x9000
	v_add_f32_e32 v27, v27, v97
	v_cvt_pk_bf16_f32 v90, v90, v91
	global_load_lds_dwordx4 v[24:25], off
	v_lshl_add_u64 v[24:25], v[24:25], 0, s[30:31]
	v_cvt_pk_bf16_f32 v91, v92, v93
	v_cvt_pk_bf16_f32 v92, v94, v95
	v_cvt_pk_bf16_f32 v93, v96, v97
	v_mfma_f32_32x32x16_bf16 v[142:157], v[186:189], v[134:137], v[142:157]
	v_exp_f32_e32 v98, v98
	v_exp_f32_e32 v99, v99
	v_exp_f32_e32 v100, v100
	v_add_f32_e32 v27, v27, v98
	v_exp_f32_e32 v101, v101
	v_mfma_f32_32x32x16_bf16 v[158:173], v[182:185], v[134:137], v[158:173]
	v_add_f32_e32 v27, v27, v99
	v_exp_f32_e32 v102, v102
	v_add_f32_e32 v27, v27, v100
	v_exp_f32_e32 v103, v103
	v_add_f32_e32 v27, v27, v101
	v_mfma_f32_32x32x16_bf16 v[142:157], v[178:181], v[138:141], v[142:157]
	v_exp_f32_e32 v104, v104
	v_add_f32_e32 v27, v27, v102
	v_exp_f32_e32 v105, v105
	v_add_f32_e32 v27, v27, v103
	v_add_f32_e32 v27, v27, v104
	v_mfma_f32_32x32x16_bf16 v[158:173], v[174:177], v[138:141], v[158:173]
	v_add_f32_e32 v27, v27, v105
	v_cvt_pk_bf16_f32 v98, v98, v99
	v_cvt_pk_bf16_f32 v99, v100, v101
	v_cvt_pk_bf16_f32 v100, v102, v103
	v_cvt_pk_bf16_f32 v101, v104, v105
	s_waitcnt lgkmcnt(0)
	v_mov_b32_e32 v2, v238
	v_mfma_f32_32x32x16_bf16 v[34:49], v[82:85], v[114:117], v[34:49]
	v_exp_f32_e32 v106, v106
	v_exp_f32_e32 v107, v107
	v_exp_f32_e32 v108, v108
	v_add_f32_e32 v27, v27, v106
	v_exp_f32_e32 v109, v109
	ds_read_b128 v[218:221], v2
	ds_read_b128 v[214:217], v2 offset:512
	ds_read_b128 v[210:213], v2 offset:2048
	v_mfma_f32_32x32x16_bf16 v[50:65], v[82:85], v[240:243], v[50:65]
	v_add_f32_e32 v27, v27, v107
	v_exp_f32_e32 v110, v110
	v_add_f32_e32 v27, v27, v108
	v_exp_f32_e32 v111, v111
	v_add_f32_e32 v27, v27, v109
	ds_read_b128 v[206:209], v2 offset:2560
	ds_read_b128 v[202:205], v2 offset:4096
	ds_read_b128 v[198:201], v2 offset:4608
	v_mfma_f32_32x32x16_bf16 v[34:49], v[90:93], v[118:121], v[34:49]
	v_exp_f32_e32 v112, v112
	v_add_f32_e32 v27, v27, v110
	v_exp_f32_e32 v113, v113
	v_add_f32_e32 v27, v27, v111
	v_add_f32_e32 v27, v27, v112
	ds_read_b128 v[194:197], v2 offset:6144
	ds_read_b128 v[190:193], v2 offset:6656
	ds_read_b128 v[186:189], v2 offset:8192
	v_mfma_f32_32x32x16_bf16 v[50:65], v[90:93], v[244:247], v[50:65]
	v_add_f32_e32 v27, v27, v113
	v_cvt_pk_bf16_f32 v106, v106, v107
	v_cvt_pk_bf16_f32 v107, v108, v109
	v_cvt_pk_bf16_f32 v108, v110, v111
	v_cvt_pk_bf16_f32 v109, v112, v113
	v_add_f32_e32 v236, v236, v27
	ds_read_b128 v[182:185], v2 offset:8704
	ds_read_b128 v[178:181], v2 offset:10240
	ds_read_b128 v[174:177], v2 offset:10752
	v_mfma_f32_32x32x16_bf16 v[34:49], v[98:101], v[122:125], v[34:49]
	v_max3_f32 v19, v142, v143, v144
	v_max3_f32 v26, v145, v146, v147
	v_max3_f32 v19, v19, v148, v149
	v_max3_f32 v26, v26, v150, v151
	v_mfma_f32_32x32x16_bf16 v[50:65], v[98:101], v[248:251], v[50:65]
	v_max3_f32 v19, v19, v152, v153
	v_max3_f32 v26, v26, v154, v155
	v_max3_f32 v19, v19, v156, v157
	v_max3_f32 v26, v26, v158, v159
	v_mfma_f32_32x32x16_bf16 v[34:49], v[106:109], v[126:129], v[34:49]
	v_max3_f32 v19, v19, v160, v161
	v_max3_f32 v26, v26, v162, v163
	v_max3_f32 v19, v19, v164, v165
	v_max3_f32 v26, v26, v166, v167
	v_mfma_f32_32x32x16_bf16 v[50:65], v[106:109], v[20:23], v[50:65]
	v_max3_f32 v19, v19, v168, v169
	v_max3_f32 v26, v26, v170, v171
	v_max3_f32 v19, v19, v172, v173
	v_max_f32_e32 v19, v19, v26
	v_cmp_lt_f32_e32 vcc, s41, v19
	s_cbranch_vccz .Lmy_nors_38
	s_nop 15
	s_nop 15
	v_mov_b32_e32 v26, v19
	s_nop 1
	v_permlane32_swap_b32_e32 v19, v26
	v_max_f32_e32 v19, v19, v26
	v_max_f32_e32 v19, v19, v19
	v_max_f32_e32 v90, 0, v19
	v_exp_f32_e64 v91, -v90
	v_add_f32_e32 v239, v239, v90
	v_xor_b32_e32 v66, 0x80000000, v239
	v_mov_b32_e32 v67, v66
	v_mov_b32_e32 v68, v66
	v_mov_b32_e32 v69, v66
	v_mov_b32_e32 v70, v66
	v_mov_b32_e32 v71, v66
	v_mov_b32_e32 v72, v66
	v_mov_b32_e32 v73, v66
	v_mov_b32_e32 v74, v66
	v_mov_b32_e32 v75, v66
	v_mov_b32_e32 v76, v66
	v_mov_b32_e32 v77, v66
	v_mov_b32_e32 v78, v66
	v_mov_b32_e32 v79, v66
	v_mov_b32_e32 v80, v66
	v_mov_b32_e32 v81, v66
	v_sub_f32_e32 v142, v142, v90
	v_sub_f32_e32 v143, v143, v90
	v_sub_f32_e32 v144, v144, v90
	v_sub_f32_e32 v145, v145, v90
	v_sub_f32_e32 v146, v146, v90
	v_sub_f32_e32 v147, v147, v90
	v_sub_f32_e32 v148, v148, v90
	v_sub_f32_e32 v149, v149, v90
	v_sub_f32_e32 v150, v150, v90
	v_sub_f32_e32 v151, v151, v90
	v_sub_f32_e32 v152, v152, v90
	v_sub_f32_e32 v153, v153, v90
	v_sub_f32_e32 v154, v154, v90
	v_sub_f32_e32 v155, v155, v90
	v_sub_f32_e32 v156, v156, v90
	v_sub_f32_e32 v157, v157, v90
	v_sub_f32_e32 v158, v158, v90
	v_sub_f32_e32 v159, v159, v90
	v_sub_f32_e32 v160, v160, v90
	v_sub_f32_e32 v161, v161, v90
	v_sub_f32_e32 v162, v162, v90
	v_sub_f32_e32 v163, v163, v90
	v_sub_f32_e32 v164, v164, v90
	v_sub_f32_e32 v165, v165, v90
	v_sub_f32_e32 v166, v166, v90
	v_sub_f32_e32 v167, v167, v90
	v_sub_f32_e32 v168, v168, v90
	v_sub_f32_e32 v169, v169, v90
	v_sub_f32_e32 v170, v170, v90
	v_sub_f32_e32 v171, v171, v90
	v_sub_f32_e32 v172, v172, v90
	v_sub_f32_e32 v173, v173, v90
	v_mul_f32_e32 v236, v236, v91
	s_mov_b64 s[96:97], exec
	s_and_b64 exec, exec, s[8:9]
	ds_write_b32 v235, v91
	s_mov_b64 exec, s[96:97]
	v_lshl_add_u32 v2, v228, 4, s47
	ds_read_b128 v[94:97], v2 offset:0
	s_waitcnt lgkmcnt(0)
	v_mul_f32_e32 v34, v34, v94
	v_mul_f32_e32 v50, v50, v94
	v_mul_f32_e32 v35, v35, v95
	v_mul_f32_e32 v51, v51, v95
	v_mul_f32_e32 v36, v36, v96
	v_mul_f32_e32 v52, v52, v96
	v_mul_f32_e32 v37, v37, v97
	v_mul_f32_e32 v53, v53, v97
	ds_read_b128 v[94:97], v2 offset:32
	s_waitcnt lgkmcnt(0)
	v_mul_f32_e32 v38, v38, v94
	v_mul_f32_e32 v54, v54, v94
	v_mul_f32_e32 v39, v39, v95
	v_mul_f32_e32 v55, v55, v95
	v_mul_f32_e32 v40, v40, v96
	v_mul_f32_e32 v56, v56, v96
	v_mul_f32_e32 v41, v41, v97
	v_mul_f32_e32 v57, v57, v97
	ds_read_b128 v[94:97], v2 offset:64
	s_waitcnt lgkmcnt(0)
	v_mul_f32_e32 v42, v42, v94
	v_mul_f32_e32 v58, v58, v94
	v_mul_f32_e32 v43, v43, v95
	v_mul_f32_e32 v59, v59, v95
	v_mul_f32_e32 v44, v44, v96
	v_mul_f32_e32 v60, v60, v96
	v_mul_f32_e32 v45, v45, v97
	v_mul_f32_e32 v61, v61, v97
	ds_read_b128 v[94:97], v2 offset:96
	s_waitcnt lgkmcnt(0)
	v_mul_f32_e32 v46, v46, v94
	v_mul_f32_e32 v62, v62, v94
	v_mul_f32_e32 v47, v47, v95
	v_mul_f32_e32 v63, v63, v95
	v_mul_f32_e32 v48, v48, v96
	v_mul_f32_e32 v64, v64, v96
	v_mul_f32_e32 v49, v49, v97
	v_mul_f32_e32 v65, v65, v97

.Lmy_tf_41:
	s_waitcnt lgkmcnt(0)
	v_mov_b32_e32 v2, v237
	v_mfma_f32_32x32x16_bf16 v[142:157], v[218:221], v[4:7], v[66:81]
	v_exp_f32_e32 v82, v82
	v_exp_f32_e32 v83, v83
	v_exp_f32_e32 v84, v84
	v_add_f32_e32 v27, v82, v83
	v_exp_f32_e32 v85, v85
	ds_read_b64_tr_b16 v[114:115], v2 offset:49152
	ds_read_b64_tr_b16 v[116:117], v2 offset:49664
	ds_read_b64_tr_b16 v[118:119], v2 offset:50176
	ds_read_b64_tr_b16 v[120:121], v2 offset:50688
	v_mfma_f32_32x32x16_bf16 v[158:173], v[214:217], v[4:7], v[66:81]
	v_exp_f32_e32 v86, v86
	v_add_f32_e32 v27, v27, v84
	v_exp_f32_e32 v87, v87
	v_add_f32_e32 v27, v27, v85
	v_exp_f32_e32 v88, v88
	ds_read_b64_tr_b16 v[122:123], v2 offset:51200
	ds_read_b64_tr_b16 v[124:125], v2 offset:51712
	ds_read_b64_tr_b16 v[126:127], v2 offset:52224
	ds_read_b64_tr_b16 v[128:129], v2 offset:52736
	v_mfma_f32_32x32x16_bf16 v[142:157], v[210:213], v[8:11], v[142:157]
	v_add_f32_e32 v27, v27, v86
	v_exp_f32_e32 v89, v89
	v_add_f32_e32 v27, v27, v87
	v_add_f32_e32 v27, v27, v88
	v_add_f32_e32 v27, v27, v89
	ds_read_b64_tr_b16 v[240:241], v2 offset:53248
	ds_read_b64_tr_b16 v[242:243], v2 offset:53760
	ds_read_b64_tr_b16 v[244:245], v2 offset:54272
	ds_read_b64_tr_b16 v[246:247], v2 offset:54784
	v_mfma_f32_32x32x16_bf16 v[158:173], v[206:209], v[8:11], v[158:173]
	v_cvt_pk_bf16_f32 v82, v82, v83
	v_cvt_pk_bf16_f32 v83, v84, v85
	v_cvt_pk_bf16_f32 v84, v86, v87
	v_cvt_pk_bf16_f32 v85, v88, v89
	ds_read_b64_tr_b16 v[248:249], v2 offset:55296
	ds_read_b64_tr_b16 v[250:251], v2 offset:55808
	ds_read_b64_tr_b16 v[20:21], v2 offset:56320
	ds_read_b64_tr_b16 v[22:23], v2 offset:56832
	v_mfma_f32_32x32x16_bf16 v[142:157], v[202:205], v[12:15], v[142:157]
	v_exp_f32_e32 v90, v90
	v_exp_f32_e32 v91, v91
	v_exp_f32_e32 v92, v92
	v_add_f32_e32 v27, v27, v90
	v_exp_f32_e32 v93, v93
	v_mfma_f32_32x32x16_bf16 v[158:173], v[198:201], v[12:15], v[158:173]
	v_add_f32_e32 v27, v27, v91
	v_exp_f32_e32 v94, v94
	v_add_f32_e32 v27, v27, v92
	v_exp_f32_e32 v95, v95
	v_add_f32_e32 v27, v27, v93
	s_waitcnt vmcnt(2)
	s_barrier
	v_mfma_f32_32x32x16_bf16 v[142:157], v[194:197], v[130:133], v[142:157]
	s_add_u32 m0, s57, 0x6000
	v_exp_f32_e32 v96, v96
	v_add_f32_e32 v27, v27, v94
	global_load_lds_dwordx4 v[28:29], off
	v_lshl_add_u64 v[28:29], v[28:29], 0, s[30:31]
	v_exp_f32_e32 v97, v97
	v_add_f32_e32 v27, v27, v95
	v_add_f32_e32 v27, v27, v96
	v_mfma_f32_32x32x16_bf16 v[158:173], v[190:193], v[130:133], v[158:173]
	v_add_f32_e32 v27, v27, v97
	v_cvt_pk_bf16_f32 v90, v90, v91
	v_cvt_pk_bf16_f32 v91, v92, v93
	v_cvt_pk_bf16_f32 v92, v94, v95
	v_cvt_pk_bf16_f32 v93, v96, v97
	v_mfma_f32_32x32x16_bf16 v[142:157], v[186:189], v[134:137], v[142:157]
	v_exp_f32_e32 v98, v98
	v_exp_f32_e32 v99, v99
	v_exp_f32_e32 v100, v100
	v_add_f32_e32 v27, v27, v98
	v_exp_f32_e32 v101, v101
	v_mfma_f32_32x32x16_bf16 v[158:173], v[182:185], v[134:137], v[158:173]
	v_add_f32_e32 v27, v27, v99
	v_exp_f32_e32 v102, v102
	v_add_f32_e32 v27, v27, v100
	v_exp_f32_e32 v103, v103
	v_add_f32_e32 v27, v27, v101
	v_mfma_f32_32x32x16_bf16 v[142:157], v[178:181], v[138:141], v[142:157]
	v_exp_f32_e32 v104, v104
	v_add_f32_e32 v27, v27, v102
	v_exp_f32_e32 v105, v105
	v_add_f32_e32 v27, v27, v103
	v_add_f32_e32 v27, v27, v104
	v_mfma_f32_32x32x16_bf16 v[158:173], v[174:177], v[138:141], v[158:173]
	v_add_f32_e32 v27, v27, v105
	v_cvt_pk_bf16_f32 v98, v98, v99
	v_cvt_pk_bf16_f32 v99, v100, v101
	v_cvt_pk_bf16_f32 v100, v102, v103
	v_cvt_pk_bf16_f32 v101, v104, v105
	s_waitcnt lgkmcnt(0)
	v_add_u32_e32 v2, 0x6000, v238
	v_mfma_f32_32x32x16_bf16 v[34:49], v[82:85], v[114:117], v[34:49]
	v_exp_f32_e32 v106, v106
	v_exp_f32_e32 v107, v107
	v_exp_f32_e32 v108, v108
	v_add_f32_e32 v27, v27, v106
	v_exp_f32_e32 v109, v109
	s_cmp_gt_u32 s71, 1
	s_cbranch_scc0 .Lmy_nok_44
	ds_read_b128 v[218:221], v2
	ds_read_b128 v[214:217], v2 offset:512
	ds_read_b128 v[210:213], v2 offset:2048
	ds_read_b128 v[206:209], v2 offset:2560
	ds_read_b128 v[202:205], v2 offset:4096
	ds_read_b128 v[198:201], v2 offset:4608
	ds_read_b128 v[194:197], v2 offset:6144
	ds_read_b128 v[190:193], v2 offset:6656
	ds_read_b128 v[186:189], v2 offset:8192
	ds_read_b128 v[182:185], v2 offset:8704
	ds_read_b128 v[178:181], v2 offset:10240
	ds_read_b128 v[174:177], v2 offset:10752
